# v31 plus GEMM staging reorder: address VALU fills the M0-write wait state before each LDS-DMA (78 s_nop removed)
# baseline (speedup 1.0000x reference)
.LBB0_38:
	ds_read_b128 v[150:153], v147
	ds_read_b128 v[156:159], v147 offset:1024
	ds_read_b128 v[160:163], v147 offset:2048
	ds_read_b128 v[164:167], v147 offset:3072
	s_add_u32 s83, s88, 0xfffc0080
	s_addc_u32 s90, s89, -1
	s_cmp_eq_u32 s82, 12
	s_cselect_b32 s93, s13, s90
	s_cselect_b32 s92, s78, s83
	s_cselect_b32 s91, s11, s81
	s_cselect_b32 s90, s79, s80
	v_lshl_add_u64 v[200:201], s[88:89], 0, v[136:137]
	s_add_i32 m0, s9, 0xc000
	ds_read_b128 v[168:171], v148
	ds_read_b128 v[172:175], v148 offset:1024
	ds_read_b128 v[176:179], v148 offset:2048
	ds_read_b128 v[180:183], v148 offset:3072
	ds_read_b128 v[184:187], v148 offset:4096
	ds_read_b128 v[188:191], v148 offset:5120
	ds_read_b128 v[192:195], v148 offset:6144
	ds_read_b128 v[196:199], v148 offset:7168
	global_load_lds_dwordx4 v[200:201], off
	s_add_i32 m0, s9, 0xe000
	v_lshl_add_u64 v[200:201], s[88:89], 0, v[138:139]
	global_load_lds_dwordx4 v[200:201], off
	s_waitcnt lgkmcnt(8)
	s_barrier
	s_waitcnt lgkmcnt(0)
	s_waitcnt lgkmcnt(0)
	v_mfma_f32_16x16x32_bf16 v[124:127], v[150:153], v[168:171], v[124:127]
	v_mfma_f32_16x16x32_bf16 v[120:123], v[160:163], v[168:171], v[120:123]
	v_mfma_f32_16x16x32_bf16 v[116:119], v[150:153], v[176:179], v[116:119]
	v_mfma_f32_16x16x32_bf16 v[112:115], v[160:163], v[176:179], v[112:115]
	v_mfma_f32_16x16x32_bf16 v[100:103], v[150:153], v[184:187], v[100:103]
	v_mfma_f32_16x16x32_bf16 v[96:99], v[160:163], v[184:187], v[96:99]
	v_mfma_f32_16x16x32_bf16 v[84:87], v[150:153], v[192:195], v[84:87]
	v_mfma_f32_16x16x32_bf16 v[80:83], v[160:163], v[192:195], v[80:83]
	v_mfma_f32_16x16x32_bf16 v[124:127], v[156:159], v[172:175], v[124:127]
	v_mfma_f32_16x16x32_bf16 v[120:123], v[164:167], v[172:175], v[120:123]
	v_mfma_f32_16x16x32_bf16 v[116:119], v[156:159], v[180:183], v[116:119]
	v_mfma_f32_16x16x32_bf16 v[112:115], v[164:167], v[180:183], v[112:115]
	v_mfma_f32_16x16x32_bf16 v[100:103], v[156:159], v[188:191], v[100:103]
	v_mfma_f32_16x16x32_bf16 v[96:99], v[164:167], v[188:191], v[96:99]
	v_mfma_f32_16x16x32_bf16 v[84:87], v[156:159], v[196:199], v[84:87]
	v_mfma_f32_16x16x32_bf16 v[80:83], v[164:167], v[196:199], v[80:83]
	s_barrier
	s_add_i32 s83, s74, s1
	v_lshl_add_u64 v[216:217], s[90:91], 0, v[132:133]
	s_mov_b32 m0, s83
	ds_read_b128 v[200:203], v149
	ds_read_b128 v[204:207], v149 offset:1024
	ds_read_b128 v[208:211], v149 offset:2048
	ds_read_b128 v[212:215], v149 offset:3072
	global_load_lds_dwordx4 v[216:217], off
	s_add_i32 m0, s83, 0x2000
	v_lshl_add_u64 v[218:219], s[90:91], 0, v[128:129]
	global_load_lds_dwordx4 v[218:219], off
	s_barrier
	s_waitcnt lgkmcnt(0)
	s_waitcnt lgkmcnt(0)
	v_mfma_f32_16x16x32_bf16 v[108:111], v[200:203], v[168:171], v[108:111]
	v_mfma_f32_16x16x32_bf16 v[104:107], v[208:211], v[168:171], v[104:107]
	v_mfma_f32_16x16x32_bf16 v[92:95], v[200:203], v[176:179], v[92:95]
	v_mfma_f32_16x16x32_bf16 v[88:91], v[208:211], v[176:179], v[88:91]
	v_mfma_f32_16x16x32_bf16 v[76:79], v[200:203], v[184:187], v[76:79]
	v_mfma_f32_16x16x32_bf16 v[72:75], v[208:211], v[184:187], v[72:75]
	v_mfma_f32_16x16x32_bf16 v[68:71], v[200:203], v[192:195], v[68:71]
	v_mfma_f32_16x16x32_bf16 v[64:67], v[208:211], v[192:195], v[64:67]
	v_mfma_f32_16x16x32_bf16 v[108:111], v[204:207], v[172:175], v[108:111]
	v_mfma_f32_16x16x32_bf16 v[104:107], v[212:215], v[172:175], v[104:107]
	v_mfma_f32_16x16x32_bf16 v[92:95], v[204:207], v[180:183], v[92:95]
	v_mfma_f32_16x16x32_bf16 v[88:91], v[212:215], v[180:183], v[88:91]
	v_mfma_f32_16x16x32_bf16 v[76:79], v[204:207], v[188:191], v[76:79]
	v_mfma_f32_16x16x32_bf16 v[72:75], v[212:215], v[188:191], v[72:75]
	v_mfma_f32_16x16x32_bf16 v[68:71], v[204:207], v[196:199], v[68:71]
	v_mfma_f32_16x16x32_bf16 v[64:67], v[212:215], v[196:199], v[64:67]
	s_mov_b32 m0, s9
	v_lshl_add_u64 v[220:221], s[92:93], 0, v[134:135]
	s_barrier
	ds_read_b128 v[168:171], v148 offset:16384
	ds_read_b128 v[172:175], v148 offset:17408
	ds_read_b128 v[176:179], v148 offset:18432
	ds_read_b128 v[180:183], v148 offset:19456
	ds_read_b128 v[184:187], v148 offset:20480
	ds_read_b128 v[188:191], v148 offset:21504
	ds_read_b128 v[192:195], v148 offset:22528
	ds_read_b128 v[196:199], v148 offset:23552
	global_load_lds_dwordx4 v[220:221], off
	s_mov_b32 m0, s35
	v_lshl_add_u64 v[222:223], s[92:93], 0, v[130:131]
	global_load_lds_dwordx4 v[222:223], off
	s_barrier
	s_waitcnt lgkmcnt(0)
	s_waitcnt lgkmcnt(0)
	v_mfma_f32_16x16x32_bf16 v[60:63], v[150:153], v[168:171], v[60:63]
	v_mfma_f32_16x16x32_bf16 v[56:59], v[160:163], v[168:171], v[56:59]
	v_mfma_f32_16x16x32_bf16 v[52:55], v[150:153], v[176:179], v[52:55]
	v_mfma_f32_16x16x32_bf16 v[48:51], v[160:163], v[176:179], v[48:51]
	v_mfma_f32_16x16x32_bf16 v[36:39], v[150:153], v[184:187], v[36:39]
	v_mfma_f32_16x16x32_bf16 v[32:35], v[160:163], v[184:187], v[32:35]
	v_mfma_f32_16x16x32_bf16 v[20:23], v[150:153], v[192:195], v[20:23]
	v_mfma_f32_16x16x32_bf16 v[16:19], v[160:163], v[192:195], v[16:19]
	v_mfma_f32_16x16x32_bf16 v[60:63], v[156:159], v[172:175], v[60:63]
	v_mfma_f32_16x16x32_bf16 v[56:59], v[164:167], v[172:175], v[56:59]
	v_mfma_f32_16x16x32_bf16 v[52:55], v[156:159], v[180:183], v[52:55]
	v_mfma_f32_16x16x32_bf16 v[48:51], v[164:167], v[180:183], v[48:51]
	v_mfma_f32_16x16x32_bf16 v[36:39], v[156:159], v[188:191], v[36:39]
	v_mfma_f32_16x16x32_bf16 v[32:35], v[164:167], v[188:191], v[32:35]
	v_mfma_f32_16x16x32_bf16 v[20:23], v[156:159], v[196:199], v[20:23]
	v_mfma_f32_16x16x32_bf16 v[16:19], v[164:167], v[196:199], v[16:19]
	s_barrier
	s_add_u32 s94, s90, 0x40000
	s_addc_u32 s95, s91, 0
	s_add_i32 s83, s75, s1
	s_mov_b32 m0, s83
	v_lshl_add_u64 v[150:151], s[94:95], 0, v[132:133]
	global_load_lds_dwordx4 v[150:151], off
	s_add_i32 m0, s83, 0x2000
	v_lshl_add_u64 v[150:151], s[94:95], 0, v[128:129]
	global_load_lds_dwordx4 v[150:151], off
	s_waitcnt vmcnt(6)
	s_barrier
	v_mfma_f32_16x16x32_bf16 v[44:47], v[200:203], v[168:171], v[44:47]
	v_mfma_f32_16x16x32_bf16 v[40:43], v[208:211], v[168:171], v[40:43]
	v_mfma_f32_16x16x32_bf16 v[28:31], v[200:203], v[176:179], v[28:31]
	v_mfma_f32_16x16x32_bf16 v[24:27], v[208:211], v[176:179], v[24:27]
	v_mfma_f32_16x16x32_bf16 v[12:15], v[200:203], v[184:187], v[12:15]
	v_mfma_f32_16x16x32_bf16 v[8:11], v[208:211], v[184:187], v[8:11]
	v_mfma_f32_16x16x32_bf16 v[4:7], v[200:203], v[192:195], v[4:7]
	v_mfma_f32_16x16x32_bf16 v[0:3], v[208:211], v[192:195], v[0:3]
	v_mfma_f32_16x16x32_bf16 v[44:47], v[204:207], v[172:175], v[44:47]
	v_mfma_f32_16x16x32_bf16 v[40:43], v[212:215], v[172:175], v[40:43]
	v_mfma_f32_16x16x32_bf16 v[28:31], v[204:207], v[180:183], v[28:31]
	v_mfma_f32_16x16x32_bf16 v[24:27], v[212:215], v[180:183], v[24:27]
	v_mfma_f32_16x16x32_bf16 v[12:15], v[204:207], v[188:191], v[12:15]
	v_mfma_f32_16x16x32_bf16 v[8:11], v[212:215], v[188:191], v[8:11]
	v_mfma_f32_16x16x32_bf16 v[4:7], v[204:207], v[196:199], v[4:7]
	v_mfma_f32_16x16x32_bf16 v[0:3], v[212:215], v[196:199], v[0:3]
	s_add_i32 s83, 0, 0x18000
	v_add_u32_e32 v164, s83, v145
	s_barrier
	ds_read_b128 v[150:153], v164
	ds_read_b128 v[156:159], v164 offset:1024
	ds_read_b128 v[160:163], v164 offset:2048
	ds_read_b128 v[164:167], v164 offset:3072
	s_add_u32 s92, s92, 0x40000
	s_addc_u32 s93, s93, 0
	s_mov_b32 m0, s68
	v_lshl_add_u64 v[200:201], s[92:93], 0, v[134:135]
	ds_read_b128 v[168:171], v148 offset:32768
	ds_read_b128 v[172:175], v148 offset:33792
	ds_read_b128 v[176:179], v148 offset:34816
	ds_read_b128 v[180:183], v148 offset:35840
	ds_read_b128 v[184:187], v148 offset:36864
	ds_read_b128 v[188:191], v148 offset:37888
	ds_read_b128 v[192:195], v148 offset:38912
	ds_read_b128 v[196:199], v148 offset:39936
	global_load_lds_dwordx4 v[200:201], off
	s_mov_b32 m0, s69
	v_lshl_add_u64 v[200:201], s[92:93], 0, v[130:131]
	global_load_lds_dwordx4 v[200:201], off
	s_waitcnt lgkmcnt(8)
	s_barrier
	s_waitcnt lgkmcnt(0)
	s_waitcnt lgkmcnt(0)
	v_mfma_f32_16x16x32_bf16 v[124:127], v[150:153], v[168:171], v[124:127]
	v_mfma_f32_16x16x32_bf16 v[120:123], v[160:163], v[168:171], v[120:123]
	v_mfma_f32_16x16x32_bf16 v[116:119], v[150:153], v[176:179], v[116:119]
	v_mfma_f32_16x16x32_bf16 v[112:115], v[160:163], v[176:179], v[112:115]
	v_mfma_f32_16x16x32_bf16 v[100:103], v[150:153], v[184:187], v[100:103]
	v_mfma_f32_16x16x32_bf16 v[96:99], v[160:163], v[184:187], v[96:99]
	v_mfma_f32_16x16x32_bf16 v[84:87], v[150:153], v[192:195], v[84:87]
	v_mfma_f32_16x16x32_bf16 v[80:83], v[160:163], v[192:195], v[80:83]
	v_mfma_f32_16x16x32_bf16 v[124:127], v[156:159], v[172:175], v[124:127]
	v_mfma_f32_16x16x32_bf16 v[120:123], v[164:167], v[172:175], v[120:123]
	v_mfma_f32_16x16x32_bf16 v[116:119], v[156:159], v[180:183], v[116:119]
	v_mfma_f32_16x16x32_bf16 v[112:115], v[164:167], v[180:183], v[112:115]
	v_mfma_f32_16x16x32_bf16 v[100:103], v[156:159], v[188:191], v[100:103]
	v_mfma_f32_16x16x32_bf16 v[96:99], v[164:167], v[188:191], v[96:99]
	v_mfma_f32_16x16x32_bf16 v[84:87], v[156:159], v[196:199], v[84:87]
	v_mfma_f32_16x16x32_bf16 v[80:83], v[164:167], v[196:199], v[80:83]
	s_barrier
	s_add_i32 s92, 0, 0x1c000
	s_add_i32 s83, s83, s1
	v_add_u32_e32 v212, s92, v145
	v_lshl_add_u64 v[216:217], v[216:217], 0, s[6:7]
	s_mov_b32 m0, s83
	ds_read_b128 v[200:203], v212
	ds_read_b128 v[204:207], v212 offset:1024
	ds_read_b128 v[208:211], v212 offset:2048
	ds_read_b128 v[212:215], v212 offset:3072
	global_load_lds_dwordx4 v[216:217], off
	s_add_i32 m0, s83, 0x2000
	v_lshl_add_u64 v[216:217], v[218:219], 0, s[6:7]
	global_load_lds_dwordx4 v[216:217], off
	s_barrier
	s_waitcnt lgkmcnt(0)
	s_waitcnt lgkmcnt(0)
	v_mfma_f32_16x16x32_bf16 v[108:111], v[200:203], v[168:171], v[108:111]
	v_mfma_f32_16x16x32_bf16 v[104:107], v[208:211], v[168:171], v[104:107]
	v_mfma_f32_16x16x32_bf16 v[92:95], v[200:203], v[176:179], v[92:95]
	v_mfma_f32_16x16x32_bf16 v[88:91], v[208:211], v[176:179], v[88:91]
	v_mfma_f32_16x16x32_bf16 v[76:79], v[200:203], v[184:187], v[76:79]
	v_mfma_f32_16x16x32_bf16 v[72:75], v[208:211], v[184:187], v[72:75]
	v_mfma_f32_16x16x32_bf16 v[68:71], v[200:203], v[192:195], v[68:71]
	v_mfma_f32_16x16x32_bf16 v[64:67], v[208:211], v[192:195], v[64:67]
	v_mfma_f32_16x16x32_bf16 v[108:111], v[204:207], v[172:175], v[108:111]
	v_mfma_f32_16x16x32_bf16 v[104:107], v[212:215], v[172:175], v[104:107]
	v_mfma_f32_16x16x32_bf16 v[92:95], v[204:207], v[180:183], v[92:95]
	v_mfma_f32_16x16x32_bf16 v[88:91], v[212:215], v[180:183], v[88:91]
	v_mfma_f32_16x16x32_bf16 v[76:79], v[204:207], v[188:191], v[76:79]
	v_mfma_f32_16x16x32_bf16 v[72:75], v[212:215], v[188:191], v[72:75]
	v_mfma_f32_16x16x32_bf16 v[68:71], v[204:207], v[196:199], v[68:71]
	v_mfma_f32_16x16x32_bf16 v[64:67], v[212:215], v[196:199], v[64:67]
	s_mov_b32 m0, s71
	v_lshl_add_u64 v[216:217], v[220:221], 0, s[6:7]
	s_barrier
	ds_read_b128 v[168:171], v148 offset:49152
	ds_read_b128 v[172:175], v148 offset:50176
	ds_read_b128 v[176:179], v148 offset:51200
	ds_read_b128 v[180:183], v148 offset:52224
	ds_read_b128 v[184:187], v148 offset:53248
	ds_read_b128 v[188:191], v148 offset:54272
	ds_read_b128 v[192:195], v148 offset:55296
	ds_read_b128 v[196:199], v148 offset:56320
	global_load_lds_dwordx4 v[216:217], off
	s_mov_b32 m0, s72
	v_lshl_add_u64 v[216:217], v[222:223], 0, s[6:7]
	global_load_lds_dwordx4 v[216:217], off
	s_barrier
	s_waitcnt lgkmcnt(0)
	s_waitcnt lgkmcnt(0)
	v_mfma_f32_16x16x32_bf16 v[60:63], v[150:153], v[168:171], v[60:63]
	v_mfma_f32_16x16x32_bf16 v[56:59], v[160:163], v[168:171], v[56:59]
	v_mfma_f32_16x16x32_bf16 v[52:55], v[150:153], v[176:179], v[52:55]
	v_mfma_f32_16x16x32_bf16 v[48:51], v[160:163], v[176:179], v[48:51]
	v_mfma_f32_16x16x32_bf16 v[36:39], v[150:153], v[184:187], v[36:39]
	v_mfma_f32_16x16x32_bf16 v[32:35], v[160:163], v[184:187], v[32:35]
	v_mfma_f32_16x16x32_bf16 v[20:23], v[150:153], v[192:195], v[20:23]
	v_mfma_f32_16x16x32_bf16 v[16:19], v[160:163], v[192:195], v[16:19]
	v_mfma_f32_16x16x32_bf16 v[60:63], v[156:159], v[172:175], v[60:63]
	v_mfma_f32_16x16x32_bf16 v[56:59], v[164:167], v[172:175], v[56:59]
	v_mfma_f32_16x16x32_bf16 v[52:55], v[156:159], v[180:183], v[52:55]
	v_mfma_f32_16x16x32_bf16 v[48:51], v[164:167], v[180:183], v[48:51]
	v_mfma_f32_16x16x32_bf16 v[36:39], v[156:159], v[188:191], v[36:39]
	v_mfma_f32_16x16x32_bf16 v[32:35], v[164:167], v[188:191], v[32:35]
	v_mfma_f32_16x16x32_bf16 v[20:23], v[156:159], v[196:199], v[20:23]
	v_mfma_f32_16x16x32_bf16 v[16:19], v[164:167], v[196:199], v[16:19]
	s_barrier
	s_add_u32 s90, s90, 0x40080
	s_addc_u32 s91, s91, 0
	s_add_i32 s83, s92, s1
	s_mov_b32 m0, s83
	v_lshl_add_u64 v[150:151], s[90:91], 0, v[132:133]
	global_load_lds_dwordx4 v[150:151], off
	s_add_i32 m0, s83, 0x2000
	v_lshl_add_u64 v[150:151], s[90:91], 0, v[128:129]
	global_load_lds_dwordx4 v[150:151], off
	s_waitcnt vmcnt(6)
	s_barrier
	v_mfma_f32_16x16x32_bf16 v[44:47], v[200:203], v[168:171], v[44:47]
	v_mfma_f32_16x16x32_bf16 v[40:43], v[208:211], v[168:171], v[40:43]
	v_mfma_f32_16x16x32_bf16 v[28:31], v[200:203], v[176:179], v[28:31]
	v_mfma_f32_16x16x32_bf16 v[24:27], v[208:211], v[176:179], v[24:27]
	v_mfma_f32_16x16x32_bf16 v[12:15], v[200:203], v[184:187], v[12:15]
	v_mfma_f32_16x16x32_bf16 v[8:11], v[208:211], v[184:187], v[8:11]
	v_mfma_f32_16x16x32_bf16 v[4:7], v[200:203], v[192:195], v[4:7]
	v_mfma_f32_16x16x32_bf16 v[0:3], v[208:211], v[192:195], v[0:3]
	v_mfma_f32_16x16x32_bf16 v[44:47], v[204:207], v[172:175], v[44:47]
	v_mfma_f32_16x16x32_bf16 v[40:43], v[212:215], v[172:175], v[40:43]
	v_mfma_f32_16x16x32_bf16 v[28:31], v[204:207], v[180:183], v[28:31]
	v_mfma_f32_16x16x32_bf16 v[24:27], v[212:215], v[180:183], v[24:27]
	v_mfma_f32_16x16x32_bf16 v[12:15], v[204:207], v[188:191], v[12:15]
	v_mfma_f32_16x16x32_bf16 v[8:11], v[212:215], v[188:191], v[8:11]
	v_mfma_f32_16x16x32_bf16 v[4:7], v[204:207], v[196:199], v[4:7]
	v_mfma_f32_16x16x32_bf16 v[0:3], v[212:215], v[196:199], v[0:3]
	s_add_i32 s82, s82, 2
	s_add_u32 s88, s88, 0x100
	s_addc_u32 s89, s89, 0
	s_add_u32 s80, s80, 0x100
	s_addc_u32 s81, s81, 0
	s_cmp_gt_u32 s82, 13
	s_barrier
	s_cbranch_scc0 .LBB0_38
	v_lshl_add_u32 v152, s8, 8, v144
	v_lshl_or_b32 v150, s77, 8, v146
	v_cvt_pk_bf16_f32 v124, v124, v125
	v_cvt_pk_bf16_f32 v125, v126, v127
	v_cvt_pk_bf16_f32 v126, v120, v121
	v_mov_b64_e32 v[120:121], s[42:43]
	v_ashrrev_i32_e32 v151, 31, v150
	v_cvt_pk_bf16_f32 v68, v68, v69
	v_cvt_pk_bf16_f32 v69, v70, v71
	v_cvt_pk_bf16_f32 v70, v64, v65
	v_add_u32_e32 v64, 0x80, v152
	v_cvt_pk_bf16_f32 v127, v122, v123
	v_mad_i64_i32 v[122:123], s[78:79], v152, s76, v[120:121]
	v_lshlrev_b64 v[150:151], 1, v[150:151]
	v_cvt_pk_bf16_f32 v60, v60, v61
	v_cvt_pk_bf16_f32 v61, v62, v63
	v_cvt_pk_bf16_f32 v62, v56, v57
	v_mad_i64_i32 v[56:57], s[78:79], v64, s76, v[120:121]
	v_lshl_add_u64 v[122:123], v[122:123], 0, v[150:151]
	v_cvt_pk_bf16_f32 v108, v108, v109
	v_cvt_pk_bf16_f32 v109, v110, v111
	v_cvt_pk_bf16_f32 v110, v104, v105
	v_cvt_pk_bf16_f32 v111, v106, v107
	v_lshl_add_u64 v[56:57], v[56:57], 0, v[150:151]
	v_cvt_pk_bf16_f32 v44, v44, v45
	v_cvt_pk_bf16_f32 v45, v46, v47
	v_cvt_pk_bf16_f32 v46, v40, v41
	v_cvt_pk_bf16_f32 v47, v42, v43
	global_store_dwordx4 v[122:123], v[108:111], off offset:256
	global_store_dwordx4 v[56:57], v[44:47], off offset:256
	v_cvt_pk_bf16_f32 v92, v92, v93
	v_or_b32_e32 v108, 16, v152
	v_add_u32_e32 v44, 0x90, v152
	v_mad_i64_i32 v[108:109], s[78:79], v108, s76, v[120:121]
	v_mad_i64_i32 v[44:45], s[78:79], v44, s76, v[120:121]
	v_lshl_add_u64 v[108:109], v[108:109], 0, v[150:151]
	v_cvt_pk_bf16_f32 v93, v94, v95
	v_cvt_pk_bf16_f32 v94, v88, v89
	v_cvt_pk_bf16_f32 v95, v90, v91
	v_lshl_add_u64 v[44:45], v[44:45], 0, v[150:151]
	v_cvt_pk_bf16_f32 v28, v28, v29
	v_cvt_pk_bf16_f32 v29, v30, v31
	v_cvt_pk_bf16_f32 v30, v24, v25
	v_cvt_pk_bf16_f32 v31, v26, v27
	global_store_dwordx4 v[108:109], v[92:95], off offset:256
	global_store_dwordx4 v[44:45], v[28:31], off offset:256
	v_cvt_pk_bf16_f32 v76, v76, v77
	v_or_b32_e32 v92, 32, v152
	v_add_u32_e32 v28, 0xa0, v152
	v_mad_i64_i32 v[92:93], s[78:79], v92, s76, v[120:121]
	v_mad_i64_i32 v[28:29], s[78:79], v28, s76, v[120:121]
	v_lshl_add_u64 v[92:93], v[92:93], 0, v[150:151]
	v_cvt_pk_bf16_f32 v77, v78, v79
	v_cvt_pk_bf16_f32 v78, v72, v73
	v_cvt_pk_bf16_f32 v79, v74, v75
	v_lshl_add_u64 v[28:29], v[28:29], 0, v[150:151]
	v_cvt_pk_bf16_f32 v12, v12, v13
	v_cvt_pk_bf16_f32 v13, v14, v15
	v_cvt_pk_bf16_f32 v14, v8, v9
	v_cvt_pk_bf16_f32 v15, v10, v11
	global_store_dwordx4 v[92:93], v[76:79], off offset:256
	global_store_dwordx4 v[28:29], v[12:15], off offset:256
	v_cvt_pk_bf16_f32 v104, v116, v117
	v_or_b32_e32 v76, 48, v152
	v_add_u32_e32 v12, 0xb0, v152
	v_mad_i64_i32 v[76:77], s[78:79], v76, s76, v[120:121]
	v_mad_i64_i32 v[12:13], s[78:79], v12, s76, v[120:121]
	v_cvt_pk_bf16_f32 v105, v118, v119
	v_cvt_pk_bf16_f32 v106, v112, v113
	v_cvt_pk_bf16_f32 v107, v114, v115
	v_cvt_pk_bf16_f32 v88, v100, v101
	v_cvt_pk_bf16_f32 v89, v102, v103
	v_cvt_pk_bf16_f32 v90, v96, v97
	v_cvt_pk_bf16_f32 v91, v98, v99
	v_cvt_pk_bf16_f32 v72, v84, v85
	v_cvt_pk_bf16_f32 v73, v86, v87
	v_cvt_pk_bf16_f32 v74, v80, v81
	v_cvt_pk_bf16_f32 v75, v82, v83
	v_lshl_add_u64 v[76:77], v[76:77], 0, v[150:151]
	v_cvt_pk_bf16_f32 v71, v66, v67
	v_cvt_pk_bf16_f32 v63, v58, v59
	v_cvt_pk_bf16_f32 v40, v52, v53
	v_cvt_pk_bf16_f32 v41, v54, v55
	v_cvt_pk_bf16_f32 v42, v48, v49
	v_cvt_pk_bf16_f32 v43, v50, v51
	v_cvt_pk_bf16_f32 v24, v36, v37
	v_cvt_pk_bf16_f32 v25, v38, v39
	v_cvt_pk_bf16_f32 v26, v32, v33
	v_cvt_pk_bf16_f32 v27, v34, v35
	v_cvt_pk_bf16_f32 v8, v20, v21
	v_cvt_pk_bf16_f32 v9, v22, v23
	v_cvt_pk_bf16_f32 v10, v16, v17
	v_cvt_pk_bf16_f32 v11, v18, v19
	v_lshl_add_u64 v[12:13], v[12:13], 0, v[150:151]
	v_cvt_pk_bf16_f32 v4, v4, v5
	v_cvt_pk_bf16_f32 v5, v6, v7
	v_cvt_pk_bf16_f32 v6, v0, v1
	v_cvt_pk_bf16_f32 v7, v2, v3
	s_and_b64 vcc, exec, s[4:5]
	s_mov_b32 s77, s10
	s_mov_b32 s8, s12
	s_mov_b64 s[90:91], s[86:87]
	s_mov_b64 s[88:89], s[14:15]
	global_store_dwordx4 v[122:123], v[124:127], off
	global_store_dwordx4 v[108:109], v[104:107], off
	global_store_dwordx4 v[92:93], v[88:91], off
	global_store_dwordx4 v[76:77], v[72:75], off
	global_store_dwordx4 v[76:77], v[68:71], off offset:256
	global_store_dwordx4 v[56:57], v[60:63], off
	global_store_dwordx4 v[44:45], v[40:43], off
	global_store_dwordx4 v[28:29], v[24:27], off
	global_store_dwordx4 v[12:13], v[8:11], off
	global_store_dwordx4 v[12:13], v[4:7], off offset:256
	s_cbranch_vccz .LBB0_35
	s_waitcnt vmcnt(0)
	s_cmpk_gt_u32 s0, 0xff
	v_readlane_b32 s33, v228, 32
	v_readlane_b32 s56, v228, 35
	s_cbranch_scc1 .LBB0_42
	s_barrier

.LBB0_547:
	s_add_u32 s68, s54, s60
	s_addc_u32 s69, s55, s61
	s_add_u32 s64, s68, 0x100
	s_addc_u32 s65, s69, 0
	s_and_b64 s[62:63], s[58:59], exec
	s_cselect_b32 s65, s41, s65
	s_cselect_b32 s64, s82, s64
	s_add_u32 s60, s52, s60
	s_addc_u32 s61, s53, s61
	s_add_u32 s60, s60, 0x100
	s_addc_u32 s61, s61, 0
	s_and_b64 s[58:59], s[58:59], exec
	s_cselect_b32 s67, s25, s61
	s_cselect_b32 s66, s83, s60
	s_add_u32 s68, s68, 0x10080
	s_addc_u32 s69, s69, 0
	s_add_i32 s94, s79, s1
	s_add_i32 m0, s51, 0xc000
	s_add_i32 s95, s51, 0xe000
	s_add_i32 s93, s94, 0x2000
	s_add_u32 s62, s66, 0x10000
	s_addc_u32 s63, s67, 0
	s_add_i32 s92, s72, s1
	ds_read_b128 v[140:143], v149
	ds_read_b128 v[156:159], v149 offset:1024
	ds_read_b128 v[160:163], v149 offset:2048
	ds_read_b128 v[164:167], v149 offset:3072
	s_add_i32 s91, s92, 0x2000
	s_add_i32 s90, 0, 0x18000
	s_add_u32 s60, s64, 0x10000
	s_addc_u32 s61, s65, 0
	s_add_i32 s89, s90, s1
	s_add_i32 s88, s89, 0x2000
	s_add_u32 s58, s66, 0x10080
	s_addc_u32 s59, s67, 0
	s_add_i32 s87, s97, s1
	s_add_i32 s86, s87, 0x2000
	v_lshl_add_u64 v[144:145], s[68:69], 0, v[134:135]
	ds_read_b128 v[168:171], v150
	ds_read_b128 v[172:175], v150 offset:1024
	ds_read_b128 v[176:179], v150 offset:2048
	ds_read_b128 v[180:183], v150 offset:3072
	ds_read_b128 v[184:187], v150 offset:4096
	ds_read_b128 v[188:191], v150 offset:5120
	ds_read_b128 v[192:195], v150 offset:6144
	ds_read_b128 v[196:199], v150 offset:7168
	global_load_lds_dwordx4 v[144:145], off
	s_mov_b32 m0, s95
	v_lshl_add_u64 v[144:145], s[68:69], 0, v[130:131]
	global_load_lds_dwordx4 v[144:145], off
	s_waitcnt lgkmcnt(8)
	s_barrier
	s_waitcnt lgkmcnt(0)
	s_waitcnt lgkmcnt(0)
	v_mfma_f32_16x16x32_bf16 v[124:127], v[140:143], v[168:171], v[124:127]
	v_mfma_f32_16x16x32_bf16 v[120:123], v[160:163], v[168:171], v[120:123]
	v_mfma_f32_16x16x32_bf16 v[112:115], v[140:143], v[176:179], v[112:115]
	v_mfma_f32_16x16x32_bf16 v[104:107], v[160:163], v[176:179], v[104:107]
	v_mfma_f32_16x16x32_bf16 v[92:95], v[140:143], v[184:187], v[92:95]
	v_mfma_f32_16x16x32_bf16 v[88:91], v[160:163], v[184:187], v[88:91]
	v_mfma_f32_16x16x32_bf16 v[80:83], v[140:143], v[192:195], v[80:83]
	v_mfma_f32_16x16x32_bf16 v[72:75], v[160:163], v[192:195], v[72:75]
	v_mfma_f32_16x16x32_bf16 v[124:127], v[156:159], v[172:175], v[124:127]
	v_mfma_f32_16x16x32_bf16 v[120:123], v[164:167], v[172:175], v[120:123]
	v_mfma_f32_16x16x32_bf16 v[112:115], v[156:159], v[180:183], v[112:115]
	v_mfma_f32_16x16x32_bf16 v[104:107], v[164:167], v[180:183], v[104:107]
	v_mfma_f32_16x16x32_bf16 v[92:95], v[156:159], v[188:191], v[92:95]
	v_mfma_f32_16x16x32_bf16 v[88:91], v[164:167], v[188:191], v[88:91]
	v_mfma_f32_16x16x32_bf16 v[80:83], v[156:159], v[196:199], v[80:83]
	v_mfma_f32_16x16x32_bf16 v[72:75], v[164:167], v[196:199], v[72:75]
	s_barrier
	s_mov_b32 m0, s94
	v_lshl_add_u64 v[144:145], s[66:67], 0, v[132:133]
	ds_read_b128 v[200:203], v151
	ds_read_b128 v[204:207], v151 offset:1024
	ds_read_b128 v[208:211], v151 offset:2048
	ds_read_b128 v[212:215], v151 offset:3072
	global_load_lds_dwordx4 v[144:145], off
	s_mov_b32 m0, s93
	v_lshl_add_u64 v[152:153], s[66:67], 0, v[128:129]
	global_load_lds_dwordx4 v[152:153], off
	s_barrier
	s_waitcnt lgkmcnt(0)
	s_waitcnt lgkmcnt(0)
	v_mfma_f32_16x16x32_bf16 v[116:119], v[200:203], v[168:171], v[116:119]
	v_mfma_f32_16x16x32_bf16 v[108:111], v[208:211], v[168:171], v[108:111]
	v_mfma_f32_16x16x32_bf16 v[100:103], v[200:203], v[176:179], v[100:103]
	v_mfma_f32_16x16x32_bf16 v[96:99], v[208:211], v[176:179], v[96:99]
	v_mfma_f32_16x16x32_bf16 v[84:87], v[200:203], v[184:187], v[84:87]
	v_mfma_f32_16x16x32_bf16 v[76:79], v[208:211], v[184:187], v[76:79]
	v_mfma_f32_16x16x32_bf16 v[68:71], v[200:203], v[192:195], v[68:71]
	v_mfma_f32_16x16x32_bf16 v[64:67], v[208:211], v[192:195], v[64:67]
	v_mfma_f32_16x16x32_bf16 v[116:119], v[204:207], v[172:175], v[116:119]
	v_mfma_f32_16x16x32_bf16 v[108:111], v[212:215], v[172:175], v[108:111]
	v_mfma_f32_16x16x32_bf16 v[100:103], v[204:207], v[180:183], v[100:103]
	v_mfma_f32_16x16x32_bf16 v[96:99], v[212:215], v[180:183], v[96:99]
	v_mfma_f32_16x16x32_bf16 v[84:87], v[204:207], v[188:191], v[84:87]
	v_mfma_f32_16x16x32_bf16 v[76:79], v[212:215], v[188:191], v[76:79]
	v_mfma_f32_16x16x32_bf16 v[68:71], v[204:207], v[196:199], v[68:71]
	v_mfma_f32_16x16x32_bf16 v[64:67], v[212:215], v[196:199], v[64:67]
	s_mov_b32 m0, s51
	v_lshl_add_u64 v[216:217], s[64:65], 0, v[134:135]
	s_barrier
	ds_read_b128 v[168:171], v150 offset:16384
	ds_read_b128 v[172:175], v150 offset:17408
	ds_read_b128 v[176:179], v150 offset:18432
	ds_read_b128 v[180:183], v150 offset:19456
	ds_read_b128 v[184:187], v150 offset:20480
	ds_read_b128 v[188:191], v150 offset:21504
	ds_read_b128 v[192:195], v150 offset:22528
	ds_read_b128 v[196:199], v150 offset:23552
	global_load_lds_dwordx4 v[216:217], off
	s_mov_b32 m0, s71
	v_lshl_add_u64 v[218:219], s[64:65], 0, v[130:131]
	global_load_lds_dwordx4 v[218:219], off
	s_barrier
	s_waitcnt lgkmcnt(0)
	s_waitcnt lgkmcnt(0)
	v_mfma_f32_16x16x32_bf16 v[60:63], v[140:143], v[168:171], v[60:63]
	v_mfma_f32_16x16x32_bf16 v[56:59], v[160:163], v[168:171], v[56:59]
	v_mfma_f32_16x16x32_bf16 v[52:55], v[140:143], v[176:179], v[52:55]
	v_mfma_f32_16x16x32_bf16 v[48:51], v[160:163], v[176:179], v[48:51]
	v_mfma_f32_16x16x32_bf16 v[28:31], v[140:143], v[184:187], v[28:31]
	v_mfma_f32_16x16x32_bf16 v[20:23], v[160:163], v[184:187], v[20:23]
	v_mfma_f32_16x16x32_bf16 v[24:27], v[140:143], v[192:195], v[24:27]
	v_mfma_f32_16x16x32_bf16 v[16:19], v[160:163], v[192:195], v[16:19]
	v_mfma_f32_16x16x32_bf16 v[60:63], v[156:159], v[172:175], v[60:63]
	v_mfma_f32_16x16x32_bf16 v[56:59], v[164:167], v[172:175], v[56:59]
	v_mfma_f32_16x16x32_bf16 v[52:55], v[156:159], v[180:183], v[52:55]
	v_mfma_f32_16x16x32_bf16 v[48:51], v[164:167], v[180:183], v[48:51]
	v_mfma_f32_16x16x32_bf16 v[28:31], v[156:159], v[188:191], v[28:31]
	v_mfma_f32_16x16x32_bf16 v[20:23], v[164:167], v[188:191], v[20:23]
	v_mfma_f32_16x16x32_bf16 v[24:27], v[156:159], v[196:199], v[24:27]
	v_mfma_f32_16x16x32_bf16 v[16:19], v[164:167], v[196:199], v[16:19]
	s_barrier
	s_mov_b32 m0, s92
	v_lshl_add_u64 v[140:141], s[62:63], 0, v[132:133]
	global_load_lds_dwordx4 v[140:141], off
	s_mov_b32 m0, s91
	v_lshl_add_u64 v[140:141], s[62:63], 0, v[128:129]
	global_load_lds_dwordx4 v[140:141], off
	s_waitcnt vmcnt(6)
	s_barrier
	v_mfma_f32_16x16x32_bf16 v[44:47], v[200:203], v[168:171], v[44:47]
	v_mfma_f32_16x16x32_bf16 v[40:43], v[208:211], v[168:171], v[40:43]
	v_mfma_f32_16x16x32_bf16 v[36:39], v[200:203], v[176:179], v[36:39]
	v_mfma_f32_16x16x32_bf16 v[32:35], v[208:211], v[176:179], v[32:35]
	v_mfma_f32_16x16x32_bf16 v[12:15], v[200:203], v[184:187], v[12:15]
	v_mfma_f32_16x16x32_bf16 v[4:7], v[208:211], v[184:187], v[4:7]
	v_mfma_f32_16x16x32_bf16 v[8:11], v[200:203], v[192:195], v[8:11]
	v_mfma_f32_16x16x32_bf16 v[0:3], v[208:211], v[192:195], v[0:3]
	v_mfma_f32_16x16x32_bf16 v[44:47], v[204:207], v[172:175], v[44:47]
	v_mfma_f32_16x16x32_bf16 v[40:43], v[212:215], v[172:175], v[40:43]
	v_mfma_f32_16x16x32_bf16 v[36:39], v[204:207], v[180:183], v[36:39]
	v_mfma_f32_16x16x32_bf16 v[32:35], v[212:215], v[180:183], v[32:35]
	v_mfma_f32_16x16x32_bf16 v[12:15], v[204:207], v[188:191], v[12:15]
	v_mfma_f32_16x16x32_bf16 v[4:7], v[212:215], v[188:191], v[4:7]
	v_mfma_f32_16x16x32_bf16 v[8:11], v[204:207], v[196:199], v[8:11]
	v_mfma_f32_16x16x32_bf16 v[0:3], v[212:215], v[196:199], v[0:3]
	v_add_u32_e32 v164, s90, v147
	s_barrier
	ds_read_b128 v[140:143], v164
	ds_read_b128 v[156:159], v164 offset:1024
	ds_read_b128 v[160:163], v164 offset:2048
	ds_read_b128 v[164:167], v164 offset:3072
	s_mov_b32 m0, s73
	v_lshl_add_u64 v[200:201], s[60:61], 0, v[134:135]
	ds_read_b128 v[168:171], v150 offset:32768
	ds_read_b128 v[172:175], v150 offset:33792
	ds_read_b128 v[176:179], v150 offset:34816
	ds_read_b128 v[180:183], v150 offset:35840
	ds_read_b128 v[184:187], v150 offset:36864
	ds_read_b128 v[188:191], v150 offset:37888
	ds_read_b128 v[192:195], v150 offset:38912
	ds_read_b128 v[196:199], v150 offset:39936
	global_load_lds_dwordx4 v[200:201], off
	s_mov_b32 m0, s74
	v_lshl_add_u64 v[200:201], s[60:61], 0, v[130:131]
	global_load_lds_dwordx4 v[200:201], off
	s_waitcnt lgkmcnt(8)
	s_barrier
	s_waitcnt lgkmcnt(0)
	s_waitcnt lgkmcnt(0)
	v_mfma_f32_16x16x32_bf16 v[124:127], v[140:143], v[168:171], v[124:127]
	v_mfma_f32_16x16x32_bf16 v[120:123], v[160:163], v[168:171], v[120:123]
	v_mfma_f32_16x16x32_bf16 v[112:115], v[140:143], v[176:179], v[112:115]
	v_mfma_f32_16x16x32_bf16 v[104:107], v[160:163], v[176:179], v[104:107]
	v_mfma_f32_16x16x32_bf16 v[92:95], v[140:143], v[184:187], v[92:95]
	v_mfma_f32_16x16x32_bf16 v[88:91], v[160:163], v[184:187], v[88:91]
	v_mfma_f32_16x16x32_bf16 v[80:83], v[140:143], v[192:195], v[80:83]
	v_mfma_f32_16x16x32_bf16 v[72:75], v[160:163], v[192:195], v[72:75]
	v_mfma_f32_16x16x32_bf16 v[124:127], v[156:159], v[172:175], v[124:127]
	v_mfma_f32_16x16x32_bf16 v[120:123], v[164:167], v[172:175], v[120:123]
	v_mfma_f32_16x16x32_bf16 v[112:115], v[156:159], v[180:183], v[112:115]
	v_mfma_f32_16x16x32_bf16 v[104:107], v[164:167], v[180:183], v[104:107]
	v_mfma_f32_16x16x32_bf16 v[92:95], v[156:159], v[188:191], v[92:95]
	v_mfma_f32_16x16x32_bf16 v[88:91], v[164:167], v[188:191], v[88:91]
	v_mfma_f32_16x16x32_bf16 v[80:83], v[156:159], v[196:199], v[80:83]
	v_mfma_f32_16x16x32_bf16 v[72:75], v[164:167], v[196:199], v[72:75]
	s_barrier
	s_mov_b32 m0, s89
	v_add_u32_e32 v212, s97, v147
	v_lshl_add_u64 v[144:145], v[144:145], 0, s[6:7]
	ds_read_b128 v[200:203], v212
	ds_read_b128 v[204:207], v212 offset:1024
	ds_read_b128 v[208:211], v212 offset:2048
	ds_read_b128 v[212:215], v212 offset:3072
	global_load_lds_dwordx4 v[144:145], off
	s_mov_b32 m0, s88
	v_lshl_add_u64 v[144:145], v[152:153], 0, s[6:7]
	global_load_lds_dwordx4 v[144:145], off
	s_barrier
	s_waitcnt lgkmcnt(0)
	s_waitcnt lgkmcnt(0)
	v_mfma_f32_16x16x32_bf16 v[116:119], v[200:203], v[168:171], v[116:119]
	v_mfma_f32_16x16x32_bf16 v[108:111], v[208:211], v[168:171], v[108:111]
	v_mfma_f32_16x16x32_bf16 v[100:103], v[200:203], v[176:179], v[100:103]
	v_mfma_f32_16x16x32_bf16 v[96:99], v[208:211], v[176:179], v[96:99]
	v_mfma_f32_16x16x32_bf16 v[84:87], v[200:203], v[184:187], v[84:87]
	v_mfma_f32_16x16x32_bf16 v[76:79], v[208:211], v[184:187], v[76:79]
	v_mfma_f32_16x16x32_bf16 v[68:71], v[200:203], v[192:195], v[68:71]
	v_mfma_f32_16x16x32_bf16 v[64:67], v[208:211], v[192:195], v[64:67]
	v_mfma_f32_16x16x32_bf16 v[116:119], v[204:207], v[172:175], v[116:119]
	v_mfma_f32_16x16x32_bf16 v[108:111], v[212:215], v[172:175], v[108:111]
	v_mfma_f32_16x16x32_bf16 v[100:103], v[204:207], v[180:183], v[100:103]
	v_mfma_f32_16x16x32_bf16 v[96:99], v[212:215], v[180:183], v[96:99]
	v_mfma_f32_16x16x32_bf16 v[84:87], v[204:207], v[188:191], v[84:87]
	v_mfma_f32_16x16x32_bf16 v[76:79], v[212:215], v[188:191], v[76:79]
	v_mfma_f32_16x16x32_bf16 v[68:71], v[204:207], v[196:199], v[68:71]
	v_mfma_f32_16x16x32_bf16 v[64:67], v[212:215], v[196:199], v[64:67]
	s_mov_b32 m0, s76
	v_lshl_add_u64 v[144:145], v[216:217], 0, s[6:7]
	s_barrier
	ds_read_b128 v[168:171], v150 offset:49152
	ds_read_b128 v[172:175], v150 offset:50176
	ds_read_b128 v[176:179], v150 offset:51200
	ds_read_b128 v[180:183], v150 offset:52224
	ds_read_b128 v[184:187], v150 offset:53248
	ds_read_b128 v[188:191], v150 offset:54272
	ds_read_b128 v[192:195], v150 offset:55296
	ds_read_b128 v[196:199], v150 offset:56320
	global_load_lds_dwordx4 v[144:145], off
	s_mov_b32 m0, s77
	v_lshl_add_u64 v[144:145], v[218:219], 0, s[6:7]
	global_load_lds_dwordx4 v[144:145], off
	s_barrier
	s_waitcnt lgkmcnt(0)
	s_waitcnt lgkmcnt(0)
	v_mfma_f32_16x16x32_bf16 v[60:63], v[140:143], v[168:171], v[60:63]
	v_mfma_f32_16x16x32_bf16 v[56:59], v[160:163], v[168:171], v[56:59]
	v_mfma_f32_16x16x32_bf16 v[52:55], v[140:143], v[176:179], v[52:55]
	v_mfma_f32_16x16x32_bf16 v[48:51], v[160:163], v[176:179], v[48:51]
	v_mfma_f32_16x16x32_bf16 v[28:31], v[140:143], v[184:187], v[28:31]
	v_mfma_f32_16x16x32_bf16 v[20:23], v[160:163], v[184:187], v[20:23]
	v_mfma_f32_16x16x32_bf16 v[24:27], v[140:143], v[192:195], v[24:27]
	v_mfma_f32_16x16x32_bf16 v[16:19], v[160:163], v[192:195], v[16:19]
	v_mfma_f32_16x16x32_bf16 v[60:63], v[156:159], v[172:175], v[60:63]
	v_mfma_f32_16x16x32_bf16 v[56:59], v[164:167], v[172:175], v[56:59]
	v_mfma_f32_16x16x32_bf16 v[52:55], v[156:159], v[180:183], v[52:55]
	v_mfma_f32_16x16x32_bf16 v[48:51], v[164:167], v[180:183], v[48:51]
	v_mfma_f32_16x16x32_bf16 v[28:31], v[156:159], v[188:191], v[28:31]
	v_mfma_f32_16x16x32_bf16 v[20:23], v[164:167], v[188:191], v[20:23]
	v_mfma_f32_16x16x32_bf16 v[24:27], v[156:159], v[196:199], v[24:27]
	v_mfma_f32_16x16x32_bf16 v[16:19], v[164:167], v[196:199], v[16:19]
	s_barrier
	s_mov_b32 m0, s87
	v_lshl_add_u64 v[140:141], s[58:59], 0, v[132:133]
	global_load_lds_dwordx4 v[140:141], off
	s_mov_b32 m0, s86
	v_lshl_add_u64 v[140:141], s[58:59], 0, v[128:129]
	global_load_lds_dwordx4 v[140:141], off
	s_waitcnt vmcnt(6)
	s_barrier
	v_mfma_f32_16x16x32_bf16 v[44:47], v[200:203], v[168:171], v[44:47]
	v_mfma_f32_16x16x32_bf16 v[40:43], v[208:211], v[168:171], v[40:43]
	v_mfma_f32_16x16x32_bf16 v[36:39], v[200:203], v[176:179], v[36:39]
	v_mfma_f32_16x16x32_bf16 v[32:35], v[208:211], v[176:179], v[32:35]
	v_mfma_f32_16x16x32_bf16 v[12:15], v[200:203], v[184:187], v[12:15]
	v_mfma_f32_16x16x32_bf16 v[4:7], v[208:211], v[184:187], v[4:7]
	v_mfma_f32_16x16x32_bf16 v[8:11], v[200:203], v[192:195], v[8:11]
	v_mfma_f32_16x16x32_bf16 v[0:3], v[208:211], v[192:195], v[0:3]
	v_mfma_f32_16x16x32_bf16 v[44:47], v[204:207], v[172:175], v[44:47]
	v_mfma_f32_16x16x32_bf16 v[40:43], v[212:215], v[172:175], v[40:43]
	v_mfma_f32_16x16x32_bf16 v[36:39], v[204:207], v[180:183], v[36:39]
	v_mfma_f32_16x16x32_bf16 v[32:35], v[212:215], v[180:183], v[32:35]
	v_mfma_f32_16x16x32_bf16 v[12:15], v[204:207], v[188:191], v[12:15]
	v_mfma_f32_16x16x32_bf16 v[4:7], v[212:215], v[188:191], v[4:7]
	v_mfma_f32_16x16x32_bf16 v[8:11], v[204:207], v[196:199], v[8:11]
	v_mfma_f32_16x16x32_bf16 v[0:3], v[212:215], v[196:199], v[0:3]
	s_andn2_b64 vcc, exec, s[56:57]
	s_mov_b64 s[58:59], -1
	s_mov_b64 s[56:57], 0
	s_mov_b64 s[60:61], 0x100
	s_barrier
	s_cbranch_vccz .LBB0_547
	v_lshl_add_u32 v142, s50, 8, v146
	v_lshl_or_b32 v140, s81, 8, v148
	v_ashrrev_i32_e32 v143, 31, v142
	v_lshlrev_b64 v[144:145], 11, v[142:143]
	v_ashrrev_i32_e32 v141, 31, v140
	v_lshl_add_u64 v[152:153], s[28:29], 0, v[144:145]
	v_lshlrev_b64 v[144:145], 1, v[140:141]
	v_lshl_add_u64 v[140:141], v[152:153], 0, v[144:145]
	v_or_b32_e32 v152, 16, v142
	v_ashrrev_i32_e32 v153, 31, v152
	v_lshlrev_b64 v[152:153], 11, v[152:153]
	global_load_dwordx4 v[156:159], v[140:141], off
	global_load_dwordx4 v[160:163], v[140:141], off offset:256
	v_lshl_add_u64 v[152:153], s[28:29], 0, v[152:153]
	v_lshl_add_u64 v[152:153], v[152:153], 0, v[144:145]
	global_load_dwordx4 v[164:167], v[152:153], off
	global_load_dwordx4 v[168:171], v[152:153], off offset:256
	s_waitcnt vmcnt(0)
	v_lshlrev_b32_e32 v172, 16, v156
	v_and_b32_e32 v173, 0xffff0000, v156
	v_lshlrev_b32_e32 v156, 16, v157
	v_and_b32_e32 v157, 0xffff0000, v157
	v_lshlrev_b32_e32 v176, 16, v160
	v_and_b32_e32 v177, 0xffff0000, v160
	v_lshlrev_b32_e32 v160, 16, v161
	v_and_b32_e32 v161, 0xffff0000, v161
	v_lshlrev_b32_e32 v178, 16, v162
	v_and_b32_e32 v179, 0xffff0000, v162
	v_lshlrev_b32_e32 v162, 16, v163
	v_and_b32_e32 v163, 0xffff0000, v163
	v_lshlrev_b32_e32 v174, 16, v158
	v_and_b32_e32 v175, 0xffff0000, v158
	v_lshlrev_b32_e32 v158, 16, v159
	v_and_b32_e32 v159, 0xffff0000, v159
	v_pk_mul_f32 v[126:127], v[126:127], v[156:157]
	v_pk_mul_f32 v[118:119], v[118:119], v[160:161]
	v_pk_mul_f32 v[156:157], v[110:111], v[162:163]
	v_lshlrev_b32_e32 v160, 16, v164
	v_and_b32_e32 v161, 0xffff0000, v164
	v_lshlrev_b32_e32 v162, 16, v165
	v_and_b32_e32 v163, 0xffff0000, v165
	v_lshlrev_b32_e32 v164, 16, v166
	v_and_b32_e32 v165, 0xffff0000, v166
	v_lshlrev_b32_e32 v166, 16, v167
	v_and_b32_e32 v167, 0xffff0000, v167
	v_pk_mul_f32 v[124:125], v[124:125], v[172:173]
	v_pk_mul_f32 v[122:123], v[122:123], v[158:159]
	v_pk_mul_f32 v[120:121], v[120:121], v[174:175]
	v_lshlrev_b32_e32 v172, 16, v168
	v_and_b32_e32 v173, 0xffff0000, v168
	v_lshlrev_b32_e32 v168, 16, v169
	v_and_b32_e32 v169, 0xffff0000, v169
	v_lshlrev_b32_e32 v174, 16, v170
	v_and_b32_e32 v175, 0xffff0000, v170
	v_lshlrev_b32_e32 v170, 16, v171
	v_and_b32_e32 v171, 0xffff0000, v171
	v_pk_mul_f32 v[114:115], v[114:115], v[162:163]
	v_pk_mul_f32 v[112:113], v[112:113], v[160:161]
	v_pk_mul_f32 v[106:107], v[106:107], v[166:167]
	v_pk_mul_f32 v[104:105], v[104:105], v[164:165]
	v_pk_mul_f32 v[116:117], v[116:117], v[176:177]
	v_pk_mul_f32 v[158:159], v[108:109], v[178:179]
	v_cvt_pk_bf16_f32 v108, v124, v125
	v_cvt_pk_bf16_f32 v109, v126, v127
	v_cvt_pk_bf16_f32 v110, v120, v121
	v_cvt_pk_bf16_f32 v111, v122, v123
	v_pk_mul_f32 v[102:103], v[102:103], v[168:169]
	v_pk_mul_f32 v[100:101], v[100:101], v[172:173]
	v_pk_mul_f32 v[120:121], v[98:99], v[170:171]
	v_pk_mul_f32 v[122:123], v[96:97], v[174:175]
	v_cvt_pk_bf16_f32 v96, v112, v113
	v_cvt_pk_bf16_f32 v97, v114, v115
	v_cvt_pk_bf16_f32 v98, v104, v105
	v_cvt_pk_bf16_f32 v99, v106, v107
	v_cvt_pk_bf16_f32 v116, v116, v117
	v_cvt_pk_bf16_f32 v117, v118, v119
	v_cvt_pk_bf16_f32 v118, v158, v159
	v_cvt_pk_bf16_f32 v119, v156, v157
	global_store_dwordx4 v[140:141], v[108:111], off
	global_store_dwordx4 v[140:141], v[116:119], off offset:256
	v_cvt_pk_bf16_f32 v100, v100, v101
	v_cvt_pk_bf16_f32 v101, v102, v103
	v_cvt_pk_bf16_f32 v102, v122, v123
	v_cvt_pk_bf16_f32 v103, v120, v121
	global_store_dwordx4 v[152:153], v[96:99], off
	global_store_dwordx4 v[152:153], v[100:103], off offset:256
	s_nop 0
	v_or_b32_e32 v96, 32, v142
	v_ashrrev_i32_e32 v97, 31, v96
	v_lshlrev_b64 v[96:97], 11, v[96:97]
	v_or_b32_e32 v104, 48, v142
	v_lshl_add_u64 v[96:97], s[28:29], 0, v[96:97]
	v_ashrrev_i32_e32 v105, 31, v104
	v_lshl_add_u64 v[112:113], v[96:97], 0, v[144:145]
	v_lshlrev_b64 v[104:105], 11, v[104:105]
	global_load_dwordx4 v[96:99], v[112:113], off
	global_load_dwordx4 v[100:103], v[112:113], off offset:256
	v_lshl_add_u64 v[104:105], s[28:29], 0, v[104:105]
	v_lshl_add_u64 v[114:115], v[104:105], 0, v[144:145]
	global_load_dwordx4 v[104:107], v[114:115], off
	global_load_dwordx4 v[108:111], v[114:115], off offset:256
	s_waitcnt vmcnt(0)
	v_lshlrev_b32_e32 v116, 16, v96
	v_and_b32_e32 v117, 0xffff0000, v96
	v_lshlrev_b32_e32 v96, 16, v97
	v_and_b32_e32 v97, 0xffff0000, v97
	v_lshlrev_b32_e32 v120, 16, v100
	v_and_b32_e32 v121, 0xffff0000, v100
	v_lshlrev_b32_e32 v100, 16, v101
	v_and_b32_e32 v101, 0xffff0000, v101
	v_lshlrev_b32_e32 v122, 16, v102
	v_and_b32_e32 v123, 0xffff0000, v102
	v_lshlrev_b32_e32 v102, 16, v103
	v_and_b32_e32 v103, 0xffff0000, v103
	v_lshlrev_b32_e32 v118, 16, v98
	v_and_b32_e32 v119, 0xffff0000, v98
	v_lshlrev_b32_e32 v98, 16, v99
	v_and_b32_e32 v99, 0xffff0000, v99
	v_pk_mul_f32 v[94:95], v[94:95], v[96:97]
	v_pk_mul_f32 v[86:87], v[86:87], v[100:101]
	v_pk_mul_f32 v[96:97], v[78:79], v[102:103]
	v_lshlrev_b32_e32 v100, 16, v104
	v_and_b32_e32 v101, 0xffff0000, v104
	v_lshlrev_b32_e32 v102, 16, v105
	v_and_b32_e32 v103, 0xffff0000, v105
	v_lshlrev_b32_e32 v104, 16, v106
	v_and_b32_e32 v105, 0xffff0000, v106
	v_lshlrev_b32_e32 v106, 16, v107
	v_and_b32_e32 v107, 0xffff0000, v107
	v_pk_mul_f32 v[92:93], v[92:93], v[116:117]
	v_pk_mul_f32 v[90:91], v[90:91], v[98:99]
	v_pk_mul_f32 v[88:89], v[88:89], v[118:119]
	v_lshlrev_b32_e32 v116, 16, v108
	v_and_b32_e32 v117, 0xffff0000, v108
	v_lshlrev_b32_e32 v108, 16, v109
	v_and_b32_e32 v109, 0xffff0000, v109
	v_lshlrev_b32_e32 v118, 16, v110
	v_and_b32_e32 v119, 0xffff0000, v110
	v_lshlrev_b32_e32 v110, 16, v111
	v_and_b32_e32 v111, 0xffff0000, v111
	v_pk_mul_f32 v[82:83], v[82:83], v[102:103]
	v_pk_mul_f32 v[80:81], v[80:81], v[100:101]
	v_pk_mul_f32 v[74:75], v[74:75], v[106:107]
	v_pk_mul_f32 v[72:73], v[72:73], v[104:105]
	v_pk_mul_f32 v[84:85], v[84:85], v[120:121]
	v_pk_mul_f32 v[98:99], v[76:77], v[122:123]
	v_cvt_pk_bf16_f32 v76, v92, v93
	v_cvt_pk_bf16_f32 v77, v94, v95
	v_cvt_pk_bf16_f32 v78, v88, v89
	v_cvt_pk_bf16_f32 v79, v90, v91
	v_pk_mul_f32 v[70:71], v[70:71], v[108:109]
	v_pk_mul_f32 v[68:69], v[68:69], v[116:117]
	v_pk_mul_f32 v[88:89], v[66:67], v[110:111]
	v_pk_mul_f32 v[90:91], v[64:65], v[118:119]
	v_cvt_pk_bf16_f32 v64, v80, v81
	v_cvt_pk_bf16_f32 v65, v82, v83
	v_cvt_pk_bf16_f32 v66, v72, v73
	v_cvt_pk_bf16_f32 v67, v74, v75
	v_cvt_pk_bf16_f32 v84, v84, v85
	v_cvt_pk_bf16_f32 v85, v86, v87
	v_cvt_pk_bf16_f32 v86, v98, v99
	v_cvt_pk_bf16_f32 v87, v96, v97
	global_store_dwordx4 v[112:113], v[76:79], off
	global_store_dwordx4 v[112:113], v[84:87], off offset:256
	v_cvt_pk_bf16_f32 v68, v68, v69
	v_cvt_pk_bf16_f32 v69, v70, v71
	v_cvt_pk_bf16_f32 v70, v90, v91
	v_cvt_pk_bf16_f32 v71, v88, v89
	global_store_dwordx4 v[114:115], v[64:67], off
	global_store_dwordx4 v[114:115], v[68:71], off offset:256
	s_mov_b32 s25, 0x40000
	v_add_co_u32_e32 v80, vcc, s25, v140
	s_mov_b64 s[52:53], 0x40000
	s_nop 0
	v_addc_co_u32_e32 v81, vcc, 0, v141, vcc
	s_mov_b32 s25, 0x48000
	v_lshl_add_u64 v[82:83], v[140:141], 0, s[52:53]
	v_add_co_u32_e32 v84, vcc, s25, v140
	s_mov_b64 s[52:53], 0x48000
	global_load_dwordx4 v[64:67], v[80:81], off
	global_load_dwordx4 v[68:71], v[82:83], off offset:256
	v_addc_co_u32_e32 v85, vcc, 0, v141, vcc
	v_lshl_add_u64 v[86:87], v[140:141], 0, s[52:53]
	global_load_dwordx4 v[72:75], v[84:85], off
	global_load_dwordx4 v[76:79], v[86:87], off offset:256
	s_waitcnt vmcnt(0)
	v_lshlrev_b32_e32 v88, 16, v64
	v_and_b32_e32 v89, 0xffff0000, v64
	v_lshlrev_b32_e32 v64, 16, v65
	v_and_b32_e32 v65, 0xffff0000, v65
	v_lshlrev_b32_e32 v90, 16, v66
	v_and_b32_e32 v91, 0xffff0000, v66
	v_lshlrev_b32_e32 v66, 16, v67
	v_and_b32_e32 v67, 0xffff0000, v67
	v_lshlrev_b32_e32 v92, 16, v68
	v_and_b32_e32 v93, 0xffff0000, v68
	v_lshlrev_b32_e32 v68, 16, v69
	v_and_b32_e32 v69, 0xffff0000, v69
	v_lshlrev_b32_e32 v94, 16, v70
	v_and_b32_e32 v95, 0xffff0000, v70
	v_lshlrev_b32_e32 v70, 16, v71
	v_and_b32_e32 v71, 0xffff0000, v71
	v_lshlrev_b32_e32 v96, 16, v72
	v_and_b32_e32 v97, 0xffff0000, v72
	v_lshlrev_b32_e32 v72, 16, v73
	v_and_b32_e32 v73, 0xffff0000, v73
	v_lshlrev_b32_e32 v98, 16, v74
	v_and_b32_e32 v99, 0xffff0000, v74
	v_lshlrev_b32_e32 v74, 16, v75
	v_and_b32_e32 v75, 0xffff0000, v75
	v_lshlrev_b32_e32 v100, 16, v76
	v_and_b32_e32 v101, 0xffff0000, v76
	v_lshlrev_b32_e32 v76, 16, v77
	v_and_b32_e32 v77, 0xffff0000, v77
	v_lshlrev_b32_e32 v102, 16, v78
	v_and_b32_e32 v103, 0xffff0000, v78
	v_lshlrev_b32_e32 v78, 16, v79
	v_and_b32_e32 v79, 0xffff0000, v79
	v_pk_mul_f32 v[62:63], v[62:63], v[64:65]
	v_pk_mul_f32 v[60:61], v[60:61], v[88:89]
	v_pk_mul_f32 v[58:59], v[58:59], v[66:67]
	v_pk_mul_f32 v[56:57], v[56:57], v[90:91]
	v_pk_mul_f32 v[46:47], v[46:47], v[68:69]
	v_pk_mul_f32 v[44:45], v[44:45], v[92:93]
	v_pk_mul_f32 v[42:43], v[42:43], v[70:71]
	v_pk_mul_f32 v[40:41], v[40:41], v[94:95]
	v_pk_mul_f32 v[54:55], v[54:55], v[72:73]
	v_pk_mul_f32 v[52:53], v[52:53], v[96:97]
	v_pk_mul_f32 v[50:51], v[50:51], v[74:75]
	v_pk_mul_f32 v[48:49], v[48:49], v[98:99]
	v_pk_mul_f32 v[64:65], v[38:39], v[76:77]
	v_pk_mul_f32 v[66:67], v[36:37], v[100:101]
	v_pk_mul_f32 v[68:69], v[34:35], v[78:79]
	v_pk_mul_f32 v[70:71], v[32:33], v[102:103]
	v_cvt_pk_bf16_f32 v32, v60, v61
	v_cvt_pk_bf16_f32 v33, v62, v63
	v_cvt_pk_bf16_f32 v34, v56, v57
	v_cvt_pk_bf16_f32 v35, v58, v59
	v_cvt_pk_bf16_f32 v36, v44, v45
	v_cvt_pk_bf16_f32 v37, v46, v47
	v_cvt_pk_bf16_f32 v38, v40, v41
	v_cvt_pk_bf16_f32 v39, v42, v43
	v_cvt_pk_bf16_f32 v40, v52, v53
	v_cvt_pk_bf16_f32 v41, v54, v55
	v_cvt_pk_bf16_f32 v42, v48, v49
	v_cvt_pk_bf16_f32 v43, v50, v51
	v_cvt_pk_bf16_f32 v44, v66, v67
	v_cvt_pk_bf16_f32 v45, v64, v65
	v_cvt_pk_bf16_f32 v46, v70, v71
	v_cvt_pk_bf16_f32 v47, v68, v69
	global_store_dwordx4 v[80:81], v[32:35], off
	global_store_dwordx4 v[82:83], v[36:39], off offset:256
	global_store_dwordx4 v[84:85], v[40:43], off
	global_store_dwordx4 v[86:87], v[44:47], off offset:256
	v_add_co_u32_e32 v48, vcc, s80, v140
	s_mov_b32 s25, 0x50000
	s_nop 0
	v_addc_co_u32_e32 v49, vcc, 0, v141, vcc
	v_add_co_u32_e32 v52, vcc, s25, v140
	v_lshl_add_u64 v[50:51], v[140:141], 0, s[14:15]
	s_nop 0
	v_addc_co_u32_e32 v53, vcc, 0, v141, vcc
	s_mov_b64 s[52:53], 0x50000
	global_load_dwordx4 v[32:35], v[48:49], off
	global_load_dwordx4 v[36:39], v[50:51], off offset:256
	global_load_dwordx4 v[40:43], v[52:53], off
	v_lshl_add_u64 v[54:55], v[140:141], 0, s[52:53]
	global_load_dwordx4 v[44:47], v[54:55], off offset:256
	s_and_b64 vcc, exec, s[4:5]
	s_mov_b32 s81, s24
	s_mov_b32 s50, s40
	s_mov_b64 s[52:53], s[48:49]
	s_mov_b64 s[54:55], s[46:47]
	s_waitcnt vmcnt(0)
	v_lshlrev_b32_e32 v56, 16, v32
	v_lshlrev_b32_e32 v60, 16, v36
	v_and_b32_e32 v61, 0xffff0000, v36
	v_lshlrev_b32_e32 v36, 16, v37
	v_and_b32_e32 v37, 0xffff0000, v37
	v_lshlrev_b32_e32 v64, 16, v40
	v_and_b32_e32 v65, 0xffff0000, v40
	v_lshlrev_b32_e32 v40, 16, v41
	v_and_b32_e32 v41, 0xffff0000, v41
	v_lshlrev_b32_e32 v66, 16, v42
	v_and_b32_e32 v67, 0xffff0000, v42
	v_lshlrev_b32_e32 v42, 16, v43
	v_and_b32_e32 v43, 0xffff0000, v43
	v_and_b32_e32 v57, 0xffff0000, v32
	v_lshlrev_b32_e32 v32, 16, v33
	v_and_b32_e32 v33, 0xffff0000, v33
	v_lshlrev_b32_e32 v58, 16, v34
	v_and_b32_e32 v59, 0xffff0000, v34
	v_lshlrev_b32_e32 v34, 16, v35
	v_and_b32_e32 v35, 0xffff0000, v35
	v_lshlrev_b32_e32 v62, 16, v38
	v_and_b32_e32 v63, 0xffff0000, v38
	v_lshlrev_b32_e32 v38, 16, v39
	v_and_b32_e32 v39, 0xffff0000, v39
	v_lshlrev_b32_e32 v68, 16, v44
	v_and_b32_e32 v69, 0xffff0000, v44
	v_lshlrev_b32_e32 v44, 16, v45
	v_and_b32_e32 v45, 0xffff0000, v45
	v_lshlrev_b32_e32 v70, 16, v46
	v_and_b32_e32 v71, 0xffff0000, v46
	v_lshlrev_b32_e32 v46, 16, v47
	v_and_b32_e32 v47, 0xffff0000, v47
	v_pk_mul_f32 v[10:11], v[10:11], v[36:37]
	v_pk_mul_f32 v[8:9], v[8:9], v[60:61]
	v_pk_mul_f32 v[30:31], v[30:31], v[40:41]
	v_pk_mul_f32 v[28:29], v[28:29], v[64:65]
	v_pk_mul_f32 v[22:23], v[22:23], v[42:43]
	v_pk_mul_f32 v[20:21], v[20:21], v[66:67]
	v_pk_mul_f32 v[26:27], v[26:27], v[32:33]
	v_pk_mul_f32 v[24:25], v[24:25], v[56:57]
	v_pk_mul_f32 v[18:19], v[18:19], v[34:35]
	v_pk_mul_f32 v[16:17], v[16:17], v[58:59]
	v_pk_mul_f32 v[32:33], v[2:3], v[38:39]
	v_pk_mul_f32 v[34:35], v[0:1], v[62:63]
	v_pk_mul_f32 v[14:15], v[14:15], v[44:45]
	v_pk_mul_f32 v[12:13], v[12:13], v[68:69]
	v_pk_mul_f32 v[36:37], v[6:7], v[46:47]
	v_pk_mul_f32 v[38:39], v[4:5], v[70:71]
	v_cvt_pk_bf16_f32 v4, v8, v9
	v_cvt_pk_bf16_f32 v5, v10, v11
	v_cvt_pk_bf16_f32 v8, v28, v29
	v_cvt_pk_bf16_f32 v9, v30, v31
	v_cvt_pk_bf16_f32 v10, v20, v21
	v_cvt_pk_bf16_f32 v11, v22, v23
	v_cvt_pk_bf16_f32 v0, v24, v25
	v_cvt_pk_bf16_f32 v1, v26, v27
	v_cvt_pk_bf16_f32 v2, v16, v17
	v_cvt_pk_bf16_f32 v3, v18, v19
	v_cvt_pk_bf16_f32 v6, v34, v35
	v_cvt_pk_bf16_f32 v7, v32, v33
	v_cvt_pk_bf16_f32 v12, v12, v13
	v_cvt_pk_bf16_f32 v13, v14, v15
	v_cvt_pk_bf16_f32 v14, v38, v39
	v_cvt_pk_bf16_f32 v15, v36, v37
	global_store_dwordx4 v[52:53], v[8:11], off
	global_store_dwordx4 v[54:55], v[12:15], off offset:256
	global_store_dwordx4 v[48:49], v[0:3], off
	global_store_dwordx4 v[50:51], v[4:7], off offset:256
	s_cbranch_vccz .LBB0_544
	s_waitcnt vmcnt(0)
	v_readlane_b32 s78, v228, 33
	v_readlane_b32 s80, v228, 36
	s_cmpk_gt_u32 s0, 0xff
	v_readlane_b32 s76, v228, 32
	v_readlane_b32 s79, v228, 34
	v_readlane_b32 s77, v228, 35
	v_readlane_b32 s81, v228, 37
	s_cbranch_scc1 .LBB0_551
	s_barrier

.LBB0_569:
	ds_read_b128 v[144:147], v157
	ds_read_b128 v[148:151], v157 offset:1024
	ds_read_b128 v[160:163], v157 offset:2048
	ds_read_b128 v[164:167], v157 offset:3072
	s_add_u32 s60, s58, 0xfffc0080
	s_addc_u32 s61, s59, -1
	s_cmp_eq_u32 s83, 12
	s_cselect_b32 s63, s51, s61
	s_cselect_b32 s62, s79, s60
	s_cselect_b32 s61, s49, s82
	s_cselect_b32 s60, s80, s81
	v_lshl_add_u64 v[200:201], s[58:59], 0, v[136:137]
	s_add_i32 m0, s57, 0xc000
	ds_read_b128 v[168:171], v158
	ds_read_b128 v[172:175], v158 offset:1024
	ds_read_b128 v[176:179], v158 offset:2048
	ds_read_b128 v[180:183], v158 offset:3072
	ds_read_b128 v[184:187], v158 offset:4096
	ds_read_b128 v[188:191], v158 offset:5120
	ds_read_b128 v[192:195], v158 offset:6144
	ds_read_b128 v[196:199], v158 offset:7168
	global_load_lds_dwordx4 v[200:201], off
	s_add_i32 m0, s57, 0xe000
	v_lshl_add_u64 v[200:201], s[58:59], 0, v[138:139]
	global_load_lds_dwordx4 v[200:201], off
	s_waitcnt lgkmcnt(8)
	s_barrier
	s_waitcnt lgkmcnt(0)
	s_waitcnt lgkmcnt(0)
	v_mfma_f32_16x16x32_bf16 v[124:127], v[144:147], v[168:171], v[124:127]
	v_mfma_f32_16x16x32_bf16 v[120:123], v[160:163], v[168:171], v[120:123]
	v_mfma_f32_16x16x32_bf16 v[108:111], v[144:147], v[176:179], v[108:111]
	v_mfma_f32_16x16x32_bf16 v[104:107], v[160:163], v[176:179], v[104:107]
	v_mfma_f32_16x16x32_bf16 v[92:95], v[144:147], v[184:187], v[92:95]
	v_mfma_f32_16x16x32_bf16 v[88:91], v[160:163], v[184:187], v[88:91]
	v_mfma_f32_16x16x32_bf16 v[76:79], v[144:147], v[192:195], v[76:79]
	v_mfma_f32_16x16x32_bf16 v[72:75], v[160:163], v[192:195], v[72:75]
	v_mfma_f32_16x16x32_bf16 v[124:127], v[148:151], v[172:175], v[124:127]
	v_mfma_f32_16x16x32_bf16 v[120:123], v[164:167], v[172:175], v[120:123]
	v_mfma_f32_16x16x32_bf16 v[108:111], v[148:151], v[180:183], v[108:111]
	v_mfma_f32_16x16x32_bf16 v[104:107], v[164:167], v[180:183], v[104:107]
	v_mfma_f32_16x16x32_bf16 v[92:95], v[148:151], v[188:191], v[92:95]
	v_mfma_f32_16x16x32_bf16 v[88:91], v[164:167], v[188:191], v[88:91]
	v_mfma_f32_16x16x32_bf16 v[76:79], v[148:151], v[196:199], v[76:79]
	v_mfma_f32_16x16x32_bf16 v[72:75], v[164:167], v[196:199], v[72:75]
	s_barrier
	s_add_i32 s86, s73, s34
	v_lshl_add_u64 v[216:217], s[60:61], 0, v[132:133]
	s_mov_b32 m0, s86
	ds_read_b128 v[200:203], v159
	ds_read_b128 v[204:207], v159 offset:1024
	ds_read_b128 v[208:211], v159 offset:2048
	ds_read_b128 v[212:215], v159 offset:3072
	global_load_lds_dwordx4 v[216:217], off
	s_add_i32 m0, s86, 0x2000
	v_lshl_add_u64 v[218:219], s[60:61], 0, v[128:129]
	global_load_lds_dwordx4 v[218:219], off
	s_barrier
	s_waitcnt lgkmcnt(0)
	s_waitcnt lgkmcnt(0)
	v_mfma_f32_16x16x32_bf16 v[116:119], v[200:203], v[168:171], v[116:119]
	v_mfma_f32_16x16x32_bf16 v[112:115], v[208:211], v[168:171], v[112:115]
	v_mfma_f32_16x16x32_bf16 v[100:103], v[200:203], v[176:179], v[100:103]
	v_mfma_f32_16x16x32_bf16 v[96:99], v[208:211], v[176:179], v[96:99]
	v_mfma_f32_16x16x32_bf16 v[84:87], v[200:203], v[184:187], v[84:87]
	v_mfma_f32_16x16x32_bf16 v[80:83], v[208:211], v[184:187], v[80:83]
	v_mfma_f32_16x16x32_bf16 v[68:71], v[200:203], v[192:195], v[68:71]
	v_mfma_f32_16x16x32_bf16 v[64:67], v[208:211], v[192:195], v[64:67]
	v_mfma_f32_16x16x32_bf16 v[116:119], v[204:207], v[172:175], v[116:119]
	v_mfma_f32_16x16x32_bf16 v[112:115], v[212:215], v[172:175], v[112:115]
	v_mfma_f32_16x16x32_bf16 v[100:103], v[204:207], v[180:183], v[100:103]
	v_mfma_f32_16x16x32_bf16 v[96:99], v[212:215], v[180:183], v[96:99]
	v_mfma_f32_16x16x32_bf16 v[84:87], v[204:207], v[188:191], v[84:87]
	v_mfma_f32_16x16x32_bf16 v[80:83], v[212:215], v[188:191], v[80:83]
	v_mfma_f32_16x16x32_bf16 v[68:71], v[204:207], v[196:199], v[68:71]
	v_mfma_f32_16x16x32_bf16 v[64:67], v[212:215], v[196:199], v[64:67]
	s_mov_b32 m0, s57
	v_lshl_add_u64 v[220:221], s[62:63], 0, v[134:135]
	s_barrier
	ds_read_b128 v[168:171], v158 offset:16384
	ds_read_b128 v[172:175], v158 offset:17408
	ds_read_b128 v[176:179], v158 offset:18432
	ds_read_b128 v[180:183], v158 offset:19456
	ds_read_b128 v[184:187], v158 offset:20480
	ds_read_b128 v[188:191], v158 offset:21504
	ds_read_b128 v[192:195], v158 offset:22528
	ds_read_b128 v[196:199], v158 offset:23552
	global_load_lds_dwordx4 v[220:221], off
	s_mov_b32 m0, s65
	v_lshl_add_u64 v[222:223], s[62:63], 0, v[130:131]
	global_load_lds_dwordx4 v[222:223], off
	s_barrier
	s_waitcnt lgkmcnt(0)
	s_waitcnt lgkmcnt(0)
	v_mfma_f32_16x16x32_bf16 v[60:63], v[144:147], v[168:171], v[60:63]
	v_mfma_f32_16x16x32_bf16 v[56:59], v[160:163], v[168:171], v[56:59]
	v_mfma_f32_16x16x32_bf16 v[44:47], v[144:147], v[176:179], v[44:47]
	v_mfma_f32_16x16x32_bf16 v[40:43], v[160:163], v[176:179], v[40:43]
	v_mfma_f32_16x16x32_bf16 v[28:31], v[144:147], v[184:187], v[28:31]
	v_mfma_f32_16x16x32_bf16 v[24:27], v[160:163], v[184:187], v[24:27]
	v_mfma_f32_16x16x32_bf16 v[12:15], v[144:147], v[192:195], v[12:15]
	v_mfma_f32_16x16x32_bf16 v[8:11], v[160:163], v[192:195], v[8:11]
	v_mfma_f32_16x16x32_bf16 v[60:63], v[148:151], v[172:175], v[60:63]
	v_mfma_f32_16x16x32_bf16 v[56:59], v[164:167], v[172:175], v[56:59]
	v_mfma_f32_16x16x32_bf16 v[44:47], v[148:151], v[180:183], v[44:47]
	v_mfma_f32_16x16x32_bf16 v[40:43], v[164:167], v[180:183], v[40:43]
	v_mfma_f32_16x16x32_bf16 v[28:31], v[148:151], v[188:191], v[28:31]
	v_mfma_f32_16x16x32_bf16 v[24:27], v[164:167], v[188:191], v[24:27]
	v_mfma_f32_16x16x32_bf16 v[12:15], v[148:151], v[196:199], v[12:15]
	v_mfma_f32_16x16x32_bf16 v[8:11], v[164:167], v[196:199], v[8:11]
	s_barrier
	s_add_u32 s86, s60, 0x40000
	s_addc_u32 s87, s61, 0
	s_add_i32 s88, s72, s34
	s_mov_b32 m0, s88
	v_lshl_add_u64 v[144:145], s[86:87], 0, v[132:133]
	global_load_lds_dwordx4 v[144:145], off
	s_add_i32 m0, s88, 0x2000
	v_lshl_add_u64 v[144:145], s[86:87], 0, v[128:129]
	global_load_lds_dwordx4 v[144:145], off
	s_waitcnt vmcnt(6)
	s_barrier
	v_mfma_f32_16x16x32_bf16 v[52:55], v[200:203], v[168:171], v[52:55]
	v_mfma_f32_16x16x32_bf16 v[48:51], v[208:211], v[168:171], v[48:51]
	v_mfma_f32_16x16x32_bf16 v[36:39], v[200:203], v[176:179], v[36:39]
	v_mfma_f32_16x16x32_bf16 v[32:35], v[208:211], v[176:179], v[32:35]
	v_mfma_f32_16x16x32_bf16 v[20:23], v[200:203], v[184:187], v[20:23]
	v_mfma_f32_16x16x32_bf16 v[16:19], v[208:211], v[184:187], v[16:19]
	v_mfma_f32_16x16x32_bf16 v[4:7], v[200:203], v[192:195], v[4:7]
	v_mfma_f32_16x16x32_bf16 v[0:3], v[208:211], v[192:195], v[0:3]
	v_mfma_f32_16x16x32_bf16 v[52:55], v[204:207], v[172:175], v[52:55]
	v_mfma_f32_16x16x32_bf16 v[48:51], v[212:215], v[172:175], v[48:51]
	v_mfma_f32_16x16x32_bf16 v[36:39], v[204:207], v[180:183], v[36:39]
	v_mfma_f32_16x16x32_bf16 v[32:35], v[212:215], v[180:183], v[32:35]
	v_mfma_f32_16x16x32_bf16 v[20:23], v[204:207], v[188:191], v[20:23]
	v_mfma_f32_16x16x32_bf16 v[16:19], v[212:215], v[188:191], v[16:19]
	v_mfma_f32_16x16x32_bf16 v[4:7], v[204:207], v[196:199], v[4:7]
	v_mfma_f32_16x16x32_bf16 v[0:3], v[212:215], v[196:199], v[0:3]
	s_add_i32 s86, 0, 0x18000
	v_add_u32_e32 v164, s86, v153
	s_barrier
	ds_read_b128 v[144:147], v164
	ds_read_b128 v[148:151], v164 offset:1024
	ds_read_b128 v[160:163], v164 offset:2048
	ds_read_b128 v[164:167], v164 offset:3072
	s_add_u32 s62, s62, 0x40000
	s_addc_u32 s63, s63, 0
	s_mov_b32 m0, s66
	v_lshl_add_u64 v[200:201], s[62:63], 0, v[134:135]
	ds_read_b128 v[168:171], v158 offset:32768
	ds_read_b128 v[172:175], v158 offset:33792
	ds_read_b128 v[176:179], v158 offset:34816
	ds_read_b128 v[180:183], v158 offset:35840
	ds_read_b128 v[184:187], v158 offset:36864
	ds_read_b128 v[188:191], v158 offset:37888
	ds_read_b128 v[192:195], v158 offset:38912
	ds_read_b128 v[196:199], v158 offset:39936
	global_load_lds_dwordx4 v[200:201], off
	s_mov_b32 m0, s67
	v_lshl_add_u64 v[200:201], s[62:63], 0, v[130:131]
	global_load_lds_dwordx4 v[200:201], off
	s_waitcnt lgkmcnt(8)
	s_barrier
	s_waitcnt lgkmcnt(0)
	s_waitcnt lgkmcnt(0)
	v_mfma_f32_16x16x32_bf16 v[124:127], v[144:147], v[168:171], v[124:127]
	v_mfma_f32_16x16x32_bf16 v[120:123], v[160:163], v[168:171], v[120:123]
	v_mfma_f32_16x16x32_bf16 v[108:111], v[144:147], v[176:179], v[108:111]
	v_mfma_f32_16x16x32_bf16 v[104:107], v[160:163], v[176:179], v[104:107]
	v_mfma_f32_16x16x32_bf16 v[92:95], v[144:147], v[184:187], v[92:95]
	v_mfma_f32_16x16x32_bf16 v[88:91], v[160:163], v[184:187], v[88:91]
	v_mfma_f32_16x16x32_bf16 v[76:79], v[144:147], v[192:195], v[76:79]
	v_mfma_f32_16x16x32_bf16 v[72:75], v[160:163], v[192:195], v[72:75]
	v_mfma_f32_16x16x32_bf16 v[124:127], v[148:151], v[172:175], v[124:127]
	v_mfma_f32_16x16x32_bf16 v[120:123], v[164:167], v[172:175], v[120:123]
	v_mfma_f32_16x16x32_bf16 v[108:111], v[148:151], v[180:183], v[108:111]
	v_mfma_f32_16x16x32_bf16 v[104:107], v[164:167], v[180:183], v[104:107]
	v_mfma_f32_16x16x32_bf16 v[92:95], v[148:151], v[188:191], v[92:95]
	v_mfma_f32_16x16x32_bf16 v[88:91], v[164:167], v[188:191], v[88:91]
	v_mfma_f32_16x16x32_bf16 v[76:79], v[148:151], v[196:199], v[76:79]
	v_mfma_f32_16x16x32_bf16 v[72:75], v[164:167], v[196:199], v[72:75]
	s_barrier
	s_add_i32 s62, s86, s34
	v_add_u32_e32 v212, s97, v153
	v_lshl_add_u64 v[216:217], v[216:217], 0, s[8:9]
	s_mov_b32 m0, s62
	ds_read_b128 v[200:203], v212
	ds_read_b128 v[204:207], v212 offset:1024
	ds_read_b128 v[208:211], v212 offset:2048
	ds_read_b128 v[212:215], v212 offset:3072
	global_load_lds_dwordx4 v[216:217], off
	s_add_i32 m0, s62, 0x2000
	v_lshl_add_u64 v[216:217], v[218:219], 0, s[8:9]
	global_load_lds_dwordx4 v[216:217], off
	s_barrier
	s_waitcnt lgkmcnt(0)
	s_waitcnt lgkmcnt(0)
	v_mfma_f32_16x16x32_bf16 v[116:119], v[200:203], v[168:171], v[116:119]
	v_mfma_f32_16x16x32_bf16 v[112:115], v[208:211], v[168:171], v[112:115]
	v_mfma_f32_16x16x32_bf16 v[100:103], v[200:203], v[176:179], v[100:103]
	v_mfma_f32_16x16x32_bf16 v[96:99], v[208:211], v[176:179], v[96:99]
	v_mfma_f32_16x16x32_bf16 v[84:87], v[200:203], v[184:187], v[84:87]
	v_mfma_f32_16x16x32_bf16 v[80:83], v[208:211], v[184:187], v[80:83]
	v_mfma_f32_16x16x32_bf16 v[68:71], v[200:203], v[192:195], v[68:71]
	v_mfma_f32_16x16x32_bf16 v[64:67], v[208:211], v[192:195], v[64:67]
	v_mfma_f32_16x16x32_bf16 v[116:119], v[204:207], v[172:175], v[116:119]
	v_mfma_f32_16x16x32_bf16 v[112:115], v[212:215], v[172:175], v[112:115]
	v_mfma_f32_16x16x32_bf16 v[100:103], v[204:207], v[180:183], v[100:103]
	v_mfma_f32_16x16x32_bf16 v[96:99], v[212:215], v[180:183], v[96:99]
	v_mfma_f32_16x16x32_bf16 v[84:87], v[204:207], v[188:191], v[84:87]
	v_mfma_f32_16x16x32_bf16 v[80:83], v[212:215], v[188:191], v[80:83]
	v_mfma_f32_16x16x32_bf16 v[68:71], v[204:207], v[196:199], v[68:71]
	v_mfma_f32_16x16x32_bf16 v[64:67], v[212:215], v[196:199], v[64:67]
	s_mov_b32 m0, s69
	v_lshl_add_u64 v[216:217], v[220:221], 0, s[8:9]
	s_barrier
	ds_read_b128 v[168:171], v158 offset:49152
	ds_read_b128 v[172:175], v158 offset:50176
	ds_read_b128 v[176:179], v158 offset:51200
	ds_read_b128 v[180:183], v158 offset:52224
	ds_read_b128 v[184:187], v158 offset:53248
	ds_read_b128 v[188:191], v158 offset:54272
	ds_read_b128 v[192:195], v158 offset:55296
	ds_read_b128 v[196:199], v158 offset:56320
	global_load_lds_dwordx4 v[216:217], off
	s_mov_b32 m0, s70
	v_lshl_add_u64 v[216:217], v[222:223], 0, s[8:9]
	global_load_lds_dwordx4 v[216:217], off
	s_barrier
	s_waitcnt lgkmcnt(0)
	s_waitcnt lgkmcnt(0)
	v_mfma_f32_16x16x32_bf16 v[60:63], v[144:147], v[168:171], v[60:63]
	v_mfma_f32_16x16x32_bf16 v[56:59], v[160:163], v[168:171], v[56:59]
	v_mfma_f32_16x16x32_bf16 v[44:47], v[144:147], v[176:179], v[44:47]
	v_mfma_f32_16x16x32_bf16 v[40:43], v[160:163], v[176:179], v[40:43]
	v_mfma_f32_16x16x32_bf16 v[28:31], v[144:147], v[184:187], v[28:31]
	v_mfma_f32_16x16x32_bf16 v[24:27], v[160:163], v[184:187], v[24:27]
	v_mfma_f32_16x16x32_bf16 v[12:15], v[144:147], v[192:195], v[12:15]
	v_mfma_f32_16x16x32_bf16 v[8:11], v[160:163], v[192:195], v[8:11]
	v_mfma_f32_16x16x32_bf16 v[60:63], v[148:151], v[172:175], v[60:63]
	v_mfma_f32_16x16x32_bf16 v[56:59], v[164:167], v[172:175], v[56:59]
	v_mfma_f32_16x16x32_bf16 v[44:47], v[148:151], v[180:183], v[44:47]
	v_mfma_f32_16x16x32_bf16 v[40:43], v[164:167], v[180:183], v[40:43]
	v_mfma_f32_16x16x32_bf16 v[28:31], v[148:151], v[188:191], v[28:31]
	v_mfma_f32_16x16x32_bf16 v[24:27], v[164:167], v[188:191], v[24:27]
	v_mfma_f32_16x16x32_bf16 v[12:15], v[148:151], v[196:199], v[12:15]
	v_mfma_f32_16x16x32_bf16 v[8:11], v[164:167], v[196:199], v[8:11]
	s_barrier
	s_add_u32 s60, s60, 0x40080
	s_addc_u32 s61, s61, 0
	s_add_i32 s62, s97, s34
	s_mov_b32 m0, s62
	v_lshl_add_u64 v[144:145], s[60:61], 0, v[132:133]
	global_load_lds_dwordx4 v[144:145], off
	s_add_i32 m0, s62, 0x2000
	v_lshl_add_u64 v[144:145], s[60:61], 0, v[128:129]
	global_load_lds_dwordx4 v[144:145], off
	s_waitcnt vmcnt(6)
	s_barrier
	v_mfma_f32_16x16x32_bf16 v[52:55], v[200:203], v[168:171], v[52:55]
	v_mfma_f32_16x16x32_bf16 v[48:51], v[208:211], v[168:171], v[48:51]
	v_mfma_f32_16x16x32_bf16 v[36:39], v[200:203], v[176:179], v[36:39]
	v_mfma_f32_16x16x32_bf16 v[32:35], v[208:211], v[176:179], v[32:35]
	v_mfma_f32_16x16x32_bf16 v[20:23], v[200:203], v[184:187], v[20:23]
	v_mfma_f32_16x16x32_bf16 v[16:19], v[208:211], v[184:187], v[16:19]
	v_mfma_f32_16x16x32_bf16 v[4:7], v[200:203], v[192:195], v[4:7]
	v_mfma_f32_16x16x32_bf16 v[0:3], v[208:211], v[192:195], v[0:3]
	v_mfma_f32_16x16x32_bf16 v[52:55], v[204:207], v[172:175], v[52:55]
	v_mfma_f32_16x16x32_bf16 v[48:51], v[212:215], v[172:175], v[48:51]
	v_mfma_f32_16x16x32_bf16 v[36:39], v[204:207], v[180:183], v[36:39]
	v_mfma_f32_16x16x32_bf16 v[32:35], v[212:215], v[180:183], v[32:35]
	v_mfma_f32_16x16x32_bf16 v[20:23], v[204:207], v[188:191], v[20:23]
	v_mfma_f32_16x16x32_bf16 v[16:19], v[212:215], v[188:191], v[16:19]
	v_mfma_f32_16x16x32_bf16 v[4:7], v[204:207], v[196:199], v[4:7]
	v_mfma_f32_16x16x32_bf16 v[0:3], v[212:215], v[196:199], v[0:3]
	s_add_i32 s83, s83, 2
	s_add_u32 s58, s58, 0x100
	s_addc_u32 s59, s59, 0
	s_add_u32 s81, s81, 0x100
	s_addc_u32 s82, s82, 0
	s_cmp_gt_u32 s83, 13
	s_barrier
	s_cbranch_scc0 .LBB0_569
	v_lshl_or_b32 v146, s78, 8, v156
	v_ashrrev_i32_e32 v147, 31, v146
	v_lshl_add_u64 v[144:145], v[146:147], 2, s[44:45]
	global_load_dwordx4 v[160:163], v[144:145], off
	global_load_dwordx4 v[164:167], v[144:145], off offset:16
	v_lshl_add_u32 v148, s56, 8, v152
	v_ashrrev_i32_e32 v149, 31, v148
	v_lshlrev_b64 v[168:169], 12, v[148:149]
	v_lshlrev_b64 v[150:151], 1, v[146:147]
	v_lshl_add_u64 v[146:147], s[6:7], 0, v[168:169]
	v_lshl_add_u64 v[146:147], v[146:147], 0, v[150:151]
	s_mov_b32 s78, s48
	s_mov_b32 s56, s50
	s_mov_b64 s[60:61], s[54:55]
	s_mov_b64 s[58:59], s[52:53]
	s_waitcnt vmcnt(0)
	v_add_f32_e32 v124, v124, v160
	v_add_f32_e32 v120, v120, v164
	v_add_f32_e32 v125, v125, v161
	v_add_f32_e32 v121, v121, v165
	v_add_f32_e32 v126, v126, v162
	v_add_f32_e32 v122, v122, v166
	v_add_f32_e32 v127, v127, v163
	v_add_f32_e32 v123, v123, v167
	v_mul_f32_e32 v124, 0xbfb8aa3b, v124
	v_mul_f32_e32 v120, 0xbfb8aa3b, v120
	v_mul_f32_e32 v125, 0xbfb8aa3b, v125
	v_mul_f32_e32 v121, 0xbfb8aa3b, v121
	v_mul_f32_e32 v126, 0xbfb8aa3b, v126
	v_mul_f32_e32 v122, 0xbfb8aa3b, v122
	v_mul_f32_e32 v127, 0xbfb8aa3b, v127
	v_mul_f32_e32 v123, 0xbfb8aa3b, v123
	v_exp_f32_e32 v124, v124
	v_exp_f32_e32 v120, v120
	v_exp_f32_e32 v125, v125
	v_exp_f32_e32 v121, v121
	v_exp_f32_e32 v126, v126
	v_exp_f32_e32 v122, v122
	v_exp_f32_e32 v127, v127
	v_exp_f32_e32 v123, v123
	v_add_f32_e32 v124, 1.0, v124
	v_add_f32_e32 v120, 1.0, v120
	v_add_f32_e32 v125, 1.0, v125
	v_add_f32_e32 v121, 1.0, v121
	v_add_f32_e32 v126, 1.0, v126
	v_add_f32_e32 v122, 1.0, v122
	v_add_f32_e32 v127, 1.0, v127
	v_add_f32_e32 v123, 1.0, v123
	v_rcp_f32_e32 v124, v124
	v_rcp_f32_e32 v149, v120
	v_rcp_f32_e32 v120, v125
	v_rcp_f32_e32 v125, v121
	v_rcp_f32_e32 v121, v126
	v_rcp_f32_e32 v126, v127
	v_rcp_f32_e32 v127, v122
	v_rcp_f32_e32 v123, v123
	v_cvt_pk_bf16_f32 v120, v124, v120
	v_cvt_pk_bf16_f32 v121, v121, v126
	v_cvt_pk_bf16_f32 v122, v149, v125
	v_cvt_pk_bf16_f32 v123, v127, v123
	global_store_dwordx4 v[146:147], v[120:123], off
	global_load_dwordx4 v[120:123], v[144:145], off offset:512
	s_nop 0
	global_load_dwordx4 v[124:127], v[144:145], off offset:528
	s_waitcnt vmcnt(0)
	v_add_f32_e32 v116, v116, v120
	v_add_f32_e32 v112, v112, v124
	v_add_f32_e32 v117, v117, v121
	v_add_f32_e32 v113, v113, v125
	v_add_f32_e32 v118, v118, v122
	v_add_f32_e32 v114, v114, v126
	v_add_f32_e32 v119, v119, v123
	v_add_f32_e32 v115, v115, v127
	v_mul_f32_e32 v116, 0xbfb8aa3b, v116
	v_mul_f32_e32 v112, 0xbfb8aa3b, v112
	v_mul_f32_e32 v117, 0xbfb8aa3b, v117
	v_mul_f32_e32 v113, 0xbfb8aa3b, v113
	v_mul_f32_e32 v118, 0xbfb8aa3b, v118
	v_mul_f32_e32 v114, 0xbfb8aa3b, v114
	v_mul_f32_e32 v119, 0xbfb8aa3b, v119
	v_mul_f32_e32 v115, 0xbfb8aa3b, v115
	v_exp_f32_e32 v116, v116
	v_exp_f32_e32 v112, v112
	v_exp_f32_e32 v117, v117
	v_exp_f32_e32 v113, v113
	v_exp_f32_e32 v118, v118
	v_exp_f32_e32 v114, v114
	v_exp_f32_e32 v119, v119
	v_exp_f32_e32 v115, v115
	v_add_f32_e32 v116, 1.0, v116
	v_add_f32_e32 v112, 1.0, v112
	v_add_f32_e32 v117, 1.0, v117
	v_add_f32_e32 v113, 1.0, v113
	v_add_f32_e32 v118, 1.0, v118
	v_add_f32_e32 v114, 1.0, v114
	v_add_f32_e32 v119, 1.0, v119
	v_add_f32_e32 v115, 1.0, v115
	v_rcp_f32_e32 v116, v116
	v_rcp_f32_e32 v120, v112
	v_rcp_f32_e32 v112, v117
	v_rcp_f32_e32 v117, v113
	v_rcp_f32_e32 v113, v118
	v_rcp_f32_e32 v118, v119
	v_rcp_f32_e32 v119, v114
	v_rcp_f32_e32 v115, v115
	v_cvt_pk_bf16_f32 v112, v116, v112
	v_cvt_pk_bf16_f32 v113, v113, v118
	v_cvt_pk_bf16_f32 v114, v120, v117
	v_cvt_pk_bf16_f32 v115, v119, v115
	global_store_dwordx4 v[146:147], v[112:115], off offset:256
	global_load_dwordx4 v[112:115], v[144:145], off
	s_nop 0
	global_load_dwordx4 v[116:119], v[144:145], off offset:16
	v_or_b32_e32 v120, 16, v148
	v_ashrrev_i32_e32 v121, 31, v120
	v_lshlrev_b64 v[120:121], 12, v[120:121]
	v_lshl_add_u64 v[120:121], s[6:7], 0, v[120:121]
	v_lshl_add_u64 v[120:121], v[120:121], 0, v[150:151]
	s_waitcnt vmcnt(0)
	v_add_f32_e32 v108, v108, v112
	v_add_f32_e32 v104, v104, v116
	v_add_f32_e32 v109, v109, v113
	v_add_f32_e32 v105, v105, v117
	v_add_f32_e32 v110, v110, v114
	v_add_f32_e32 v106, v106, v118
	v_add_f32_e32 v111, v111, v115
	v_add_f32_e32 v107, v107, v119
	v_mul_f32_e32 v108, 0xbfb8aa3b, v108
	v_mul_f32_e32 v104, 0xbfb8aa3b, v104
	v_mul_f32_e32 v109, 0xbfb8aa3b, v109
	v_mul_f32_e32 v105, 0xbfb8aa3b, v105
	v_mul_f32_e32 v110, 0xbfb8aa3b, v110
	v_mul_f32_e32 v106, 0xbfb8aa3b, v106
	v_mul_f32_e32 v111, 0xbfb8aa3b, v111
	v_mul_f32_e32 v107, 0xbfb8aa3b, v107
	v_exp_f32_e32 v108, v108
	v_exp_f32_e32 v104, v104
	v_exp_f32_e32 v109, v109
	v_exp_f32_e32 v105, v105
	v_exp_f32_e32 v110, v110
	v_exp_f32_e32 v106, v106
	v_exp_f32_e32 v111, v111
	v_exp_f32_e32 v107, v107
	v_add_f32_e32 v108, 1.0, v108
	v_add_f32_e32 v104, 1.0, v104
	v_add_f32_e32 v109, 1.0, v109
	v_add_f32_e32 v105, 1.0, v105
	v_add_f32_e32 v110, 1.0, v110
	v_add_f32_e32 v106, 1.0, v106
	v_add_f32_e32 v111, 1.0, v111
	v_add_f32_e32 v107, 1.0, v107
	v_rcp_f32_e32 v108, v108
	v_rcp_f32_e32 v112, v104
	v_rcp_f32_e32 v104, v109
	v_rcp_f32_e32 v109, v105
	v_rcp_f32_e32 v105, v110
	v_rcp_f32_e32 v110, v111
	v_rcp_f32_e32 v111, v106
	v_rcp_f32_e32 v107, v107
	v_cvt_pk_bf16_f32 v104, v108, v104
	v_cvt_pk_bf16_f32 v105, v105, v110
	v_cvt_pk_bf16_f32 v106, v112, v109
	v_cvt_pk_bf16_f32 v107, v111, v107
	global_store_dwordx4 v[120:121], v[104:107], off
	global_load_dwordx4 v[104:107], v[144:145], off offset:512
	s_nop 0
	global_load_dwordx4 v[108:111], v[144:145], off offset:528
	s_waitcnt vmcnt(0)
	v_add_f32_e32 v100, v100, v104
	v_add_f32_e32 v96, v96, v108
	v_add_f32_e32 v101, v101, v105
	v_add_f32_e32 v97, v97, v109
	v_add_f32_e32 v102, v102, v106
	v_add_f32_e32 v98, v98, v110
	v_add_f32_e32 v103, v103, v107
	v_add_f32_e32 v99, v99, v111
	v_mul_f32_e32 v100, 0xbfb8aa3b, v100
	v_mul_f32_e32 v96, 0xbfb8aa3b, v96
	v_mul_f32_e32 v101, 0xbfb8aa3b, v101
	v_mul_f32_e32 v97, 0xbfb8aa3b, v97
	v_mul_f32_e32 v102, 0xbfb8aa3b, v102
	v_mul_f32_e32 v98, 0xbfb8aa3b, v98
	v_mul_f32_e32 v103, 0xbfb8aa3b, v103
	v_mul_f32_e32 v99, 0xbfb8aa3b, v99
	v_exp_f32_e32 v100, v100
	v_exp_f32_e32 v96, v96
	v_exp_f32_e32 v101, v101
	v_exp_f32_e32 v97, v97
	v_exp_f32_e32 v102, v102
	v_exp_f32_e32 v98, v98
	v_exp_f32_e32 v103, v103
	v_exp_f32_e32 v99, v99
	v_add_f32_e32 v100, 1.0, v100
	v_add_f32_e32 v96, 1.0, v96
	v_add_f32_e32 v101, 1.0, v101
	v_add_f32_e32 v97, 1.0, v97
	v_add_f32_e32 v102, 1.0, v102
	v_add_f32_e32 v98, 1.0, v98
	v_add_f32_e32 v103, 1.0, v103
	v_add_f32_e32 v99, 1.0, v99
	v_rcp_f32_e32 v100, v100
	v_rcp_f32_e32 v104, v96
	v_rcp_f32_e32 v96, v101
	v_rcp_f32_e32 v101, v97
	v_rcp_f32_e32 v97, v102
	v_rcp_f32_e32 v102, v103
	v_rcp_f32_e32 v103, v98
	v_rcp_f32_e32 v99, v99
	v_cvt_pk_bf16_f32 v96, v100, v96
	v_cvt_pk_bf16_f32 v97, v97, v102
	v_cvt_pk_bf16_f32 v98, v104, v101
	v_cvt_pk_bf16_f32 v99, v103, v99
	global_store_dwordx4 v[120:121], v[96:99], off offset:256
	global_load_dwordx4 v[96:99], v[144:145], off
	s_nop 0
	global_load_dwordx4 v[100:103], v[144:145], off offset:16
	v_or_b32_e32 v104, 32, v148
	v_ashrrev_i32_e32 v105, 31, v104
	v_lshlrev_b64 v[104:105], 12, v[104:105]
	v_lshl_add_u64 v[104:105], s[6:7], 0, v[104:105]
	v_lshl_add_u64 v[104:105], v[104:105], 0, v[150:151]
	s_waitcnt vmcnt(0)
	v_add_f32_e32 v92, v92, v96
	v_add_f32_e32 v88, v88, v100
	v_add_f32_e32 v93, v93, v97
	v_add_f32_e32 v89, v89, v101
	v_add_f32_e32 v94, v94, v98
	v_add_f32_e32 v90, v90, v102
	v_add_f32_e32 v95, v95, v99
	v_add_f32_e32 v91, v91, v103
	v_mul_f32_e32 v92, 0xbfb8aa3b, v92
	v_mul_f32_e32 v88, 0xbfb8aa3b, v88
	v_mul_f32_e32 v93, 0xbfb8aa3b, v93
	v_mul_f32_e32 v89, 0xbfb8aa3b, v89
	v_mul_f32_e32 v94, 0xbfb8aa3b, v94
	v_mul_f32_e32 v90, 0xbfb8aa3b, v90
	v_mul_f32_e32 v95, 0xbfb8aa3b, v95
	v_mul_f32_e32 v91, 0xbfb8aa3b, v91
	v_exp_f32_e32 v92, v92
	v_exp_f32_e32 v88, v88
	v_exp_f32_e32 v93, v93
	v_exp_f32_e32 v89, v89
	v_exp_f32_e32 v94, v94
	v_exp_f32_e32 v90, v90
	v_exp_f32_e32 v95, v95
	v_exp_f32_e32 v91, v91
	v_add_f32_e32 v92, 1.0, v92
	v_add_f32_e32 v88, 1.0, v88
	v_add_f32_e32 v93, 1.0, v93
	v_add_f32_e32 v89, 1.0, v89
	v_add_f32_e32 v94, 1.0, v94
	v_add_f32_e32 v90, 1.0, v90
	v_add_f32_e32 v95, 1.0, v95
	v_add_f32_e32 v91, 1.0, v91
	v_rcp_f32_e32 v92, v92
	v_rcp_f32_e32 v96, v88
	v_rcp_f32_e32 v88, v93
	v_rcp_f32_e32 v93, v89
	v_rcp_f32_e32 v89, v94
	v_rcp_f32_e32 v94, v95
	v_rcp_f32_e32 v95, v90
	v_rcp_f32_e32 v91, v91
	v_cvt_pk_bf16_f32 v88, v92, v88
	v_cvt_pk_bf16_f32 v89, v89, v94
	v_cvt_pk_bf16_f32 v90, v96, v93
	v_cvt_pk_bf16_f32 v91, v95, v91
	global_store_dwordx4 v[104:105], v[88:91], off
	global_load_dwordx4 v[88:91], v[144:145], off offset:512
	s_nop 0
	global_load_dwordx4 v[92:95], v[144:145], off offset:528
	s_waitcnt vmcnt(0)
	v_add_f32_e32 v84, v84, v88
	v_add_f32_e32 v80, v80, v92
	v_add_f32_e32 v85, v85, v89
	v_add_f32_e32 v81, v81, v93
	v_add_f32_e32 v86, v86, v90
	v_add_f32_e32 v82, v82, v94
	v_add_f32_e32 v87, v87, v91
	v_add_f32_e32 v83, v83, v95
	v_mul_f32_e32 v84, 0xbfb8aa3b, v84
	v_mul_f32_e32 v80, 0xbfb8aa3b, v80
	v_mul_f32_e32 v85, 0xbfb8aa3b, v85
	v_mul_f32_e32 v81, 0xbfb8aa3b, v81
	v_mul_f32_e32 v86, 0xbfb8aa3b, v86
	v_mul_f32_e32 v82, 0xbfb8aa3b, v82
	v_mul_f32_e32 v87, 0xbfb8aa3b, v87
	v_mul_f32_e32 v83, 0xbfb8aa3b, v83
	v_exp_f32_e32 v84, v84
	v_exp_f32_e32 v80, v80
	v_exp_f32_e32 v85, v85
	v_exp_f32_e32 v81, v81
	v_exp_f32_e32 v86, v86
	v_exp_f32_e32 v82, v82
	v_exp_f32_e32 v87, v87
	v_exp_f32_e32 v83, v83
	v_add_f32_e32 v84, 1.0, v84
	v_add_f32_e32 v80, 1.0, v80
	v_add_f32_e32 v85, 1.0, v85
	v_add_f32_e32 v81, 1.0, v81
	v_add_f32_e32 v86, 1.0, v86
	v_add_f32_e32 v82, 1.0, v82
	v_add_f32_e32 v87, 1.0, v87
	v_add_f32_e32 v83, 1.0, v83
	v_rcp_f32_e32 v84, v84
	v_rcp_f32_e32 v88, v80
	v_rcp_f32_e32 v80, v85
	v_rcp_f32_e32 v85, v81
	v_rcp_f32_e32 v81, v86
	v_rcp_f32_e32 v86, v87
	v_rcp_f32_e32 v87, v82
	v_rcp_f32_e32 v83, v83
	v_cvt_pk_bf16_f32 v80, v84, v80
	v_cvt_pk_bf16_f32 v81, v81, v86
	v_cvt_pk_bf16_f32 v82, v88, v85
	v_cvt_pk_bf16_f32 v83, v87, v83
	global_store_dwordx4 v[104:105], v[80:83], off offset:256
	global_load_dwordx4 v[80:83], v[144:145], off
	s_nop 0
	global_load_dwordx4 v[84:87], v[144:145], off offset:16
	v_or_b32_e32 v88, 48, v148
	v_ashrrev_i32_e32 v89, 31, v88
	v_lshlrev_b64 v[88:89], 12, v[88:89]
	v_lshl_add_u64 v[88:89], s[6:7], 0, v[88:89]
	v_lshl_add_u64 v[88:89], v[88:89], 0, v[150:151]
	s_waitcnt vmcnt(0)
	v_add_f32_e32 v76, v76, v80
	v_add_f32_e32 v72, v72, v84
	v_add_f32_e32 v77, v77, v81
	v_add_f32_e32 v73, v73, v85
	v_add_f32_e32 v78, v78, v82
	v_add_f32_e32 v74, v74, v86
	v_add_f32_e32 v79, v79, v83
	v_add_f32_e32 v75, v75, v87
	v_mul_f32_e32 v76, 0xbfb8aa3b, v76
	v_mul_f32_e32 v72, 0xbfb8aa3b, v72
	v_mul_f32_e32 v77, 0xbfb8aa3b, v77
	v_mul_f32_e32 v73, 0xbfb8aa3b, v73
	v_mul_f32_e32 v78, 0xbfb8aa3b, v78
	v_mul_f32_e32 v74, 0xbfb8aa3b, v74
	v_mul_f32_e32 v79, 0xbfb8aa3b, v79
	v_mul_f32_e32 v75, 0xbfb8aa3b, v75
	v_exp_f32_e32 v76, v76
	v_exp_f32_e32 v72, v72
	v_exp_f32_e32 v77, v77
	v_exp_f32_e32 v73, v73
	v_exp_f32_e32 v78, v78
	v_exp_f32_e32 v74, v74
	v_exp_f32_e32 v79, v79
	v_exp_f32_e32 v75, v75
	v_add_f32_e32 v76, 1.0, v76
	v_add_f32_e32 v72, 1.0, v72
	v_add_f32_e32 v77, 1.0, v77
	v_add_f32_e32 v73, 1.0, v73
	v_add_f32_e32 v78, 1.0, v78
	v_add_f32_e32 v74, 1.0, v74
	v_add_f32_e32 v79, 1.0, v79
	v_add_f32_e32 v75, 1.0, v75
	v_rcp_f32_e32 v76, v76
	v_rcp_f32_e32 v80, v72
	v_rcp_f32_e32 v72, v77
	v_rcp_f32_e32 v77, v73
	v_rcp_f32_e32 v73, v78
	v_rcp_f32_e32 v78, v79
	v_rcp_f32_e32 v79, v74
	v_rcp_f32_e32 v75, v75
	v_cvt_pk_bf16_f32 v72, v76, v72
	v_cvt_pk_bf16_f32 v73, v73, v78
	v_cvt_pk_bf16_f32 v74, v80, v77
	v_cvt_pk_bf16_f32 v75, v79, v75
	global_store_dwordx4 v[88:89], v[72:75], off
	global_load_dwordx4 v[72:75], v[144:145], off offset:512
	s_nop 0
	global_load_dwordx4 v[76:79], v[144:145], off offset:528
	s_waitcnt vmcnt(0)
	v_add_f32_e32 v68, v68, v72
	v_add_f32_e32 v64, v64, v76
	v_add_f32_e32 v69, v69, v73
	v_add_f32_e32 v65, v65, v77
	v_add_f32_e32 v70, v70, v74
	v_add_f32_e32 v66, v66, v78
	v_add_f32_e32 v71, v71, v75
	v_add_f32_e32 v67, v67, v79
	v_mul_f32_e32 v68, 0xbfb8aa3b, v68
	v_mul_f32_e32 v64, 0xbfb8aa3b, v64
	v_mul_f32_e32 v69, 0xbfb8aa3b, v69
	v_mul_f32_e32 v65, 0xbfb8aa3b, v65
	v_mul_f32_e32 v70, 0xbfb8aa3b, v70
	v_mul_f32_e32 v66, 0xbfb8aa3b, v66
	v_mul_f32_e32 v71, 0xbfb8aa3b, v71
	v_mul_f32_e32 v67, 0xbfb8aa3b, v67
	v_exp_f32_e32 v68, v68
	v_exp_f32_e32 v64, v64
	v_exp_f32_e32 v69, v69
	v_exp_f32_e32 v65, v65
	v_exp_f32_e32 v70, v70
	v_exp_f32_e32 v66, v66
	v_exp_f32_e32 v71, v71
	v_exp_f32_e32 v67, v67
	v_add_f32_e32 v68, 1.0, v68
	v_add_f32_e32 v64, 1.0, v64
	v_add_f32_e32 v69, 1.0, v69
	v_add_f32_e32 v65, 1.0, v65
	v_add_f32_e32 v70, 1.0, v70
	v_add_f32_e32 v66, 1.0, v66
	v_add_f32_e32 v71, 1.0, v71
	v_add_f32_e32 v67, 1.0, v67
	v_rcp_f32_e32 v68, v68
	v_rcp_f32_e32 v72, v64
	v_rcp_f32_e32 v64, v69
	v_rcp_f32_e32 v69, v65
	v_rcp_f32_e32 v65, v70
	v_rcp_f32_e32 v70, v71
	v_rcp_f32_e32 v71, v66
	v_rcp_f32_e32 v67, v67
	v_cvt_pk_bf16_f32 v64, v68, v64
	v_cvt_pk_bf16_f32 v65, v65, v70
	v_cvt_pk_bf16_f32 v66, v72, v69
	v_cvt_pk_bf16_f32 v67, v71, v67
	global_store_dwordx4 v[88:89], v[64:67], off offset:256
	global_load_dwordx4 v[64:67], v[144:145], off
	s_nop 0
	global_load_dwordx4 v[68:71], v[144:145], off offset:16
	v_add_co_u32_e32 v72, vcc, s74, v146
	s_waitcnt vmcnt(0)
	v_add_f32_e32 v60, v60, v64
	v_add_f32_e32 v56, v56, v68
	v_add_f32_e32 v61, v61, v65
	v_add_f32_e32 v57, v57, v69
	v_add_f32_e32 v62, v62, v66
	v_add_f32_e32 v58, v58, v70
	v_add_f32_e32 v63, v63, v67
	v_add_f32_e32 v59, v59, v71
	v_mul_f32_e32 v60, 0xbfb8aa3b, v60
	v_mul_f32_e32 v56, 0xbfb8aa3b, v56
	v_mul_f32_e32 v61, 0xbfb8aa3b, v61
	v_mul_f32_e32 v57, 0xbfb8aa3b, v57
	v_mul_f32_e32 v62, 0xbfb8aa3b, v62
	v_mul_f32_e32 v58, 0xbfb8aa3b, v58
	v_mul_f32_e32 v63, 0xbfb8aa3b, v63
	v_mul_f32_e32 v59, 0xbfb8aa3b, v59
	v_exp_f32_e32 v60, v60
	v_exp_f32_e32 v56, v56
	v_exp_f32_e32 v61, v61
	v_exp_f32_e32 v57, v57
	v_exp_f32_e32 v62, v62
	v_exp_f32_e32 v58, v58
	v_exp_f32_e32 v63, v63
	v_exp_f32_e32 v59, v59
	v_add_f32_e32 v60, 1.0, v60
	v_add_f32_e32 v56, 1.0, v56
	v_add_f32_e32 v61, 1.0, v61
	v_add_f32_e32 v57, 1.0, v57
	v_add_f32_e32 v62, 1.0, v62
	v_add_f32_e32 v58, 1.0, v58
	v_add_f32_e32 v63, 1.0, v63
	v_add_f32_e32 v59, 1.0, v59
	v_rcp_f32_e32 v60, v60
	v_rcp_f32_e32 v64, v56
	v_rcp_f32_e32 v56, v61
	v_rcp_f32_e32 v61, v57
	v_rcp_f32_e32 v57, v62
	v_rcp_f32_e32 v62, v63
	v_rcp_f32_e32 v63, v58
	v_rcp_f32_e32 v59, v59
	v_addc_co_u32_e32 v73, vcc, 0, v147, vcc
	v_cvt_pk_bf16_f32 v56, v60, v56
	v_cvt_pk_bf16_f32 v57, v57, v62
	v_cvt_pk_bf16_f32 v58, v64, v61
	v_cvt_pk_bf16_f32 v59, v63, v59
	global_store_dwordx4 v[72:73], v[56:59], off
	global_load_dwordx4 v[56:59], v[144:145], off offset:512
	s_nop 0
	global_load_dwordx4 v[60:63], v[144:145], off offset:528
	v_lshl_add_u64 v[64:65], v[146:147], 0, s[14:15]
	s_waitcnt vmcnt(0)
	v_add_f32_e32 v52, v52, v56
	v_add_f32_e32 v48, v48, v60
	v_add_f32_e32 v53, v53, v57
	v_add_f32_e32 v49, v49, v61
	v_add_f32_e32 v54, v54, v58
	v_add_f32_e32 v50, v50, v62
	v_add_f32_e32 v55, v55, v59
	v_add_f32_e32 v51, v51, v63
	v_mul_f32_e32 v52, 0xbfb8aa3b, v52
	v_mul_f32_e32 v48, 0xbfb8aa3b, v48
	v_mul_f32_e32 v53, 0xbfb8aa3b, v53
	v_mul_f32_e32 v49, 0xbfb8aa3b, v49
	v_mul_f32_e32 v54, 0xbfb8aa3b, v54
	v_mul_f32_e32 v50, 0xbfb8aa3b, v50
	v_mul_f32_e32 v55, 0xbfb8aa3b, v55
	v_mul_f32_e32 v51, 0xbfb8aa3b, v51
	v_exp_f32_e32 v52, v52
	v_exp_f32_e32 v48, v48
	v_exp_f32_e32 v53, v53
	v_exp_f32_e32 v49, v49
	v_exp_f32_e32 v54, v54
	v_exp_f32_e32 v50, v50
	v_exp_f32_e32 v55, v55
	v_exp_f32_e32 v51, v51
	v_add_f32_e32 v52, 1.0, v52
	v_add_f32_e32 v48, 1.0, v48
	v_add_f32_e32 v53, 1.0, v53
	v_add_f32_e32 v49, 1.0, v49
	v_add_f32_e32 v54, 1.0, v54
	v_add_f32_e32 v50, 1.0, v50
	v_add_f32_e32 v55, 1.0, v55
	v_add_f32_e32 v51, 1.0, v51
	v_rcp_f32_e32 v52, v52
	v_rcp_f32_e32 v56, v48
	v_rcp_f32_e32 v48, v53
	v_rcp_f32_e32 v53, v49
	v_rcp_f32_e32 v49, v54
	v_rcp_f32_e32 v54, v55
	v_rcp_f32_e32 v55, v50
	v_rcp_f32_e32 v51, v51
	v_cvt_pk_bf16_f32 v48, v52, v48
	v_cvt_pk_bf16_f32 v49, v49, v54
	v_cvt_pk_bf16_f32 v50, v56, v53
	v_cvt_pk_bf16_f32 v51, v55, v51
	global_store_dwordx4 v[64:65], v[48:51], off offset:256
	global_load_dwordx4 v[48:51], v[144:145], off
	s_nop 0
	global_load_dwordx4 v[52:55], v[144:145], off offset:16
	v_add_co_u32_e32 v56, vcc, s75, v146
	s_waitcnt vmcnt(0)
	v_add_f32_e32 v44, v44, v48
	v_add_f32_e32 v40, v40, v52
	v_add_f32_e32 v45, v45, v49
	v_add_f32_e32 v41, v41, v53
	v_add_f32_e32 v46, v46, v50
	v_add_f32_e32 v42, v42, v54
	v_add_f32_e32 v47, v47, v51
	v_add_f32_e32 v43, v43, v55
	v_mul_f32_e32 v44, 0xbfb8aa3b, v44
	v_mul_f32_e32 v40, 0xbfb8aa3b, v40
	v_mul_f32_e32 v45, 0xbfb8aa3b, v45
	v_mul_f32_e32 v41, 0xbfb8aa3b, v41
	v_mul_f32_e32 v46, 0xbfb8aa3b, v46
	v_mul_f32_e32 v42, 0xbfb8aa3b, v42
	v_mul_f32_e32 v47, 0xbfb8aa3b, v47
	v_mul_f32_e32 v43, 0xbfb8aa3b, v43
	v_exp_f32_e32 v44, v44
	v_exp_f32_e32 v40, v40
	v_exp_f32_e32 v45, v45
	v_exp_f32_e32 v41, v41
	v_exp_f32_e32 v46, v46
	v_exp_f32_e32 v42, v42
	v_exp_f32_e32 v47, v47
	v_exp_f32_e32 v43, v43
	v_add_f32_e32 v44, 1.0, v44
	v_add_f32_e32 v40, 1.0, v40
	v_add_f32_e32 v45, 1.0, v45
	v_add_f32_e32 v41, 1.0, v41
	v_add_f32_e32 v46, 1.0, v46
	v_add_f32_e32 v42, 1.0, v42
	v_add_f32_e32 v47, 1.0, v47
	v_add_f32_e32 v43, 1.0, v43
	v_rcp_f32_e32 v44, v44
	v_rcp_f32_e32 v48, v40
	v_rcp_f32_e32 v40, v45
	v_rcp_f32_e32 v45, v41
	v_rcp_f32_e32 v41, v46
	v_rcp_f32_e32 v46, v47
	v_rcp_f32_e32 v47, v42
	v_rcp_f32_e32 v43, v43
	v_addc_co_u32_e32 v57, vcc, 0, v147, vcc
	v_cvt_pk_bf16_f32 v40, v44, v40
	v_cvt_pk_bf16_f32 v41, v41, v46
	v_cvt_pk_bf16_f32 v42, v48, v45
	v_cvt_pk_bf16_f32 v43, v47, v43
	global_store_dwordx4 v[56:57], v[40:43], off
	global_load_dwordx4 v[40:43], v[144:145], off offset:512
	s_nop 0
	global_load_dwordx4 v[44:47], v[144:145], off offset:528
	v_lshl_add_u64 v[48:49], v[146:147], 0, s[24:25]
	s_waitcnt vmcnt(0)
	v_add_f32_e32 v36, v36, v40
	v_add_f32_e32 v32, v32, v44
	v_add_f32_e32 v37, v37, v41
	v_add_f32_e32 v33, v33, v45
	v_add_f32_e32 v38, v38, v42
	v_add_f32_e32 v34, v34, v46
	v_add_f32_e32 v39, v39, v43
	v_add_f32_e32 v35, v35, v47
	v_mul_f32_e32 v36, 0xbfb8aa3b, v36
	v_mul_f32_e32 v32, 0xbfb8aa3b, v32
	v_mul_f32_e32 v37, 0xbfb8aa3b, v37
	v_mul_f32_e32 v33, 0xbfb8aa3b, v33
	v_mul_f32_e32 v38, 0xbfb8aa3b, v38
	v_mul_f32_e32 v34, 0xbfb8aa3b, v34
	v_mul_f32_e32 v39, 0xbfb8aa3b, v39
	v_mul_f32_e32 v35, 0xbfb8aa3b, v35
	v_exp_f32_e32 v36, v36
	v_exp_f32_e32 v32, v32
	v_exp_f32_e32 v37, v37
	v_exp_f32_e32 v33, v33
	v_exp_f32_e32 v38, v38
	v_exp_f32_e32 v34, v34
	v_exp_f32_e32 v39, v39
	v_exp_f32_e32 v35, v35
	v_add_f32_e32 v36, 1.0, v36
	v_add_f32_e32 v32, 1.0, v32
	v_add_f32_e32 v37, 1.0, v37
	v_add_f32_e32 v33, 1.0, v33
	v_add_f32_e32 v38, 1.0, v38
	v_add_f32_e32 v34, 1.0, v34
	v_add_f32_e32 v39, 1.0, v39
	v_add_f32_e32 v35, 1.0, v35
	v_rcp_f32_e32 v36, v36
	v_rcp_f32_e32 v40, v32
	v_rcp_f32_e32 v32, v37
	v_rcp_f32_e32 v37, v33
	v_rcp_f32_e32 v33, v38
	v_rcp_f32_e32 v38, v39
	v_rcp_f32_e32 v39, v34
	v_rcp_f32_e32 v35, v35
	v_cvt_pk_bf16_f32 v32, v36, v32
	v_cvt_pk_bf16_f32 v33, v33, v38
	v_cvt_pk_bf16_f32 v34, v40, v37
	v_cvt_pk_bf16_f32 v35, v39, v35
	global_store_dwordx4 v[48:49], v[32:35], off offset:256
	global_load_dwordx4 v[32:35], v[144:145], off
	s_nop 0
	global_load_dwordx4 v[36:39], v[144:145], off offset:16
	v_add_co_u32_e32 v40, vcc, s76, v146
	s_waitcnt vmcnt(0)
	v_add_f32_e32 v28, v28, v32
	v_add_f32_e32 v24, v24, v36
	v_add_f32_e32 v29, v29, v33
	v_add_f32_e32 v25, v25, v37
	v_add_f32_e32 v30, v30, v34
	v_add_f32_e32 v26, v26, v38
	v_add_f32_e32 v31, v31, v35
	v_add_f32_e32 v27, v27, v39
	v_mul_f32_e32 v28, 0xbfb8aa3b, v28
	v_mul_f32_e32 v24, 0xbfb8aa3b, v24
	v_mul_f32_e32 v29, 0xbfb8aa3b, v29
	v_mul_f32_e32 v25, 0xbfb8aa3b, v25
	v_mul_f32_e32 v30, 0xbfb8aa3b, v30
	v_mul_f32_e32 v26, 0xbfb8aa3b, v26
	v_mul_f32_e32 v31, 0xbfb8aa3b, v31
	v_mul_f32_e32 v27, 0xbfb8aa3b, v27
	v_exp_f32_e32 v28, v28
	v_exp_f32_e32 v24, v24
	v_exp_f32_e32 v29, v29
	v_exp_f32_e32 v25, v25
	v_exp_f32_e32 v30, v30
	v_exp_f32_e32 v26, v26
	v_exp_f32_e32 v31, v31
	v_exp_f32_e32 v27, v27
	v_add_f32_e32 v28, 1.0, v28
	v_add_f32_e32 v24, 1.0, v24
	v_add_f32_e32 v29, 1.0, v29
	v_add_f32_e32 v25, 1.0, v25
	v_add_f32_e32 v30, 1.0, v30
	v_add_f32_e32 v26, 1.0, v26
	v_add_f32_e32 v31, 1.0, v31
	v_add_f32_e32 v27, 1.0, v27
	v_rcp_f32_e32 v28, v28
	v_rcp_f32_e32 v32, v24
	v_rcp_f32_e32 v24, v29
	v_rcp_f32_e32 v29, v25
	v_rcp_f32_e32 v25, v30
	v_rcp_f32_e32 v30, v31
	v_rcp_f32_e32 v31, v26
	v_rcp_f32_e32 v27, v27
	v_addc_co_u32_e32 v41, vcc, 0, v147, vcc
	v_cvt_pk_bf16_f32 v24, v28, v24
	v_cvt_pk_bf16_f32 v25, v25, v30
	v_cvt_pk_bf16_f32 v26, v32, v29
	v_cvt_pk_bf16_f32 v27, v31, v27
	global_store_dwordx4 v[40:41], v[24:27], off
	global_load_dwordx4 v[24:27], v[144:145], off offset:512
	s_nop 0
	global_load_dwordx4 v[28:31], v[144:145], off offset:528
	v_lshl_add_u64 v[32:33], v[146:147], 0, s[40:41]
	s_waitcnt vmcnt(0)
	v_add_f32_e32 v20, v20, v24
	v_add_f32_e32 v16, v16, v28
	v_add_f32_e32 v21, v21, v25
	v_add_f32_e32 v17, v17, v29
	v_add_f32_e32 v22, v22, v26
	v_add_f32_e32 v18, v18, v30
	v_add_f32_e32 v23, v23, v27
	v_add_f32_e32 v19, v19, v31
	v_mul_f32_e32 v20, 0xbfb8aa3b, v20
	v_mul_f32_e32 v16, 0xbfb8aa3b, v16
	v_mul_f32_e32 v21, 0xbfb8aa3b, v21
	v_mul_f32_e32 v17, 0xbfb8aa3b, v17
	v_mul_f32_e32 v22, 0xbfb8aa3b, v22
	v_mul_f32_e32 v18, 0xbfb8aa3b, v18
	v_mul_f32_e32 v23, 0xbfb8aa3b, v23
	v_mul_f32_e32 v19, 0xbfb8aa3b, v19
	v_exp_f32_e32 v20, v20
	v_exp_f32_e32 v16, v16
	v_exp_f32_e32 v21, v21
	v_exp_f32_e32 v17, v17
	v_exp_f32_e32 v22, v22
	v_exp_f32_e32 v18, v18
	v_exp_f32_e32 v23, v23
	v_exp_f32_e32 v19, v19
	v_add_f32_e32 v20, 1.0, v20
	v_add_f32_e32 v16, 1.0, v16
	v_add_f32_e32 v21, 1.0, v21
	v_add_f32_e32 v17, 1.0, v17
	v_add_f32_e32 v22, 1.0, v22
	v_add_f32_e32 v18, 1.0, v18
	v_add_f32_e32 v23, 1.0, v23
	v_add_f32_e32 v19, 1.0, v19
	v_rcp_f32_e32 v20, v20
	v_rcp_f32_e32 v24, v16
	v_rcp_f32_e32 v16, v21
	v_rcp_f32_e32 v21, v17
	v_rcp_f32_e32 v17, v22
	v_rcp_f32_e32 v22, v23
	v_rcp_f32_e32 v23, v18
	v_rcp_f32_e32 v19, v19
	v_cvt_pk_bf16_f32 v16, v20, v16
	v_cvt_pk_bf16_f32 v17, v17, v22
	v_cvt_pk_bf16_f32 v18, v24, v21
	v_cvt_pk_bf16_f32 v19, v23, v19
	global_store_dwordx4 v[32:33], v[16:19], off offset:256
	global_load_dwordx4 v[16:19], v[144:145], off
	s_nop 0
	global_load_dwordx4 v[20:23], v[144:145], off offset:16
	v_add_co_u32_e32 v24, vcc, s77, v146
	s_waitcnt vmcnt(0)
	v_add_f32_e32 v12, v12, v16
	v_add_f32_e32 v8, v8, v20
	v_add_f32_e32 v13, v13, v17
	v_add_f32_e32 v9, v9, v21
	v_add_f32_e32 v14, v14, v18
	v_add_f32_e32 v10, v10, v22
	v_add_f32_e32 v15, v15, v19
	v_add_f32_e32 v11, v11, v23
	v_mul_f32_e32 v12, 0xbfb8aa3b, v12
	v_mul_f32_e32 v8, 0xbfb8aa3b, v8
	v_mul_f32_e32 v13, 0xbfb8aa3b, v13
	v_mul_f32_e32 v9, 0xbfb8aa3b, v9
	v_mul_f32_e32 v14, 0xbfb8aa3b, v14
	v_mul_f32_e32 v10, 0xbfb8aa3b, v10
	v_mul_f32_e32 v15, 0xbfb8aa3b, v15
	v_mul_f32_e32 v11, 0xbfb8aa3b, v11
	v_exp_f32_e32 v12, v12
	v_exp_f32_e32 v8, v8
	v_exp_f32_e32 v13, v13
	v_exp_f32_e32 v9, v9
	v_exp_f32_e32 v14, v14
	v_exp_f32_e32 v10, v10
	v_exp_f32_e32 v15, v15
	v_exp_f32_e32 v11, v11
	v_add_f32_e32 v12, 1.0, v12
	v_add_f32_e32 v8, 1.0, v8
	v_add_f32_e32 v13, 1.0, v13
	v_add_f32_e32 v9, 1.0, v9
	v_add_f32_e32 v14, 1.0, v14
	v_add_f32_e32 v10, 1.0, v10
	v_add_f32_e32 v15, 1.0, v15
	v_add_f32_e32 v11, 1.0, v11
	v_rcp_f32_e32 v12, v12
	v_rcp_f32_e32 v16, v8
	v_rcp_f32_e32 v8, v13
	v_rcp_f32_e32 v13, v9
	v_rcp_f32_e32 v9, v14
	v_rcp_f32_e32 v14, v15
	v_rcp_f32_e32 v15, v10
	v_rcp_f32_e32 v11, v11
	v_addc_co_u32_e32 v25, vcc, 0, v147, vcc
	v_cvt_pk_bf16_f32 v8, v12, v8
	v_cvt_pk_bf16_f32 v9, v9, v14
	v_cvt_pk_bf16_f32 v10, v16, v13
	v_cvt_pk_bf16_f32 v11, v15, v11
	global_store_dwordx4 v[24:25], v[8:11], off
	global_load_dwordx4 v[8:11], v[144:145], off offset:512
	s_nop 0
	global_load_dwordx4 v[12:15], v[144:145], off offset:528
	s_and_b64 vcc, exec, s[4:5]
	v_lshl_add_u64 v[16:17], v[146:147], 0, s[46:47]
	s_waitcnt vmcnt(0)
	v_add_f32_e32 v4, v4, v8
	v_add_f32_e32 v0, v0, v12
	v_add_f32_e32 v5, v5, v9
	v_add_f32_e32 v1, v1, v13
	v_add_f32_e32 v6, v6, v10
	v_add_f32_e32 v2, v2, v14
	v_add_f32_e32 v7, v7, v11
	v_add_f32_e32 v3, v3, v15
	v_mul_f32_e32 v4, 0xbfb8aa3b, v4
	v_mul_f32_e32 v0, 0xbfb8aa3b, v0
	v_mul_f32_e32 v5, 0xbfb8aa3b, v5
	v_mul_f32_e32 v1, 0xbfb8aa3b, v1
	v_mul_f32_e32 v6, 0xbfb8aa3b, v6
	v_mul_f32_e32 v2, 0xbfb8aa3b, v2
	v_mul_f32_e32 v7, 0xbfb8aa3b, v7
	v_mul_f32_e32 v3, 0xbfb8aa3b, v3
	v_exp_f32_e32 v4, v4
	v_exp_f32_e32 v0, v0
	v_exp_f32_e32 v5, v5
	v_exp_f32_e32 v1, v1
	v_exp_f32_e32 v6, v6
	v_exp_f32_e32 v2, v2
	v_exp_f32_e32 v7, v7
	v_exp_f32_e32 v3, v3
	v_add_f32_e32 v4, 1.0, v4
	v_add_f32_e32 v0, 1.0, v0
	v_add_f32_e32 v5, 1.0, v5
	v_add_f32_e32 v1, 1.0, v1
	v_add_f32_e32 v6, 1.0, v6
	v_add_f32_e32 v2, 1.0, v2
	v_add_f32_e32 v7, 1.0, v7
	v_add_f32_e32 v3, 1.0, v3
	v_rcp_f32_e32 v4, v4
	v_rcp_f32_e32 v8, v0
	v_rcp_f32_e32 v0, v5
	v_rcp_f32_e32 v5, v1
	v_rcp_f32_e32 v1, v6
	v_rcp_f32_e32 v6, v7
	v_rcp_f32_e32 v7, v2
	v_rcp_f32_e32 v3, v3
	v_cvt_pk_bf16_f32 v0, v4, v0
	v_cvt_pk_bf16_f32 v1, v1, v6
	v_cvt_pk_bf16_f32 v2, v8, v5
	v_cvt_pk_bf16_f32 v3, v7, v3
	global_store_dwordx4 v[16:17], v[0:3], off offset:256
	s_cbranch_vccz .LBB0_566
	s_waitcnt vmcnt(0)
	v_readlane_b32 s78, v228, 33
	s_cmpk_gt_u32 s0, 0xff
	v_readlane_b32 s76, v228, 32
	v_readlane_b32 s79, v228, 34
	v_readlane_b32 s77, v228, 35
	s_cbranch_scc1 .LBB0_573
	s_barrier

.LBB0_591:
	ds_read_b128 v[144:147], v151
	ds_read_b128 v[156:159], v151 offset:1024
	ds_read_b128 v[160:163], v151 offset:2048
	ds_read_b128 v[164:167], v151 offset:3072
	s_add_u32 s52, s50, 0xfffe0080
	s_addc_u32 s53, s51, -1
	s_cmp_eq_u32 s68, 4
	s_cselect_b32 s55, s41, s53
	s_cselect_b32 s54, s64, s52
	s_cselect_b32 s53, s25, s67
	s_cselect_b32 s52, s65, s66
	v_lshl_add_u64 v[200:201], s[50:51], 0, v[136:137]
	s_add_i32 m0, s35, 0xc000
	ds_read_b128 v[168:171], v152
	ds_read_b128 v[172:175], v152 offset:1024
	ds_read_b128 v[176:179], v152 offset:2048
	ds_read_b128 v[180:183], v152 offset:3072
	ds_read_b128 v[184:187], v152 offset:4096
	ds_read_b128 v[188:191], v152 offset:5120
	ds_read_b128 v[192:195], v152 offset:6144
	ds_read_b128 v[196:199], v152 offset:7168
	global_load_lds_dwordx4 v[200:201], off
	s_add_i32 m0, s35, 0xe000
	v_lshl_add_u64 v[200:201], s[50:51], 0, v[138:139]
	global_load_lds_dwordx4 v[200:201], off
	s_waitcnt lgkmcnt(8)
	s_barrier
	s_waitcnt lgkmcnt(0)
	s_waitcnt lgkmcnt(0)
	v_mfma_f32_16x16x32_bf16 v[124:127], v[144:147], v[168:171], v[124:127]
	v_mfma_f32_16x16x32_bf16 v[120:123], v[160:163], v[168:171], v[120:123]
	v_mfma_f32_16x16x32_bf16 v[108:111], v[144:147], v[176:179], v[108:111]
	v_mfma_f32_16x16x32_bf16 v[104:107], v[160:163], v[176:179], v[104:107]
	v_mfma_f32_16x16x32_bf16 v[92:95], v[144:147], v[184:187], v[92:95]
	v_mfma_f32_16x16x32_bf16 v[88:91], v[160:163], v[184:187], v[88:91]
	v_mfma_f32_16x16x32_bf16 v[76:79], v[144:147], v[192:195], v[76:79]
	v_mfma_f32_16x16x32_bf16 v[72:75], v[160:163], v[192:195], v[72:75]
	v_mfma_f32_16x16x32_bf16 v[124:127], v[156:159], v[172:175], v[124:127]
	v_mfma_f32_16x16x32_bf16 v[120:123], v[164:167], v[172:175], v[120:123]
	v_mfma_f32_16x16x32_bf16 v[108:111], v[156:159], v[180:183], v[108:111]
	v_mfma_f32_16x16x32_bf16 v[104:107], v[164:167], v[180:183], v[104:107]
	v_mfma_f32_16x16x32_bf16 v[92:95], v[156:159], v[188:191], v[92:95]
	v_mfma_f32_16x16x32_bf16 v[88:91], v[164:167], v[188:191], v[88:91]
	v_mfma_f32_16x16x32_bf16 v[76:79], v[156:159], v[196:199], v[76:79]
	v_mfma_f32_16x16x32_bf16 v[72:75], v[164:167], v[196:199], v[72:75]
	s_barrier
	s_add_i32 s69, s62, s1
	v_lshl_add_u64 v[216:217], s[52:53], 0, v[132:133]
	s_mov_b32 m0, s69
	ds_read_b128 v[200:203], v153
	ds_read_b128 v[204:207], v153 offset:1024
	ds_read_b128 v[208:211], v153 offset:2048
	ds_read_b128 v[212:215], v153 offset:3072
	global_load_lds_dwordx4 v[216:217], off
	s_add_i32 m0, s69, 0x2000
	v_lshl_add_u64 v[218:219], s[52:53], 0, v[128:129]
	global_load_lds_dwordx4 v[218:219], off
	s_barrier
	s_waitcnt lgkmcnt(0)
	s_waitcnt lgkmcnt(0)
	v_mfma_f32_16x16x32_bf16 v[116:119], v[200:203], v[168:171], v[116:119]
	v_mfma_f32_16x16x32_bf16 v[112:115], v[208:211], v[168:171], v[112:115]
	v_mfma_f32_16x16x32_bf16 v[100:103], v[200:203], v[176:179], v[100:103]
	v_mfma_f32_16x16x32_bf16 v[96:99], v[208:211], v[176:179], v[96:99]
	v_mfma_f32_16x16x32_bf16 v[84:87], v[200:203], v[184:187], v[84:87]
	v_mfma_f32_16x16x32_bf16 v[80:83], v[208:211], v[184:187], v[80:83]
	v_mfma_f32_16x16x32_bf16 v[68:71], v[200:203], v[192:195], v[68:71]
	v_mfma_f32_16x16x32_bf16 v[64:67], v[208:211], v[192:195], v[64:67]
	v_mfma_f32_16x16x32_bf16 v[116:119], v[204:207], v[172:175], v[116:119]
	v_mfma_f32_16x16x32_bf16 v[112:115], v[212:215], v[172:175], v[112:115]
	v_mfma_f32_16x16x32_bf16 v[100:103], v[204:207], v[180:183], v[100:103]
	v_mfma_f32_16x16x32_bf16 v[96:99], v[212:215], v[180:183], v[96:99]
	v_mfma_f32_16x16x32_bf16 v[84:87], v[204:207], v[188:191], v[84:87]
	v_mfma_f32_16x16x32_bf16 v[80:83], v[212:215], v[188:191], v[80:83]
	v_mfma_f32_16x16x32_bf16 v[68:71], v[204:207], v[196:199], v[68:71]
	v_mfma_f32_16x16x32_bf16 v[64:67], v[212:215], v[196:199], v[64:67]
	s_mov_b32 m0, s35
	v_lshl_add_u64 v[220:221], s[54:55], 0, v[134:135]
	s_barrier
	ds_read_b128 v[168:171], v152 offset:16384
	ds_read_b128 v[172:175], v152 offset:17408
	ds_read_b128 v[176:179], v152 offset:18432
	ds_read_b128 v[180:183], v152 offset:19456
	ds_read_b128 v[184:187], v152 offset:20480
	ds_read_b128 v[188:191], v152 offset:21504
	ds_read_b128 v[192:195], v152 offset:22528
	ds_read_b128 v[196:199], v152 offset:23552
	global_load_lds_dwordx4 v[220:221], off
	s_mov_b32 m0, s49
	v_lshl_add_u64 v[222:223], s[54:55], 0, v[130:131]
	global_load_lds_dwordx4 v[222:223], off
	s_barrier
	s_waitcnt lgkmcnt(0)
	s_waitcnt lgkmcnt(0)
	v_mfma_f32_16x16x32_bf16 v[60:63], v[144:147], v[168:171], v[60:63]
	v_mfma_f32_16x16x32_bf16 v[56:59], v[160:163], v[168:171], v[56:59]
	v_mfma_f32_16x16x32_bf16 v[44:47], v[144:147], v[176:179], v[44:47]
	v_mfma_f32_16x16x32_bf16 v[40:43], v[160:163], v[176:179], v[40:43]
	v_mfma_f32_16x16x32_bf16 v[28:31], v[144:147], v[184:187], v[28:31]
	v_mfma_f32_16x16x32_bf16 v[24:27], v[160:163], v[184:187], v[24:27]
	v_mfma_f32_16x16x32_bf16 v[12:15], v[144:147], v[192:195], v[12:15]
	v_mfma_f32_16x16x32_bf16 v[8:11], v[160:163], v[192:195], v[8:11]
	v_mfma_f32_16x16x32_bf16 v[60:63], v[156:159], v[172:175], v[60:63]
	v_mfma_f32_16x16x32_bf16 v[56:59], v[164:167], v[172:175], v[56:59]
	v_mfma_f32_16x16x32_bf16 v[44:47], v[156:159], v[180:183], v[44:47]
	v_mfma_f32_16x16x32_bf16 v[40:43], v[164:167], v[180:183], v[40:43]
	v_mfma_f32_16x16x32_bf16 v[28:31], v[156:159], v[188:191], v[28:31]
	v_mfma_f32_16x16x32_bf16 v[24:27], v[164:167], v[188:191], v[24:27]
	v_mfma_f32_16x16x32_bf16 v[12:15], v[156:159], v[196:199], v[12:15]
	v_mfma_f32_16x16x32_bf16 v[8:11], v[164:167], v[196:199], v[8:11]
	s_barrier
	s_add_u32 s70, s52, 0x20000
	s_addc_u32 s71, s53, 0
	s_add_i32 s69, s72, s1
	s_mov_b32 m0, s69
	v_lshl_add_u64 v[144:145], s[70:71], 0, v[132:133]
	global_load_lds_dwordx4 v[144:145], off
	s_add_i32 m0, s69, 0x2000
	v_lshl_add_u64 v[144:145], s[70:71], 0, v[128:129]
	global_load_lds_dwordx4 v[144:145], off
	s_waitcnt vmcnt(6)
	s_barrier
	v_mfma_f32_16x16x32_bf16 v[52:55], v[200:203], v[168:171], v[52:55]
	v_mfma_f32_16x16x32_bf16 v[48:51], v[208:211], v[168:171], v[48:51]
	v_mfma_f32_16x16x32_bf16 v[36:39], v[200:203], v[176:179], v[36:39]
	v_mfma_f32_16x16x32_bf16 v[32:35], v[208:211], v[176:179], v[32:35]
	v_mfma_f32_16x16x32_bf16 v[20:23], v[200:203], v[184:187], v[20:23]
	v_mfma_f32_16x16x32_bf16 v[16:19], v[208:211], v[184:187], v[16:19]
	v_mfma_f32_16x16x32_bf16 v[4:7], v[200:203], v[192:195], v[4:7]
	v_mfma_f32_16x16x32_bf16 v[0:3], v[208:211], v[192:195], v[0:3]
	v_mfma_f32_16x16x32_bf16 v[52:55], v[204:207], v[172:175], v[52:55]
	v_mfma_f32_16x16x32_bf16 v[48:51], v[212:215], v[172:175], v[48:51]
	v_mfma_f32_16x16x32_bf16 v[36:39], v[204:207], v[180:183], v[36:39]
	v_mfma_f32_16x16x32_bf16 v[32:35], v[212:215], v[180:183], v[32:35]
	v_mfma_f32_16x16x32_bf16 v[20:23], v[204:207], v[188:191], v[20:23]
	v_mfma_f32_16x16x32_bf16 v[16:19], v[212:215], v[188:191], v[16:19]
	v_mfma_f32_16x16x32_bf16 v[4:7], v[204:207], v[196:199], v[4:7]
	v_mfma_f32_16x16x32_bf16 v[0:3], v[212:215], v[196:199], v[0:3]
	s_add_i32 s69, 0, 0x18000
	v_add_u32_e32 v164, s69, v149
	s_barrier
	ds_read_b128 v[144:147], v164
	ds_read_b128 v[156:159], v164 offset:1024
	ds_read_b128 v[160:163], v164 offset:2048
	ds_read_b128 v[164:167], v164 offset:3072
	s_add_u32 s54, s54, 0x20000
	s_addc_u32 s55, s55, 0
	s_mov_b32 m0, s56
	v_lshl_add_u64 v[200:201], s[54:55], 0, v[134:135]
	ds_read_b128 v[168:171], v152 offset:32768
	ds_read_b128 v[172:175], v152 offset:33792
	ds_read_b128 v[176:179], v152 offset:34816
	ds_read_b128 v[180:183], v152 offset:35840
	ds_read_b128 v[184:187], v152 offset:36864
	ds_read_b128 v[188:191], v152 offset:37888
	ds_read_b128 v[192:195], v152 offset:38912
	ds_read_b128 v[196:199], v152 offset:39936
	global_load_lds_dwordx4 v[200:201], off
	s_mov_b32 m0, s57
	v_lshl_add_u64 v[200:201], s[54:55], 0, v[130:131]
	global_load_lds_dwordx4 v[200:201], off
	s_waitcnt lgkmcnt(8)
	s_barrier
	s_waitcnt lgkmcnt(0)
	s_waitcnt lgkmcnt(0)
	v_mfma_f32_16x16x32_bf16 v[124:127], v[144:147], v[168:171], v[124:127]
	v_mfma_f32_16x16x32_bf16 v[120:123], v[160:163], v[168:171], v[120:123]
	v_mfma_f32_16x16x32_bf16 v[108:111], v[144:147], v[176:179], v[108:111]
	v_mfma_f32_16x16x32_bf16 v[104:107], v[160:163], v[176:179], v[104:107]
	v_mfma_f32_16x16x32_bf16 v[92:95], v[144:147], v[184:187], v[92:95]
	v_mfma_f32_16x16x32_bf16 v[88:91], v[160:163], v[184:187], v[88:91]
	v_mfma_f32_16x16x32_bf16 v[76:79], v[144:147], v[192:195], v[76:79]
	v_mfma_f32_16x16x32_bf16 v[72:75], v[160:163], v[192:195], v[72:75]
	v_mfma_f32_16x16x32_bf16 v[124:127], v[156:159], v[172:175], v[124:127]
	v_mfma_f32_16x16x32_bf16 v[120:123], v[164:167], v[172:175], v[120:123]
	v_mfma_f32_16x16x32_bf16 v[108:111], v[156:159], v[180:183], v[108:111]
	v_mfma_f32_16x16x32_bf16 v[104:107], v[164:167], v[180:183], v[104:107]
	v_mfma_f32_16x16x32_bf16 v[92:95], v[156:159], v[188:191], v[92:95]
	v_mfma_f32_16x16x32_bf16 v[88:91], v[164:167], v[188:191], v[88:91]
	v_mfma_f32_16x16x32_bf16 v[76:79], v[156:159], v[196:199], v[76:79]
	v_mfma_f32_16x16x32_bf16 v[72:75], v[164:167], v[196:199], v[72:75]
	s_barrier
	s_add_i32 s54, s69, s1
	v_add_u32_e32 v212, s97, v149
	v_lshl_add_u64 v[216:217], v[216:217], 0, s[20:21]
	s_mov_b32 m0, s54
	ds_read_b128 v[200:203], v212
	ds_read_b128 v[204:207], v212 offset:1024
	ds_read_b128 v[208:211], v212 offset:2048
	ds_read_b128 v[212:215], v212 offset:3072
	global_load_lds_dwordx4 v[216:217], off
	s_add_i32 m0, s54, 0x2000
	v_lshl_add_u64 v[216:217], v[218:219], 0, s[20:21]
	global_load_lds_dwordx4 v[216:217], off
	s_barrier
	s_waitcnt lgkmcnt(0)
	s_waitcnt lgkmcnt(0)
	v_mfma_f32_16x16x32_bf16 v[116:119], v[200:203], v[168:171], v[116:119]
	v_mfma_f32_16x16x32_bf16 v[112:115], v[208:211], v[168:171], v[112:115]
	v_mfma_f32_16x16x32_bf16 v[100:103], v[200:203], v[176:179], v[100:103]
	v_mfma_f32_16x16x32_bf16 v[96:99], v[208:211], v[176:179], v[96:99]
	v_mfma_f32_16x16x32_bf16 v[84:87], v[200:203], v[184:187], v[84:87]
	v_mfma_f32_16x16x32_bf16 v[80:83], v[208:211], v[184:187], v[80:83]
	v_mfma_f32_16x16x32_bf16 v[68:71], v[200:203], v[192:195], v[68:71]
	v_mfma_f32_16x16x32_bf16 v[64:67], v[208:211], v[192:195], v[64:67]
	v_mfma_f32_16x16x32_bf16 v[116:119], v[204:207], v[172:175], v[116:119]
	v_mfma_f32_16x16x32_bf16 v[112:115], v[212:215], v[172:175], v[112:115]
	v_mfma_f32_16x16x32_bf16 v[100:103], v[204:207], v[180:183], v[100:103]
	v_mfma_f32_16x16x32_bf16 v[96:99], v[212:215], v[180:183], v[96:99]
	v_mfma_f32_16x16x32_bf16 v[84:87], v[204:207], v[188:191], v[84:87]
	v_mfma_f32_16x16x32_bf16 v[80:83], v[212:215], v[188:191], v[80:83]
	v_mfma_f32_16x16x32_bf16 v[68:71], v[204:207], v[196:199], v[68:71]
	v_mfma_f32_16x16x32_bf16 v[64:67], v[212:215], v[196:199], v[64:67]
	s_mov_b32 m0, s59
	v_lshl_add_u64 v[216:217], v[220:221], 0, s[20:21]
	s_barrier
	ds_read_b128 v[168:171], v152 offset:49152
	ds_read_b128 v[172:175], v152 offset:50176
	ds_read_b128 v[176:179], v152 offset:51200
	ds_read_b128 v[180:183], v152 offset:52224
	ds_read_b128 v[184:187], v152 offset:53248
	ds_read_b128 v[188:191], v152 offset:54272
	ds_read_b128 v[192:195], v152 offset:55296
	ds_read_b128 v[196:199], v152 offset:56320
	global_load_lds_dwordx4 v[216:217], off
	s_mov_b32 m0, s60
	v_lshl_add_u64 v[216:217], v[222:223], 0, s[20:21]
	global_load_lds_dwordx4 v[216:217], off
	s_barrier
	s_waitcnt lgkmcnt(0)
	s_waitcnt lgkmcnt(0)
	v_mfma_f32_16x16x32_bf16 v[60:63], v[144:147], v[168:171], v[60:63]
	v_mfma_f32_16x16x32_bf16 v[56:59], v[160:163], v[168:171], v[56:59]
	v_mfma_f32_16x16x32_bf16 v[44:47], v[144:147], v[176:179], v[44:47]
	v_mfma_f32_16x16x32_bf16 v[40:43], v[160:163], v[176:179], v[40:43]
	v_mfma_f32_16x16x32_bf16 v[28:31], v[144:147], v[184:187], v[28:31]
	v_mfma_f32_16x16x32_bf16 v[24:27], v[160:163], v[184:187], v[24:27]
	v_mfma_f32_16x16x32_bf16 v[12:15], v[144:147], v[192:195], v[12:15]
	v_mfma_f32_16x16x32_bf16 v[8:11], v[160:163], v[192:195], v[8:11]
	v_mfma_f32_16x16x32_bf16 v[60:63], v[156:159], v[172:175], v[60:63]
	v_mfma_f32_16x16x32_bf16 v[56:59], v[164:167], v[172:175], v[56:59]
	v_mfma_f32_16x16x32_bf16 v[44:47], v[156:159], v[180:183], v[44:47]
	v_mfma_f32_16x16x32_bf16 v[40:43], v[164:167], v[180:183], v[40:43]
	v_mfma_f32_16x16x32_bf16 v[28:31], v[156:159], v[188:191], v[28:31]
	v_mfma_f32_16x16x32_bf16 v[24:27], v[164:167], v[188:191], v[24:27]
	v_mfma_f32_16x16x32_bf16 v[12:15], v[156:159], v[196:199], v[12:15]
	v_mfma_f32_16x16x32_bf16 v[8:11], v[164:167], v[196:199], v[8:11]
	s_barrier
	s_add_u32 s52, s52, 0x20080
	s_addc_u32 s53, s53, 0
	s_add_i32 s54, s97, s1
	s_mov_b32 m0, s54
	v_lshl_add_u64 v[144:145], s[52:53], 0, v[132:133]
	global_load_lds_dwordx4 v[144:145], off
	s_add_i32 m0, s54, 0x2000
	v_lshl_add_u64 v[144:145], s[52:53], 0, v[128:129]
	global_load_lds_dwordx4 v[144:145], off
	s_waitcnt vmcnt(6)
	s_barrier
	v_mfma_f32_16x16x32_bf16 v[52:55], v[200:203], v[168:171], v[52:55]
	v_mfma_f32_16x16x32_bf16 v[48:51], v[208:211], v[168:171], v[48:51]
	v_mfma_f32_16x16x32_bf16 v[36:39], v[200:203], v[176:179], v[36:39]
	v_mfma_f32_16x16x32_bf16 v[32:35], v[208:211], v[176:179], v[32:35]
	v_mfma_f32_16x16x32_bf16 v[20:23], v[200:203], v[184:187], v[20:23]
	v_mfma_f32_16x16x32_bf16 v[16:19], v[208:211], v[184:187], v[16:19]
	v_mfma_f32_16x16x32_bf16 v[4:7], v[200:203], v[192:195], v[4:7]
	v_mfma_f32_16x16x32_bf16 v[0:3], v[208:211], v[192:195], v[0:3]
	v_mfma_f32_16x16x32_bf16 v[52:55], v[204:207], v[172:175], v[52:55]
	v_mfma_f32_16x16x32_bf16 v[48:51], v[212:215], v[172:175], v[48:51]
	v_mfma_f32_16x16x32_bf16 v[36:39], v[204:207], v[180:183], v[36:39]
	v_mfma_f32_16x16x32_bf16 v[32:35], v[212:215], v[180:183], v[32:35]
	v_mfma_f32_16x16x32_bf16 v[20:23], v[204:207], v[188:191], v[20:23]
	v_mfma_f32_16x16x32_bf16 v[16:19], v[212:215], v[188:191], v[16:19]
	v_mfma_f32_16x16x32_bf16 v[4:7], v[204:207], v[196:199], v[4:7]
	v_mfma_f32_16x16x32_bf16 v[0:3], v[212:215], v[196:199], v[0:3]
	s_add_i32 s68, s68, 2
	s_add_u32 s50, s50, 0x100
	s_addc_u32 s51, s51, 0
	s_add_u32 s66, s66, 0x100
	s_addc_u32 s67, s67, 0
	s_cmp_gt_u32 s68, 5
	s_barrier
	s_cbranch_scc0 .LBB0_591
	v_lshl_add_u32 v146, s48, 8, v148
	v_lshl_or_b32 v144, s63, 8, v150
	v_ashrrev_i32_e32 v147, 31, v146
	v_lshlrev_b64 v[156:157], 12, v[146:147]
	v_ashrrev_i32_e32 v145, 31, v144
	v_lshl_add_u64 v[156:157], s[6:7], 0, v[156:157]
	v_lshlrev_b64 v[144:145], 1, v[144:145]
	v_lshl_add_u64 v[160:161], v[156:157], 0, v[144:145]
	global_load_dwordx4 v[156:159], v[160:161], off
	s_nop 0
	global_load_dwordx4 v[160:163], v[160:161], off offset:256
	v_or_b32_e32 v164, 16, v146
	v_lshlrev_b64 v[166:167], 11, v[146:147]
	v_ashrrev_i32_e32 v165, 31, v164
	v_lshl_add_u64 v[166:167], s[14:15], 0, v[166:167]
	v_lshlrev_b64 v[168:169], 12, v[164:165]
	v_lshl_add_u64 v[166:167], v[166:167], 0, v[144:145]
	v_lshl_add_u64 v[168:169], s[6:7], 0, v[168:169]
	v_lshl_add_u64 v[168:169], v[168:169], 0, v[144:145]
	s_and_b64 vcc, exec, s[4:5]
	s_mov_b32 s63, s24
	s_mov_b32 s48, s40
	s_mov_b64 s[52:53], s[46:47]
	s_mov_b64 s[50:51], s[44:45]
	s_waitcnt vmcnt(0)
	v_lshlrev_b32_e32 v170, 16, v156
	v_and_b32_e32 v171, 0xffff0000, v156
	v_lshlrev_b32_e32 v156, 16, v157
	v_and_b32_e32 v157, 0xffff0000, v157
	v_lshlrev_b32_e32 v172, 16, v158
	v_and_b32_e32 v173, 0xffff0000, v158
	v_lshlrev_b32_e32 v158, 16, v159
	v_and_b32_e32 v159, 0xffff0000, v159
	v_lshlrev_b32_e32 v174, 16, v160
	v_and_b32_e32 v175, 0xffff0000, v160
	v_lshlrev_b32_e32 v160, 16, v161
	v_and_b32_e32 v161, 0xffff0000, v161
	v_lshlrev_b32_e32 v176, 16, v162
	v_and_b32_e32 v177, 0xffff0000, v162
	v_lshlrev_b32_e32 v162, 16, v163
	v_and_b32_e32 v163, 0xffff0000, v163
	v_pk_mul_f32 v[126:127], v[126:127], v[156:157]
	v_pk_mul_f32 v[124:125], v[124:125], v[170:171]
	v_pk_mul_f32 v[122:123], v[122:123], v[158:159]
	v_pk_mul_f32 v[120:121], v[120:121], v[172:173]
	v_pk_mul_f32 v[156:157], v[118:119], v[160:161]
	v_pk_mul_f32 v[158:159], v[116:117], v[174:175]
	v_cvt_pk_bf16_f32 v116, v124, v125
	v_cvt_pk_bf16_f32 v117, v126, v127
	v_cvt_pk_bf16_f32 v118, v120, v121
	v_cvt_pk_bf16_f32 v119, v122, v123
	v_pk_mul_f32 v[120:121], v[114:115], v[162:163]
	v_pk_mul_f32 v[114:115], v[112:113], v[176:177]
	global_store_dwordx4 v[166:167], v[116:119], off
	v_cvt_pk_bf16_f32 v112, v158, v159
	v_cvt_pk_bf16_f32 v113, v156, v157
	v_cvt_pk_bf16_f32 v114, v114, v115
	v_cvt_pk_bf16_f32 v115, v120, v121
	global_load_dwordx4 v[116:119], v[168:169], off
	v_or_b32_e32 v120, 32, v146
	global_store_dwordx4 v[166:167], v[112:115], off offset:256
	global_load_dwordx4 v[112:115], v[168:169], off offset:256
	v_ashrrev_i32_e32 v121, 31, v120
	v_lshlrev_b64 v[122:123], 11, v[164:165]
	v_lshlrev_b64 v[124:125], 12, v[120:121]
	v_lshl_add_u64 v[122:123], s[14:15], 0, v[122:123]
	v_lshl_add_u64 v[124:125], s[6:7], 0, v[124:125]
	v_lshl_add_u64 v[122:123], v[122:123], 0, v[144:145]
	v_lshl_add_u64 v[124:125], v[124:125], 0, v[144:145]
	s_waitcnt vmcnt(0)
	v_lshlrev_b32_e32 v126, 16, v116
	v_and_b32_e32 v127, 0xffff0000, v116
	v_lshlrev_b32_e32 v116, 16, v117
	v_and_b32_e32 v117, 0xffff0000, v117
	v_lshlrev_b32_e32 v156, 16, v118
	v_and_b32_e32 v157, 0xffff0000, v118
	v_lshlrev_b32_e32 v118, 16, v119
	v_and_b32_e32 v119, 0xffff0000, v119
	v_lshlrev_b32_e32 v158, 16, v112
	v_and_b32_e32 v159, 0xffff0000, v112
	v_lshlrev_b32_e32 v112, 16, v113
	v_and_b32_e32 v113, 0xffff0000, v113
	v_lshlrev_b32_e32 v160, 16, v114
	v_and_b32_e32 v161, 0xffff0000, v114
	v_lshlrev_b32_e32 v114, 16, v115
	v_and_b32_e32 v115, 0xffff0000, v115
	v_pk_mul_f32 v[110:111], v[110:111], v[116:117]
	v_pk_mul_f32 v[108:109], v[108:109], v[126:127]
	v_pk_mul_f32 v[106:107], v[106:107], v[118:119]
	v_pk_mul_f32 v[104:105], v[104:105], v[156:157]
	v_pk_mul_f32 v[112:113], v[102:103], v[112:113]
	v_pk_mul_f32 v[116:117], v[100:101], v[158:159]
	v_cvt_pk_bf16_f32 v100, v108, v109
	v_cvt_pk_bf16_f32 v101, v110, v111
	v_cvt_pk_bf16_f32 v102, v104, v105
	v_cvt_pk_bf16_f32 v103, v106, v107
	v_pk_mul_f32 v[104:105], v[98:99], v[114:115]
	v_pk_mul_f32 v[98:99], v[96:97], v[160:161]
	global_store_dwordx4 v[122:123], v[100:103], off
	v_cvt_pk_bf16_f32 v96, v116, v117
	v_cvt_pk_bf16_f32 v97, v112, v113
	v_cvt_pk_bf16_f32 v98, v98, v99
	v_cvt_pk_bf16_f32 v99, v104, v105
	global_load_dwordx4 v[100:103], v[124:125], off
	v_or_b32_e32 v104, 48, v146
	global_store_dwordx4 v[122:123], v[96:99], off offset:256
	global_load_dwordx4 v[96:99], v[124:125], off offset:256
	v_ashrrev_i32_e32 v105, 31, v104
	v_lshlrev_b64 v[106:107], 11, v[120:121]
	v_lshlrev_b64 v[108:109], 12, v[104:105]
	v_lshl_add_u64 v[106:107], s[14:15], 0, v[106:107]
	v_lshl_add_u64 v[108:109], s[6:7], 0, v[108:109]
	v_lshl_add_u64 v[106:107], v[106:107], 0, v[144:145]
	v_lshl_add_u64 v[108:109], v[108:109], 0, v[144:145]
	s_waitcnt vmcnt(0)
	v_lshlrev_b32_e32 v110, 16, v100
	v_and_b32_e32 v111, 0xffff0000, v100
	v_lshlrev_b32_e32 v100, 16, v101
	v_and_b32_e32 v101, 0xffff0000, v101
	v_lshlrev_b32_e32 v112, 16, v102
	v_and_b32_e32 v113, 0xffff0000, v102
	v_lshlrev_b32_e32 v102, 16, v103
	v_and_b32_e32 v103, 0xffff0000, v103
	v_lshlrev_b32_e32 v114, 16, v96
	v_and_b32_e32 v115, 0xffff0000, v96
	v_lshlrev_b32_e32 v96, 16, v97
	v_and_b32_e32 v97, 0xffff0000, v97
	v_lshlrev_b32_e32 v116, 16, v98
	v_and_b32_e32 v117, 0xffff0000, v98
	v_lshlrev_b32_e32 v98, 16, v99
	v_and_b32_e32 v99, 0xffff0000, v99
	v_pk_mul_f32 v[94:95], v[94:95], v[100:101]
	v_pk_mul_f32 v[92:93], v[92:93], v[110:111]
	v_pk_mul_f32 v[90:91], v[90:91], v[102:103]
	v_pk_mul_f32 v[88:89], v[88:89], v[112:113]
	v_pk_mul_f32 v[96:97], v[86:87], v[96:97]
	v_pk_mul_f32 v[100:101], v[84:85], v[114:115]
	v_cvt_pk_bf16_f32 v84, v92, v93
	v_cvt_pk_bf16_f32 v85, v94, v95
	v_cvt_pk_bf16_f32 v86, v88, v89
	v_cvt_pk_bf16_f32 v87, v90, v91
	v_pk_mul_f32 v[88:89], v[82:83], v[98:99]
	v_pk_mul_f32 v[82:83], v[80:81], v[116:117]
	global_store_dwordx4 v[106:107], v[84:87], off
	v_cvt_pk_bf16_f32 v80, v100, v101
	v_cvt_pk_bf16_f32 v81, v96, v97
	v_cvt_pk_bf16_f32 v82, v82, v83
	v_cvt_pk_bf16_f32 v83, v88, v89
	global_load_dwordx4 v[84:87], v[108:109], off
	v_add_u32_e32 v88, 0x80, v146
	global_store_dwordx4 v[106:107], v[80:83], off offset:256
	global_load_dwordx4 v[80:83], v[108:109], off offset:256
	v_ashrrev_i32_e32 v89, 31, v88
	v_lshlrev_b64 v[90:91], 11, v[104:105]
	v_lshlrev_b64 v[92:93], 12, v[88:89]
	v_lshl_add_u64 v[90:91], s[14:15], 0, v[90:91]
	v_lshl_add_u64 v[92:93], s[6:7], 0, v[92:93]
	v_lshl_add_u64 v[90:91], v[90:91], 0, v[144:145]
	v_lshl_add_u64 v[92:93], v[92:93], 0, v[144:145]
	s_waitcnt vmcnt(0)
	v_lshlrev_b32_e32 v94, 16, v84
	v_and_b32_e32 v95, 0xffff0000, v84
	v_lshlrev_b32_e32 v84, 16, v85
	v_and_b32_e32 v85, 0xffff0000, v85
	v_lshlrev_b32_e32 v96, 16, v86
	v_and_b32_e32 v97, 0xffff0000, v86
	v_lshlrev_b32_e32 v86, 16, v87
	v_and_b32_e32 v87, 0xffff0000, v87
	v_lshlrev_b32_e32 v98, 16, v80
	v_and_b32_e32 v99, 0xffff0000, v80
	v_lshlrev_b32_e32 v80, 16, v81
	v_and_b32_e32 v81, 0xffff0000, v81
	v_lshlrev_b32_e32 v100, 16, v82
	v_and_b32_e32 v101, 0xffff0000, v82
	v_lshlrev_b32_e32 v82, 16, v83
	v_and_b32_e32 v83, 0xffff0000, v83
	v_pk_mul_f32 v[78:79], v[78:79], v[84:85]
	v_pk_mul_f32 v[76:77], v[76:77], v[94:95]
	v_pk_mul_f32 v[74:75], v[74:75], v[86:87]
	v_pk_mul_f32 v[72:73], v[72:73], v[96:97]
	v_pk_mul_f32 v[80:81], v[70:71], v[80:81]
	v_pk_mul_f32 v[84:85], v[68:69], v[98:99]
	v_cvt_pk_bf16_f32 v68, v76, v77
	v_cvt_pk_bf16_f32 v69, v78, v79
	v_cvt_pk_bf16_f32 v70, v72, v73
	v_cvt_pk_bf16_f32 v71, v74, v75
	v_pk_mul_f32 v[72:73], v[66:67], v[82:83]
	v_pk_mul_f32 v[66:67], v[64:65], v[100:101]
	global_store_dwordx4 v[90:91], v[68:71], off
	v_cvt_pk_bf16_f32 v64, v84, v85
	v_cvt_pk_bf16_f32 v65, v80, v81
	v_cvt_pk_bf16_f32 v66, v66, v67
	v_cvt_pk_bf16_f32 v67, v72, v73
	global_load_dwordx4 v[68:71], v[92:93], off
	v_add_u32_e32 v72, 0x90, v146
	global_store_dwordx4 v[90:91], v[64:67], off offset:256
	global_load_dwordx4 v[64:67], v[92:93], off offset:256
	v_ashrrev_i32_e32 v73, 31, v72
	v_lshlrev_b64 v[74:75], 11, v[88:89]
	v_lshlrev_b64 v[76:77], 12, v[72:73]
	v_lshl_add_u64 v[74:75], s[14:15], 0, v[74:75]
	v_lshl_add_u64 v[76:77], s[6:7], 0, v[76:77]
	v_lshl_add_u64 v[74:75], v[74:75], 0, v[144:145]
	v_lshl_add_u64 v[76:77], v[76:77], 0, v[144:145]
	s_waitcnt vmcnt(0)
	v_lshlrev_b32_e32 v78, 16, v68
	v_and_b32_e32 v79, 0xffff0000, v68
	v_lshlrev_b32_e32 v68, 16, v69
	v_and_b32_e32 v69, 0xffff0000, v69
	v_lshlrev_b32_e32 v80, 16, v70
	v_and_b32_e32 v81, 0xffff0000, v70
	v_lshlrev_b32_e32 v70, 16, v71
	v_and_b32_e32 v71, 0xffff0000, v71
	v_lshlrev_b32_e32 v82, 16, v64
	v_and_b32_e32 v83, 0xffff0000, v64
	v_lshlrev_b32_e32 v64, 16, v65
	v_and_b32_e32 v65, 0xffff0000, v65
	v_lshlrev_b32_e32 v84, 16, v66
	v_and_b32_e32 v85, 0xffff0000, v66
	v_lshlrev_b32_e32 v66, 16, v67
	v_and_b32_e32 v67, 0xffff0000, v67
	v_pk_mul_f32 v[62:63], v[62:63], v[68:69]
	v_pk_mul_f32 v[60:61], v[60:61], v[78:79]
	v_pk_mul_f32 v[58:59], v[58:59], v[70:71]
	v_pk_mul_f32 v[56:57], v[56:57], v[80:81]
	v_pk_mul_f32 v[64:65], v[54:55], v[64:65]
	v_pk_mul_f32 v[68:69], v[52:53], v[82:83]
	v_cvt_pk_bf16_f32 v52, v60, v61
	v_cvt_pk_bf16_f32 v53, v62, v63
	v_cvt_pk_bf16_f32 v54, v56, v57
	v_cvt_pk_bf16_f32 v55, v58, v59
	v_pk_mul_f32 v[56:57], v[50:51], v[66:67]
	v_pk_mul_f32 v[50:51], v[48:49], v[84:85]
	global_store_dwordx4 v[74:75], v[52:55], off
	v_cvt_pk_bf16_f32 v48, v68, v69
	v_cvt_pk_bf16_f32 v49, v64, v65
	v_cvt_pk_bf16_f32 v50, v50, v51
	v_cvt_pk_bf16_f32 v51, v56, v57
	global_load_dwordx4 v[52:55], v[76:77], off
	v_add_u32_e32 v56, 0xa0, v146
	global_store_dwordx4 v[74:75], v[48:51], off offset:256
	global_load_dwordx4 v[48:51], v[76:77], off offset:256
	v_ashrrev_i32_e32 v57, 31, v56
	v_lshlrev_b64 v[58:59], 11, v[72:73]
	v_lshlrev_b64 v[60:61], 12, v[56:57]
	v_lshl_add_u64 v[58:59], s[14:15], 0, v[58:59]
	v_lshl_add_u64 v[60:61], s[6:7], 0, v[60:61]
	v_lshl_add_u64 v[58:59], v[58:59], 0, v[144:145]
	v_lshl_add_u64 v[60:61], v[60:61], 0, v[144:145]
	s_waitcnt vmcnt(0)
	v_lshlrev_b32_e32 v62, 16, v52
	v_and_b32_e32 v63, 0xffff0000, v52
	v_lshlrev_b32_e32 v52, 16, v53
	v_and_b32_e32 v53, 0xffff0000, v53
	v_lshlrev_b32_e32 v64, 16, v54
	v_and_b32_e32 v65, 0xffff0000, v54
	v_lshlrev_b32_e32 v54, 16, v55
	v_and_b32_e32 v55, 0xffff0000, v55
	v_lshlrev_b32_e32 v66, 16, v48
	v_and_b32_e32 v67, 0xffff0000, v48
	v_lshlrev_b32_e32 v48, 16, v49
	v_and_b32_e32 v49, 0xffff0000, v49
	v_lshlrev_b32_e32 v68, 16, v50
	v_and_b32_e32 v69, 0xffff0000, v50
	v_lshlrev_b32_e32 v50, 16, v51
	v_and_b32_e32 v51, 0xffff0000, v51
	v_pk_mul_f32 v[46:47], v[46:47], v[52:53]
	v_pk_mul_f32 v[44:45], v[44:45], v[62:63]
	v_pk_mul_f32 v[42:43], v[42:43], v[54:55]
	v_pk_mul_f32 v[40:41], v[40:41], v[64:65]
	v_pk_mul_f32 v[48:49], v[38:39], v[48:49]
	v_pk_mul_f32 v[52:53], v[36:37], v[66:67]
	v_cvt_pk_bf16_f32 v36, v44, v45
	v_cvt_pk_bf16_f32 v37, v46, v47
	v_cvt_pk_bf16_f32 v38, v40, v41
	v_cvt_pk_bf16_f32 v39, v42, v43
	v_pk_mul_f32 v[40:41], v[34:35], v[50:51]
	v_pk_mul_f32 v[34:35], v[32:33], v[68:69]
	global_store_dwordx4 v[58:59], v[36:39], off
	v_cvt_pk_bf16_f32 v32, v52, v53
	v_cvt_pk_bf16_f32 v33, v48, v49
	v_cvt_pk_bf16_f32 v34, v34, v35
	v_cvt_pk_bf16_f32 v35, v40, v41
	global_load_dwordx4 v[36:39], v[60:61], off
	v_add_u32_e32 v40, 0xb0, v146
	global_store_dwordx4 v[58:59], v[32:35], off offset:256
	global_load_dwordx4 v[32:35], v[60:61], off offset:256
	v_ashrrev_i32_e32 v41, 31, v40
	v_lshlrev_b64 v[42:43], 11, v[56:57]
	v_lshlrev_b64 v[44:45], 12, v[40:41]
	v_lshl_add_u64 v[42:43], s[14:15], 0, v[42:43]
	v_lshl_add_u64 v[44:45], s[6:7], 0, v[44:45]
	v_lshl_add_u64 v[42:43], v[42:43], 0, v[144:145]
	v_lshl_add_u64 v[44:45], v[44:45], 0, v[144:145]
	s_waitcnt vmcnt(0)
	v_lshlrev_b32_e32 v46, 16, v36
	v_and_b32_e32 v47, 0xffff0000, v36
	v_lshlrev_b32_e32 v36, 16, v37
	v_and_b32_e32 v37, 0xffff0000, v37
	v_lshlrev_b32_e32 v48, 16, v38
	v_and_b32_e32 v49, 0xffff0000, v38
	v_lshlrev_b32_e32 v38, 16, v39
	v_and_b32_e32 v39, 0xffff0000, v39
	v_lshlrev_b32_e32 v50, 16, v32
	v_and_b32_e32 v51, 0xffff0000, v32
	v_lshlrev_b32_e32 v32, 16, v33
	v_and_b32_e32 v33, 0xffff0000, v33
	v_lshlrev_b32_e32 v52, 16, v34
	v_and_b32_e32 v53, 0xffff0000, v34
	v_lshlrev_b32_e32 v34, 16, v35
	v_and_b32_e32 v35, 0xffff0000, v35
	v_pk_mul_f32 v[30:31], v[30:31], v[36:37]
	v_pk_mul_f32 v[28:29], v[28:29], v[46:47]
	v_pk_mul_f32 v[26:27], v[26:27], v[38:39]
	v_pk_mul_f32 v[24:25], v[24:25], v[48:49]
	v_pk_mul_f32 v[32:33], v[22:23], v[32:33]
	v_pk_mul_f32 v[36:37], v[20:21], v[50:51]
	v_cvt_pk_bf16_f32 v20, v28, v29
	v_cvt_pk_bf16_f32 v21, v30, v31
	v_cvt_pk_bf16_f32 v22, v24, v25
	v_cvt_pk_bf16_f32 v23, v26, v27
	v_pk_mul_f32 v[24:25], v[18:19], v[34:35]
	v_pk_mul_f32 v[18:19], v[16:17], v[52:53]
	global_store_dwordx4 v[42:43], v[20:23], off
	v_cvt_pk_bf16_f32 v16, v36, v37
	v_cvt_pk_bf16_f32 v17, v32, v33
	v_cvt_pk_bf16_f32 v18, v18, v19
	v_cvt_pk_bf16_f32 v19, v24, v25
	global_load_dwordx4 v[20:23], v[44:45], off
	v_lshlrev_b64 v[24:25], 11, v[40:41]
	global_store_dwordx4 v[42:43], v[16:19], off offset:256
	global_load_dwordx4 v[16:19], v[44:45], off offset:256
	v_lshl_add_u64 v[24:25], s[14:15], 0, v[24:25]
	v_lshl_add_u64 v[24:25], v[24:25], 0, v[144:145]
	s_waitcnt vmcnt(0)
	v_lshlrev_b32_e32 v26, 16, v20
	v_and_b32_e32 v27, 0xffff0000, v20
	v_lshlrev_b32_e32 v20, 16, v21
	v_and_b32_e32 v21, 0xffff0000, v21
	v_lshlrev_b32_e32 v28, 16, v22
	v_and_b32_e32 v29, 0xffff0000, v22
	v_lshlrev_b32_e32 v22, 16, v23
	v_and_b32_e32 v23, 0xffff0000, v23
	v_lshlrev_b32_e32 v30, 16, v16
	v_and_b32_e32 v31, 0xffff0000, v16
	v_lshlrev_b32_e32 v16, 16, v17
	v_and_b32_e32 v17, 0xffff0000, v17
	v_lshlrev_b32_e32 v32, 16, v18
	v_and_b32_e32 v33, 0xffff0000, v18
	v_lshlrev_b32_e32 v18, 16, v19
	v_and_b32_e32 v19, 0xffff0000, v19
	v_pk_mul_f32 v[14:15], v[14:15], v[20:21]
	v_pk_mul_f32 v[12:13], v[12:13], v[26:27]
	v_pk_mul_f32 v[10:11], v[10:11], v[22:23]
	v_pk_mul_f32 v[8:9], v[8:9], v[28:29]
	v_pk_mul_f32 v[6:7], v[6:7], v[16:17]
	v_pk_mul_f32 v[4:5], v[4:5], v[30:31]
	v_pk_mul_f32 v[16:17], v[2:3], v[18:19]
	v_pk_mul_f32 v[18:19], v[0:1], v[32:33]
	v_cvt_pk_bf16_f32 v0, v12, v13
	v_cvt_pk_bf16_f32 v1, v14, v15
	v_cvt_pk_bf16_f32 v2, v8, v9
	v_cvt_pk_bf16_f32 v3, v10, v11
	v_cvt_pk_bf16_f32 v4, v4, v5
	v_cvt_pk_bf16_f32 v5, v6, v7
	v_cvt_pk_bf16_f32 v6, v18, v19
	v_cvt_pk_bf16_f32 v7, v16, v17
	global_store_dwordx4 v[24:25], v[0:3], off
	global_store_dwordx4 v[24:25], v[4:7], off offset:256
	s_cbranch_vccz .LBB0_588
	s_waitcnt vmcnt(0)
	s_cmpk_gt_u32 s0, 0xff
	s_cbranch_scc1 .LBB0_595
	s_barrier

.LBB0_603:
	ds_read_b128 v[144:147], v153
	ds_read_b128 v[158:161], v153 offset:1024
	ds_read_b128 v[162:165], v153 offset:2048
	ds_read_b128 v[166:169], v153 offset:3072
	s_add_u32 s50, s48, 0xfffc0080
	s_addc_u32 s51, s49, -1
	s_cmp_eq_u32 s66, 12
	s_cselect_b32 s53, s25, s51
	s_cselect_b32 s52, s62, s50
	s_cselect_b32 s51, s23, s65
	s_cselect_b32 s50, s63, s64
	v_lshl_add_u64 v[148:149], s[48:49], 0, v[136:137]
	s_add_i32 m0, s35, 0xc000
	ds_read_b128 v[170:173], v156
	ds_read_b128 v[174:177], v156 offset:1024
	ds_read_b128 v[178:181], v156 offset:2048
	ds_read_b128 v[182:185], v156 offset:3072
	ds_read_b128 v[186:189], v156 offset:4096
	ds_read_b128 v[190:193], v156 offset:5120
	ds_read_b128 v[194:197], v156 offset:6144
	ds_read_b128 v[198:201], v156 offset:7168
	global_load_lds_dwordx4 v[148:149], off
	s_add_i32 m0, s35, 0xe000
	v_lshl_add_u64 v[148:149], s[48:49], 0, v[138:139]
	global_load_lds_dwordx4 v[148:149], off
	s_waitcnt lgkmcnt(8)
	s_barrier
	s_waitcnt lgkmcnt(0)
	s_waitcnt lgkmcnt(0)
	v_mfma_f32_16x16x32_bf16 v[124:127], v[144:147], v[170:173], v[124:127]
	v_mfma_f32_16x16x32_bf16 v[120:123], v[162:165], v[170:173], v[120:123]
	v_mfma_f32_16x16x32_bf16 v[108:111], v[144:147], v[178:181], v[108:111]
	v_mfma_f32_16x16x32_bf16 v[104:107], v[162:165], v[178:181], v[104:107]
	v_mfma_f32_16x16x32_bf16 v[92:95], v[144:147], v[186:189], v[92:95]
	v_mfma_f32_16x16x32_bf16 v[88:91], v[162:165], v[186:189], v[88:91]
	v_mfma_f32_16x16x32_bf16 v[76:79], v[144:147], v[194:197], v[76:79]
	v_mfma_f32_16x16x32_bf16 v[72:75], v[162:165], v[194:197], v[72:75]
	v_mfma_f32_16x16x32_bf16 v[124:127], v[158:161], v[174:177], v[124:127]
	v_mfma_f32_16x16x32_bf16 v[120:123], v[166:169], v[174:177], v[120:123]
	v_mfma_f32_16x16x32_bf16 v[108:111], v[158:161], v[182:185], v[108:111]
	v_mfma_f32_16x16x32_bf16 v[104:107], v[166:169], v[182:185], v[104:107]
	v_mfma_f32_16x16x32_bf16 v[92:95], v[158:161], v[190:193], v[92:95]
	v_mfma_f32_16x16x32_bf16 v[88:91], v[166:169], v[190:193], v[88:91]
	v_mfma_f32_16x16x32_bf16 v[76:79], v[158:161], v[198:201], v[76:79]
	v_mfma_f32_16x16x32_bf16 v[72:75], v[166:169], v[198:201], v[72:75]
	s_barrier
	s_add_i32 s67, s60, s1
	v_lshl_add_u64 v[148:149], s[50:51], 0, v[132:133]
	s_mov_b32 m0, s67
	ds_read_b128 v[202:205], v157
	ds_read_b128 v[206:209], v157 offset:1024
	ds_read_b128 v[210:213], v157 offset:2048
	ds_read_b128 v[214:217], v157 offset:3072
	global_load_lds_dwordx4 v[148:149], off
	s_add_i32 m0, s67, 0x2000
	v_lshl_add_u64 v[218:219], s[50:51], 0, v[128:129]
	global_load_lds_dwordx4 v[218:219], off
	s_barrier
	s_waitcnt lgkmcnt(0)
	s_waitcnt lgkmcnt(0)
	v_mfma_f32_16x16x32_bf16 v[116:119], v[202:205], v[170:173], v[116:119]
	v_mfma_f32_16x16x32_bf16 v[112:115], v[210:213], v[170:173], v[112:115]
	v_mfma_f32_16x16x32_bf16 v[100:103], v[202:205], v[178:181], v[100:103]
	v_mfma_f32_16x16x32_bf16 v[96:99], v[210:213], v[178:181], v[96:99]
	v_mfma_f32_16x16x32_bf16 v[84:87], v[202:205], v[186:189], v[84:87]
	v_mfma_f32_16x16x32_bf16 v[80:83], v[210:213], v[186:189], v[80:83]
	v_mfma_f32_16x16x32_bf16 v[68:71], v[202:205], v[194:197], v[68:71]
	v_mfma_f32_16x16x32_bf16 v[64:67], v[210:213], v[194:197], v[64:67]
	v_mfma_f32_16x16x32_bf16 v[116:119], v[206:209], v[174:177], v[116:119]
	v_mfma_f32_16x16x32_bf16 v[112:115], v[214:217], v[174:177], v[112:115]
	v_mfma_f32_16x16x32_bf16 v[100:103], v[206:209], v[182:185], v[100:103]
	v_mfma_f32_16x16x32_bf16 v[96:99], v[214:217], v[182:185], v[96:99]
	v_mfma_f32_16x16x32_bf16 v[84:87], v[206:209], v[190:193], v[84:87]
	v_mfma_f32_16x16x32_bf16 v[80:83], v[214:217], v[190:193], v[80:83]
	v_mfma_f32_16x16x32_bf16 v[68:71], v[206:209], v[198:201], v[68:71]
	v_mfma_f32_16x16x32_bf16 v[64:67], v[214:217], v[198:201], v[64:67]
	s_mov_b32 m0, s35
	v_lshl_add_u64 v[220:221], s[52:53], 0, v[134:135]
	s_barrier
	ds_read_b128 v[170:173], v156 offset:16384
	ds_read_b128 v[174:177], v156 offset:17408
	ds_read_b128 v[178:181], v156 offset:18432
	ds_read_b128 v[182:185], v156 offset:19456
	ds_read_b128 v[186:189], v156 offset:20480
	ds_read_b128 v[190:193], v156 offset:21504
	ds_read_b128 v[194:197], v156 offset:22528
	ds_read_b128 v[198:201], v156 offset:23552
	global_load_lds_dwordx4 v[220:221], off
	s_mov_b32 m0, s47
	v_lshl_add_u64 v[222:223], s[52:53], 0, v[130:131]
	global_load_lds_dwordx4 v[222:223], off
	s_barrier
	s_waitcnt lgkmcnt(0)
	s_waitcnt lgkmcnt(0)
	v_mfma_f32_16x16x32_bf16 v[60:63], v[144:147], v[170:173], v[60:63]
	v_mfma_f32_16x16x32_bf16 v[56:59], v[162:165], v[170:173], v[56:59]
	v_mfma_f32_16x16x32_bf16 v[44:47], v[144:147], v[178:181], v[44:47]
	v_mfma_f32_16x16x32_bf16 v[40:43], v[162:165], v[178:181], v[40:43]
	v_mfma_f32_16x16x32_bf16 v[28:31], v[144:147], v[186:189], v[28:31]
	v_mfma_f32_16x16x32_bf16 v[24:27], v[162:165], v[186:189], v[24:27]
	v_mfma_f32_16x16x32_bf16 v[12:15], v[144:147], v[194:197], v[12:15]
	v_mfma_f32_16x16x32_bf16 v[8:11], v[162:165], v[194:197], v[8:11]
	v_mfma_f32_16x16x32_bf16 v[60:63], v[158:161], v[174:177], v[60:63]
	v_mfma_f32_16x16x32_bf16 v[56:59], v[166:169], v[174:177], v[56:59]
	v_mfma_f32_16x16x32_bf16 v[44:47], v[158:161], v[182:185], v[44:47]
	v_mfma_f32_16x16x32_bf16 v[40:43], v[166:169], v[182:185], v[40:43]
	v_mfma_f32_16x16x32_bf16 v[28:31], v[158:161], v[190:193], v[28:31]
	v_mfma_f32_16x16x32_bf16 v[24:27], v[166:169], v[190:193], v[24:27]
	v_mfma_f32_16x16x32_bf16 v[12:15], v[158:161], v[198:201], v[12:15]
	v_mfma_f32_16x16x32_bf16 v[8:11], v[166:169], v[198:201], v[8:11]
	s_barrier
	s_add_u32 s68, s50, 0x40000
	s_addc_u32 s69, s51, 0
	s_add_i32 s67, s72, s1
	s_mov_b32 m0, s67
	v_lshl_add_u64 v[144:145], s[68:69], 0, v[132:133]
	global_load_lds_dwordx4 v[144:145], off
	s_add_i32 m0, s67, 0x2000
	v_lshl_add_u64 v[144:145], s[68:69], 0, v[128:129]
	global_load_lds_dwordx4 v[144:145], off
	s_waitcnt vmcnt(6)
	s_barrier
	v_mfma_f32_16x16x32_bf16 v[52:55], v[202:205], v[170:173], v[52:55]
	v_mfma_f32_16x16x32_bf16 v[48:51], v[210:213], v[170:173], v[48:51]
	v_mfma_f32_16x16x32_bf16 v[36:39], v[202:205], v[178:181], v[36:39]
	v_mfma_f32_16x16x32_bf16 v[32:35], v[210:213], v[178:181], v[32:35]
	v_mfma_f32_16x16x32_bf16 v[20:23], v[202:205], v[186:189], v[20:23]
	v_mfma_f32_16x16x32_bf16 v[16:19], v[210:213], v[186:189], v[16:19]
	v_mfma_f32_16x16x32_bf16 v[4:7], v[202:205], v[194:197], v[4:7]
	v_mfma_f32_16x16x32_bf16 v[0:3], v[210:213], v[194:197], v[0:3]
	v_mfma_f32_16x16x32_bf16 v[52:55], v[206:209], v[174:177], v[52:55]
	v_mfma_f32_16x16x32_bf16 v[48:51], v[214:217], v[174:177], v[48:51]
	v_mfma_f32_16x16x32_bf16 v[36:39], v[206:209], v[182:185], v[36:39]
	v_mfma_f32_16x16x32_bf16 v[32:35], v[214:217], v[182:185], v[32:35]
	v_mfma_f32_16x16x32_bf16 v[20:23], v[206:209], v[190:193], v[20:23]
	v_mfma_f32_16x16x32_bf16 v[16:19], v[214:217], v[190:193], v[16:19]
	v_mfma_f32_16x16x32_bf16 v[4:7], v[206:209], v[198:201], v[4:7]
	v_mfma_f32_16x16x32_bf16 v[0:3], v[214:217], v[198:201], v[0:3]
	s_add_i32 s67, 0, 0x18000
	v_add_u32_e32 v166, s67, v151
	s_barrier
	ds_read_b128 v[144:147], v166
	ds_read_b128 v[158:161], v166 offset:1024
	ds_read_b128 v[162:165], v166 offset:2048
	ds_read_b128 v[166:169], v166 offset:3072
	s_add_u32 s52, s52, 0x40000
	s_addc_u32 s53, s53, 0
	s_mov_b32 m0, s54
	v_lshl_add_u64 v[202:203], s[52:53], 0, v[134:135]
	ds_read_b128 v[170:173], v156 offset:32768
	ds_read_b128 v[174:177], v156 offset:33792
	ds_read_b128 v[178:181], v156 offset:34816
	ds_read_b128 v[182:185], v156 offset:35840
	ds_read_b128 v[186:189], v156 offset:36864
	ds_read_b128 v[190:193], v156 offset:37888
	ds_read_b128 v[194:197], v156 offset:38912
	ds_read_b128 v[198:201], v156 offset:39936
	global_load_lds_dwordx4 v[202:203], off
	s_mov_b32 m0, s55
	v_lshl_add_u64 v[202:203], s[52:53], 0, v[130:131]
	global_load_lds_dwordx4 v[202:203], off
	s_waitcnt lgkmcnt(8)
	s_barrier
	s_waitcnt lgkmcnt(0)
	s_waitcnt lgkmcnt(0)
	v_mfma_f32_16x16x32_bf16 v[124:127], v[144:147], v[170:173], v[124:127]
	v_mfma_f32_16x16x32_bf16 v[120:123], v[162:165], v[170:173], v[120:123]
	v_mfma_f32_16x16x32_bf16 v[108:111], v[144:147], v[178:181], v[108:111]
	v_mfma_f32_16x16x32_bf16 v[104:107], v[162:165], v[178:181], v[104:107]
	v_mfma_f32_16x16x32_bf16 v[92:95], v[144:147], v[186:189], v[92:95]
	v_mfma_f32_16x16x32_bf16 v[88:91], v[162:165], v[186:189], v[88:91]
	v_mfma_f32_16x16x32_bf16 v[76:79], v[144:147], v[194:197], v[76:79]
	v_mfma_f32_16x16x32_bf16 v[72:75], v[162:165], v[194:197], v[72:75]
	v_mfma_f32_16x16x32_bf16 v[124:127], v[158:161], v[174:177], v[124:127]
	v_mfma_f32_16x16x32_bf16 v[120:123], v[166:169], v[174:177], v[120:123]
	v_mfma_f32_16x16x32_bf16 v[108:111], v[158:161], v[182:185], v[108:111]
	v_mfma_f32_16x16x32_bf16 v[104:107], v[166:169], v[182:185], v[104:107]
	v_mfma_f32_16x16x32_bf16 v[92:95], v[158:161], v[190:193], v[92:95]
	v_mfma_f32_16x16x32_bf16 v[88:91], v[166:169], v[190:193], v[88:91]
	v_mfma_f32_16x16x32_bf16 v[76:79], v[158:161], v[198:201], v[76:79]
	v_mfma_f32_16x16x32_bf16 v[72:75], v[166:169], v[198:201], v[72:75]
	s_barrier
	s_add_i32 s52, s67, s1
	v_add_u32_e32 v214, s97, v151
	v_lshl_add_u64 v[148:149], v[148:149], 0, s[20:21]
	s_mov_b32 m0, s52
	ds_read_b128 v[202:205], v214
	ds_read_b128 v[206:209], v214 offset:1024
	ds_read_b128 v[210:213], v214 offset:2048
	ds_read_b128 v[214:217], v214 offset:3072
	global_load_lds_dwordx4 v[148:149], off
	s_add_i32 m0, s52, 0x2000
	v_lshl_add_u64 v[148:149], v[218:219], 0, s[20:21]
	global_load_lds_dwordx4 v[148:149], off
	s_barrier
	s_waitcnt lgkmcnt(0)
	s_waitcnt lgkmcnt(0)
	v_mfma_f32_16x16x32_bf16 v[116:119], v[202:205], v[170:173], v[116:119]
	v_mfma_f32_16x16x32_bf16 v[112:115], v[210:213], v[170:173], v[112:115]
	v_mfma_f32_16x16x32_bf16 v[100:103], v[202:205], v[178:181], v[100:103]
	v_mfma_f32_16x16x32_bf16 v[96:99], v[210:213], v[178:181], v[96:99]
	v_mfma_f32_16x16x32_bf16 v[84:87], v[202:205], v[186:189], v[84:87]
	v_mfma_f32_16x16x32_bf16 v[80:83], v[210:213], v[186:189], v[80:83]
	v_mfma_f32_16x16x32_bf16 v[68:71], v[202:205], v[194:197], v[68:71]
	v_mfma_f32_16x16x32_bf16 v[64:67], v[210:213], v[194:197], v[64:67]
	v_mfma_f32_16x16x32_bf16 v[116:119], v[206:209], v[174:177], v[116:119]
	v_mfma_f32_16x16x32_bf16 v[112:115], v[214:217], v[174:177], v[112:115]
	v_mfma_f32_16x16x32_bf16 v[100:103], v[206:209], v[182:185], v[100:103]
	v_mfma_f32_16x16x32_bf16 v[96:99], v[214:217], v[182:185], v[96:99]
	v_mfma_f32_16x16x32_bf16 v[84:87], v[206:209], v[190:193], v[84:87]
	v_mfma_f32_16x16x32_bf16 v[80:83], v[214:217], v[190:193], v[80:83]
	v_mfma_f32_16x16x32_bf16 v[68:71], v[206:209], v[198:201], v[68:71]
	v_mfma_f32_16x16x32_bf16 v[64:67], v[214:217], v[198:201], v[64:67]
	s_mov_b32 m0, s57
	v_lshl_add_u64 v[148:149], v[220:221], 0, s[20:21]
	s_barrier
	ds_read_b128 v[170:173], v156 offset:49152
	ds_read_b128 v[174:177], v156 offset:50176
	ds_read_b128 v[178:181], v156 offset:51200
	ds_read_b128 v[182:185], v156 offset:52224
	ds_read_b128 v[186:189], v156 offset:53248
	ds_read_b128 v[190:193], v156 offset:54272
	ds_read_b128 v[194:197], v156 offset:55296
	ds_read_b128 v[198:201], v156 offset:56320
	global_load_lds_dwordx4 v[148:149], off
	s_mov_b32 m0, s58
	v_lshl_add_u64 v[148:149], v[222:223], 0, s[20:21]
	global_load_lds_dwordx4 v[148:149], off
	s_barrier
	s_waitcnt lgkmcnt(0)
	s_waitcnt lgkmcnt(0)
	v_mfma_f32_16x16x32_bf16 v[60:63], v[144:147], v[170:173], v[60:63]
	v_mfma_f32_16x16x32_bf16 v[56:59], v[162:165], v[170:173], v[56:59]
	v_mfma_f32_16x16x32_bf16 v[44:47], v[144:147], v[178:181], v[44:47]
	v_mfma_f32_16x16x32_bf16 v[40:43], v[162:165], v[178:181], v[40:43]
	v_mfma_f32_16x16x32_bf16 v[28:31], v[144:147], v[186:189], v[28:31]
	v_mfma_f32_16x16x32_bf16 v[24:27], v[162:165], v[186:189], v[24:27]
	v_mfma_f32_16x16x32_bf16 v[12:15], v[144:147], v[194:197], v[12:15]
	v_mfma_f32_16x16x32_bf16 v[8:11], v[162:165], v[194:197], v[8:11]
	v_mfma_f32_16x16x32_bf16 v[60:63], v[158:161], v[174:177], v[60:63]
	v_mfma_f32_16x16x32_bf16 v[56:59], v[166:169], v[174:177], v[56:59]
	v_mfma_f32_16x16x32_bf16 v[44:47], v[158:161], v[182:185], v[44:47]
	v_mfma_f32_16x16x32_bf16 v[40:43], v[166:169], v[182:185], v[40:43]
	v_mfma_f32_16x16x32_bf16 v[28:31], v[158:161], v[190:193], v[28:31]
	v_mfma_f32_16x16x32_bf16 v[24:27], v[166:169], v[190:193], v[24:27]
	v_mfma_f32_16x16x32_bf16 v[12:15], v[158:161], v[198:201], v[12:15]
	v_mfma_f32_16x16x32_bf16 v[8:11], v[166:169], v[198:201], v[8:11]
	s_barrier
	s_add_u32 s50, s50, 0x40080
	s_addc_u32 s51, s51, 0
	s_add_i32 s52, s97, s1
	s_mov_b32 m0, s52
	v_lshl_add_u64 v[144:145], s[50:51], 0, v[132:133]
	global_load_lds_dwordx4 v[144:145], off
	s_add_i32 m0, s52, 0x2000
	v_lshl_add_u64 v[144:145], s[50:51], 0, v[128:129]
	global_load_lds_dwordx4 v[144:145], off
	s_waitcnt vmcnt(6)
	s_barrier
	v_mfma_f32_16x16x32_bf16 v[52:55], v[202:205], v[170:173], v[52:55]
	v_mfma_f32_16x16x32_bf16 v[48:51], v[210:213], v[170:173], v[48:51]
	v_mfma_f32_16x16x32_bf16 v[36:39], v[202:205], v[178:181], v[36:39]
	v_mfma_f32_16x16x32_bf16 v[32:35], v[210:213], v[178:181], v[32:35]
	v_mfma_f32_16x16x32_bf16 v[20:23], v[202:205], v[186:189], v[20:23]
	v_mfma_f32_16x16x32_bf16 v[16:19], v[210:213], v[186:189], v[16:19]
	v_mfma_f32_16x16x32_bf16 v[4:7], v[202:205], v[194:197], v[4:7]
	v_mfma_f32_16x16x32_bf16 v[0:3], v[210:213], v[194:197], v[0:3]
	v_mfma_f32_16x16x32_bf16 v[52:55], v[206:209], v[174:177], v[52:55]
	v_mfma_f32_16x16x32_bf16 v[48:51], v[214:217], v[174:177], v[48:51]
	v_mfma_f32_16x16x32_bf16 v[36:39], v[206:209], v[182:185], v[36:39]
	v_mfma_f32_16x16x32_bf16 v[32:35], v[214:217], v[182:185], v[32:35]
	v_mfma_f32_16x16x32_bf16 v[20:23], v[206:209], v[190:193], v[20:23]
	v_mfma_f32_16x16x32_bf16 v[16:19], v[214:217], v[190:193], v[16:19]
	v_mfma_f32_16x16x32_bf16 v[4:7], v[206:209], v[198:201], v[4:7]
	v_mfma_f32_16x16x32_bf16 v[0:3], v[214:217], v[198:201], v[0:3]
	s_add_i32 s66, s66, 2
	s_add_u32 s48, s48, 0x100
	s_addc_u32 s49, s49, 0
	s_add_u32 s64, s64, 0x100
	s_addc_u32 s65, s65, 0
	s_cmp_gt_u32 s66, 13
	s_barrier
	s_cbranch_scc0 .LBB0_603
	v_lshl_add_u32 v146, s46, 8, v150
	v_lshl_or_b32 v144, s61, 8, v152
	v_ashrrev_i32_e32 v147, 31, v146
	v_lshlrev_b64 v[148:149], 12, v[146:147]
	v_ashrrev_i32_e32 v145, 31, v144
	v_lshl_add_u64 v[148:149], s[6:7], 0, v[148:149]
	v_lshlrev_b64 v[144:145], 1, v[144:145]
	v_lshlrev_b64 v[162:163], 11, v[146:147]
	v_lshl_add_u64 v[148:149], v[148:149], 0, v[144:145]
	v_lshl_add_u64 v[162:163], s[14:15], 0, v[162:163]
	global_load_dwordx4 v[158:161], v[148:149], off offset:2048
	v_lshl_add_u64 v[182:183], v[162:163], 0, v[144:145]
	global_load_dwordx4 v[162:165], v[182:183], off
	global_load_dwordx4 v[166:169], v[148:149], off offset:2304
	global_load_dwordx4 v[170:173], v[182:183], off offset:256
	v_or_b32_e32 v148, 16, v146
	v_ashrrev_i32_e32 v149, 31, v148
	v_lshlrev_b64 v[174:175], 12, v[148:149]
	v_lshlrev_b64 v[148:149], 11, v[148:149]
	v_lshl_add_u64 v[148:149], s[14:15], 0, v[148:149]
	v_lshl_add_u64 v[174:175], s[6:7], 0, v[174:175]
	v_lshl_add_u64 v[148:149], v[148:149], 0, v[144:145]
	v_lshl_add_u64 v[184:185], v[174:175], 0, v[144:145]
	global_load_dwordx4 v[174:177], v[148:149], off
	global_load_dwordx4 v[178:181], v[148:149], off offset:256
	s_and_b64 vcc, exec, s[4:5]
	s_mov_b32 s61, s22
	s_mov_b32 s46, s24
	s_mov_b64 s[50:51], s[44:45]
	s_mov_b64 s[48:49], s[40:41]
	s_waitcnt vmcnt(0)
	v_lshlrev_b32_e32 v190, 16, v162
	v_lshlrev_b32_e32 v186, 16, v158
	v_and_b32_e32 v187, 0xffff0000, v158
	v_lshlrev_b32_e32 v158, 16, v159
	v_and_b32_e32 v159, 0xffff0000, v159
	v_lshlrev_b32_e32 v188, 16, v160
	v_and_b32_e32 v189, 0xffff0000, v160
	v_lshlrev_b32_e32 v160, 16, v161
	v_and_b32_e32 v161, 0xffff0000, v161
	v_and_b32_e32 v191, 0xffff0000, v162
	v_lshlrev_b32_e32 v162, 16, v163
	v_and_b32_e32 v163, 0xffff0000, v163
	v_lshlrev_b32_e32 v192, 16, v164
	v_and_b32_e32 v193, 0xffff0000, v164
	v_lshlrev_b32_e32 v164, 16, v165
	v_and_b32_e32 v165, 0xffff0000, v165
	v_lshlrev_b32_e32 v194, 16, v166
	v_and_b32_e32 v195, 0xffff0000, v166
	v_lshlrev_b32_e32 v166, 16, v167
	v_and_b32_e32 v167, 0xffff0000, v167
	v_lshlrev_b32_e32 v196, 16, v168
	v_and_b32_e32 v197, 0xffff0000, v168
	v_lshlrev_b32_e32 v168, 16, v169
	v_and_b32_e32 v169, 0xffff0000, v169
	v_lshlrev_b32_e32 v198, 16, v170
	v_and_b32_e32 v199, 0xffff0000, v170
	v_lshlrev_b32_e32 v170, 16, v171
	v_and_b32_e32 v171, 0xffff0000, v171
	v_lshlrev_b32_e32 v200, 16, v172
	v_and_b32_e32 v201, 0xffff0000, v172
	v_lshlrev_b32_e32 v172, 16, v173
	v_and_b32_e32 v173, 0xffff0000, v173
	v_pk_fma_f32 v[126:127], v[126:127], v[158:159], v[162:163]
	v_pk_fma_f32 v[124:125], v[124:125], v[186:187], v[190:191]
	v_pk_fma_f32 v[122:123], v[122:123], v[160:161], v[164:165]
	v_pk_fma_f32 v[120:121], v[120:121], v[188:189], v[192:193]
	v_pk_fma_f32 v[158:159], v[118:119], v[166:167], v[170:171]
	v_pk_fma_f32 v[160:161], v[116:117], v[194:195], v[198:199]
	v_cvt_pk_bf16_f32 v116, v124, v125
	v_cvt_pk_bf16_f32 v117, v126, v127
	v_cvt_pk_bf16_f32 v118, v120, v121
	v_cvt_pk_bf16_f32 v119, v122, v123
	v_pk_fma_f32 v[120:121], v[114:115], v[168:169], v[172:173]
	v_pk_fma_f32 v[114:115], v[112:113], v[196:197], v[200:201]
	global_store_dwordx4 v[182:183], v[116:119], off
	v_cvt_pk_bf16_f32 v112, v160, v161
	v_cvt_pk_bf16_f32 v113, v158, v159
	v_cvt_pk_bf16_f32 v114, v114, v115
	v_cvt_pk_bf16_f32 v115, v120, v121
	global_load_dwordx4 v[116:119], v[184:185], off offset:2048
	v_lshlrev_b32_e32 v162, 16, v174
	global_store_dwordx4 v[182:183], v[112:115], off offset:256
	global_load_dwordx4 v[120:123], v[184:185], off offset:2304
	v_and_b32_e32 v163, 0xffff0000, v174
	v_or_b32_e32 v112, 32, v146
	v_ashrrev_i32_e32 v113, 31, v112
	v_lshlrev_b64 v[114:115], 12, v[112:113]
	v_lshlrev_b64 v[112:113], 11, v[112:113]
	v_lshlrev_b32_e32 v164, 16, v175
	v_and_b32_e32 v165, 0xffff0000, v175
	v_lshlrev_b32_e32 v166, 16, v176
	v_and_b32_e32 v167, 0xffff0000, v176
	v_lshlrev_b32_e32 v168, 16, v177
	v_and_b32_e32 v169, 0xffff0000, v177
	v_lshlrev_b32_e32 v170, 16, v178
	v_and_b32_e32 v171, 0xffff0000, v178
	v_lshlrev_b32_e32 v172, 16, v179
	v_and_b32_e32 v173, 0xffff0000, v179
	v_lshlrev_b32_e32 v174, 16, v180
	v_and_b32_e32 v175, 0xffff0000, v180
	v_lshlrev_b32_e32 v176, 16, v181
	v_and_b32_e32 v177, 0xffff0000, v181
	v_lshl_add_u64 v[112:113], s[14:15], 0, v[112:113]
	v_lshl_add_u64 v[114:115], s[6:7], 0, v[114:115]
	v_lshl_add_u64 v[112:113], v[112:113], 0, v[144:145]
	v_lshl_add_u64 v[114:115], v[114:115], 0, v[144:145]
	global_load_dwordx4 v[124:127], v[112:113], off
	global_load_dwordx4 v[158:161], v[112:113], off offset:256
	s_waitcnt vmcnt(0)
	v_lshlrev_b32_e32 v178, 16, v116
	v_and_b32_e32 v179, 0xffff0000, v116
	v_lshlrev_b32_e32 v116, 16, v117
	v_and_b32_e32 v117, 0xffff0000, v117
	v_lshlrev_b32_e32 v180, 16, v118
	v_and_b32_e32 v181, 0xffff0000, v118
	v_lshlrev_b32_e32 v118, 16, v119
	v_and_b32_e32 v119, 0xffff0000, v119
	v_lshlrev_b32_e32 v182, 16, v120
	v_and_b32_e32 v183, 0xffff0000, v120
	v_lshlrev_b32_e32 v120, 16, v121
	v_and_b32_e32 v121, 0xffff0000, v121
	v_lshlrev_b32_e32 v184, 16, v122
	v_and_b32_e32 v185, 0xffff0000, v122
	v_lshlrev_b32_e32 v122, 16, v123
	v_and_b32_e32 v123, 0xffff0000, v123
	v_pk_fma_f32 v[110:111], v[110:111], v[116:117], v[164:165]
	v_pk_fma_f32 v[108:109], v[108:109], v[178:179], v[162:163]
	v_pk_fma_f32 v[106:107], v[106:107], v[118:119], v[168:169]
	v_pk_fma_f32 v[104:105], v[104:105], v[180:181], v[166:167]
	v_pk_fma_f32 v[116:117], v[102:103], v[120:121], v[172:173]
	v_pk_fma_f32 v[118:119], v[100:101], v[182:183], v[170:171]
	v_cvt_pk_bf16_f32 v100, v108, v109
	v_cvt_pk_bf16_f32 v101, v110, v111
	v_cvt_pk_bf16_f32 v102, v104, v105
	v_cvt_pk_bf16_f32 v103, v106, v107
	v_pk_fma_f32 v[104:105], v[98:99], v[122:123], v[176:177]
	v_pk_fma_f32 v[98:99], v[96:97], v[184:185], v[174:175]
	global_store_dwordx4 v[148:149], v[100:103], off
	v_cvt_pk_bf16_f32 v96, v118, v119
	v_cvt_pk_bf16_f32 v97, v116, v117
	v_cvt_pk_bf16_f32 v98, v98, v99
	v_cvt_pk_bf16_f32 v99, v104, v105
	global_load_dwordx4 v[100:103], v[114:115], off offset:2048
	v_lshlrev_b32_e32 v118, 16, v124
	global_store_dwordx4 v[148:149], v[96:99], off offset:256
	global_load_dwordx4 v[104:107], v[114:115], off offset:2304
	v_and_b32_e32 v119, 0xffff0000, v124
	v_or_b32_e32 v96, 48, v146
	v_ashrrev_i32_e32 v97, 31, v96
	v_lshlrev_b64 v[98:99], 12, v[96:97]
	v_lshlrev_b64 v[96:97], 11, v[96:97]
	v_lshlrev_b32_e32 v120, 16, v125
	v_and_b32_e32 v121, 0xffff0000, v125
	v_lshlrev_b32_e32 v122, 16, v126
	v_and_b32_e32 v123, 0xffff0000, v126
	v_lshlrev_b32_e32 v124, 16, v127
	v_and_b32_e32 v125, 0xffff0000, v127
	v_lshl_add_u64 v[96:97], s[14:15], 0, v[96:97]
	v_lshlrev_b32_e32 v126, 16, v158
	v_and_b32_e32 v127, 0xffff0000, v158
	v_lshlrev_b32_e32 v148, 16, v159
	v_and_b32_e32 v149, 0xffff0000, v159
	v_lshlrev_b32_e32 v158, 16, v160
	v_and_b32_e32 v159, 0xffff0000, v160
	v_lshlrev_b32_e32 v160, 16, v161
	v_and_b32_e32 v161, 0xffff0000, v161
	v_lshl_add_u64 v[98:99], s[6:7], 0, v[98:99]
	v_lshl_add_u64 v[96:97], v[96:97], 0, v[144:145]
	v_lshl_add_u64 v[98:99], v[98:99], 0, v[144:145]
	global_load_dwordx4 v[108:111], v[96:97], off
	global_load_dwordx4 v[114:117], v[96:97], off offset:256
	s_waitcnt vmcnt(0)
	v_lshlrev_b32_e32 v162, 16, v100
	v_and_b32_e32 v163, 0xffff0000, v100
	v_lshlrev_b32_e32 v100, 16, v101
	v_and_b32_e32 v101, 0xffff0000, v101
	v_lshlrev_b32_e32 v164, 16, v102
	v_and_b32_e32 v165, 0xffff0000, v102
	v_lshlrev_b32_e32 v102, 16, v103
	v_and_b32_e32 v103, 0xffff0000, v103
	v_lshlrev_b32_e32 v166, 16, v104
	v_and_b32_e32 v167, 0xffff0000, v104
	v_lshlrev_b32_e32 v104, 16, v105
	v_and_b32_e32 v105, 0xffff0000, v105
	v_lshlrev_b32_e32 v168, 16, v106
	v_and_b32_e32 v169, 0xffff0000, v106
	v_lshlrev_b32_e32 v106, 16, v107
	v_and_b32_e32 v107, 0xffff0000, v107
	v_pk_fma_f32 v[94:95], v[94:95], v[100:101], v[120:121]
	v_pk_fma_f32 v[92:93], v[92:93], v[162:163], v[118:119]
	v_pk_fma_f32 v[90:91], v[90:91], v[102:103], v[124:125]
	v_pk_fma_f32 v[88:89], v[88:89], v[164:165], v[122:123]
	v_pk_fma_f32 v[100:101], v[86:87], v[104:105], v[148:149]
	v_pk_fma_f32 v[102:103], v[84:85], v[166:167], v[126:127]
	v_cvt_pk_bf16_f32 v84, v92, v93
	v_cvt_pk_bf16_f32 v85, v94, v95
	v_cvt_pk_bf16_f32 v86, v88, v89
	v_cvt_pk_bf16_f32 v87, v90, v91
	v_pk_fma_f32 v[88:89], v[82:83], v[106:107], v[160:161]
	v_pk_fma_f32 v[82:83], v[80:81], v[168:169], v[158:159]
	global_store_dwordx4 v[112:113], v[84:87], off
	v_cvt_pk_bf16_f32 v80, v102, v103
	v_cvt_pk_bf16_f32 v81, v100, v101
	v_cvt_pk_bf16_f32 v82, v82, v83
	v_cvt_pk_bf16_f32 v83, v88, v89
	global_load_dwordx4 v[84:87], v[98:99], off offset:2048
	v_lshlrev_b32_e32 v102, 16, v108
	global_store_dwordx4 v[112:113], v[80:83], off offset:256
	global_load_dwordx4 v[88:91], v[98:99], off offset:2304
	v_and_b32_e32 v103, 0xffff0000, v108
	v_add_u32_e32 v80, 0x80, v146
	v_ashrrev_i32_e32 v81, 31, v80
	v_lshlrev_b64 v[82:83], 12, v[80:81]
	v_lshlrev_b64 v[80:81], 11, v[80:81]
	v_lshlrev_b32_e32 v104, 16, v109
	v_and_b32_e32 v105, 0xffff0000, v109
	v_lshlrev_b32_e32 v106, 16, v110
	v_and_b32_e32 v107, 0xffff0000, v110
	v_lshlrev_b32_e32 v108, 16, v111
	v_and_b32_e32 v109, 0xffff0000, v111
	v_lshl_add_u64 v[80:81], s[14:15], 0, v[80:81]
	v_lshlrev_b32_e32 v110, 16, v114
	v_and_b32_e32 v111, 0xffff0000, v114
	v_lshlrev_b32_e32 v112, 16, v115
	v_and_b32_e32 v113, 0xffff0000, v115
	v_lshlrev_b32_e32 v114, 16, v116
	v_and_b32_e32 v115, 0xffff0000, v116
	v_lshlrev_b32_e32 v116, 16, v117
	v_and_b32_e32 v117, 0xffff0000, v117
	v_lshl_add_u64 v[82:83], s[6:7], 0, v[82:83]
	v_lshl_add_u64 v[80:81], v[80:81], 0, v[144:145]
	v_lshl_add_u64 v[82:83], v[82:83], 0, v[144:145]
	global_load_dwordx4 v[92:95], v[80:81], off
	global_load_dwordx4 v[98:101], v[80:81], off offset:256
	s_waitcnt vmcnt(0)
	v_lshlrev_b32_e32 v118, 16, v84
	v_and_b32_e32 v119, 0xffff0000, v84
	v_lshlrev_b32_e32 v84, 16, v85
	v_and_b32_e32 v85, 0xffff0000, v85
	v_lshlrev_b32_e32 v120, 16, v86
	v_and_b32_e32 v121, 0xffff0000, v86
	v_lshlrev_b32_e32 v86, 16, v87
	v_and_b32_e32 v87, 0xffff0000, v87
	v_lshlrev_b32_e32 v122, 16, v88
	v_and_b32_e32 v123, 0xffff0000, v88
	v_lshlrev_b32_e32 v88, 16, v89
	v_and_b32_e32 v89, 0xffff0000, v89
	v_lshlrev_b32_e32 v124, 16, v90
	v_and_b32_e32 v125, 0xffff0000, v90
	v_lshlrev_b32_e32 v90, 16, v91
	v_and_b32_e32 v91, 0xffff0000, v91
	v_pk_fma_f32 v[78:79], v[78:79], v[84:85], v[104:105]
	v_pk_fma_f32 v[76:77], v[76:77], v[118:119], v[102:103]
	v_pk_fma_f32 v[74:75], v[74:75], v[86:87], v[108:109]
	v_pk_fma_f32 v[72:73], v[72:73], v[120:121], v[106:107]
	v_pk_fma_f32 v[84:85], v[70:71], v[88:89], v[112:113]
	v_pk_fma_f32 v[86:87], v[68:69], v[122:123], v[110:111]
	v_cvt_pk_bf16_f32 v68, v76, v77
	v_cvt_pk_bf16_f32 v69, v78, v79
	v_cvt_pk_bf16_f32 v70, v72, v73
	v_cvt_pk_bf16_f32 v71, v74, v75
	v_pk_fma_f32 v[72:73], v[66:67], v[90:91], v[116:117]
	v_pk_fma_f32 v[66:67], v[64:65], v[124:125], v[114:115]
	global_store_dwordx4 v[96:97], v[68:71], off
	v_cvt_pk_bf16_f32 v64, v86, v87
	v_cvt_pk_bf16_f32 v65, v84, v85
	v_cvt_pk_bf16_f32 v66, v66, v67
	v_cvt_pk_bf16_f32 v67, v72, v73
	global_load_dwordx4 v[68:71], v[82:83], off offset:2048
	v_lshlrev_b32_e32 v86, 16, v92
	global_store_dwordx4 v[96:97], v[64:67], off offset:256
	global_load_dwordx4 v[72:75], v[82:83], off offset:2304
	v_and_b32_e32 v87, 0xffff0000, v92
	v_add_u32_e32 v64, 0x90, v146
	v_ashrrev_i32_e32 v65, 31, v64
	v_lshlrev_b64 v[66:67], 12, v[64:65]
	v_lshlrev_b64 v[64:65], 11, v[64:65]
	v_lshlrev_b32_e32 v88, 16, v93
	v_and_b32_e32 v89, 0xffff0000, v93
	v_lshlrev_b32_e32 v90, 16, v94
	v_and_b32_e32 v91, 0xffff0000, v94
	v_lshlrev_b32_e32 v92, 16, v95
	v_and_b32_e32 v93, 0xffff0000, v95
	v_lshl_add_u64 v[64:65], s[14:15], 0, v[64:65]
	v_lshlrev_b32_e32 v94, 16, v98
	v_and_b32_e32 v95, 0xffff0000, v98
	v_lshlrev_b32_e32 v96, 16, v99
	v_and_b32_e32 v97, 0xffff0000, v99
	v_lshlrev_b32_e32 v98, 16, v100
	v_and_b32_e32 v99, 0xffff0000, v100
	v_lshlrev_b32_e32 v100, 16, v101
	v_and_b32_e32 v101, 0xffff0000, v101
	v_lshl_add_u64 v[66:67], s[6:7], 0, v[66:67]
	v_lshl_add_u64 v[64:65], v[64:65], 0, v[144:145]
	v_lshl_add_u64 v[66:67], v[66:67], 0, v[144:145]
	global_load_dwordx4 v[76:79], v[64:65], off
	global_load_dwordx4 v[82:85], v[64:65], off offset:256
	s_waitcnt vmcnt(0)
	v_lshlrev_b32_e32 v102, 16, v68
	v_and_b32_e32 v103, 0xffff0000, v68
	v_lshlrev_b32_e32 v68, 16, v69
	v_and_b32_e32 v69, 0xffff0000, v69
	v_lshlrev_b32_e32 v104, 16, v70
	v_and_b32_e32 v105, 0xffff0000, v70
	v_lshlrev_b32_e32 v70, 16, v71
	v_and_b32_e32 v71, 0xffff0000, v71
	v_lshlrev_b32_e32 v106, 16, v72
	v_and_b32_e32 v107, 0xffff0000, v72
	v_lshlrev_b32_e32 v72, 16, v73
	v_and_b32_e32 v73, 0xffff0000, v73
	v_lshlrev_b32_e32 v108, 16, v74
	v_and_b32_e32 v109, 0xffff0000, v74
	v_lshlrev_b32_e32 v74, 16, v75
	v_and_b32_e32 v75, 0xffff0000, v75
	v_pk_fma_f32 v[62:63], v[62:63], v[68:69], v[88:89]
	v_pk_fma_f32 v[60:61], v[60:61], v[102:103], v[86:87]
	v_pk_fma_f32 v[58:59], v[58:59], v[70:71], v[92:93]
	v_pk_fma_f32 v[56:57], v[56:57], v[104:105], v[90:91]
	v_pk_fma_f32 v[68:69], v[54:55], v[72:73], v[96:97]
	v_pk_fma_f32 v[70:71], v[52:53], v[106:107], v[94:95]
	v_cvt_pk_bf16_f32 v52, v60, v61
	v_cvt_pk_bf16_f32 v53, v62, v63
	v_cvt_pk_bf16_f32 v54, v56, v57
	v_cvt_pk_bf16_f32 v55, v58, v59
	v_pk_fma_f32 v[56:57], v[50:51], v[74:75], v[100:101]
	v_pk_fma_f32 v[50:51], v[48:49], v[108:109], v[98:99]
	global_store_dwordx4 v[80:81], v[52:55], off
	v_cvt_pk_bf16_f32 v48, v70, v71
	v_cvt_pk_bf16_f32 v49, v68, v69
	v_cvt_pk_bf16_f32 v50, v50, v51
	v_cvt_pk_bf16_f32 v51, v56, v57
	global_load_dwordx4 v[52:55], v[66:67], off offset:2048
	v_lshlrev_b32_e32 v70, 16, v76
	global_store_dwordx4 v[80:81], v[48:51], off offset:256
	global_load_dwordx4 v[56:59], v[66:67], off offset:2304
	v_and_b32_e32 v71, 0xffff0000, v76
	v_add_u32_e32 v48, 0xa0, v146
	v_ashrrev_i32_e32 v49, 31, v48
	v_lshlrev_b64 v[50:51], 12, v[48:49]
	v_lshlrev_b64 v[48:49], 11, v[48:49]
	v_lshlrev_b32_e32 v72, 16, v77
	v_and_b32_e32 v73, 0xffff0000, v77
	v_lshlrev_b32_e32 v74, 16, v78
	v_and_b32_e32 v75, 0xffff0000, v78
	v_lshlrev_b32_e32 v76, 16, v79
	v_and_b32_e32 v77, 0xffff0000, v79
	v_lshl_add_u64 v[48:49], s[14:15], 0, v[48:49]
	v_lshlrev_b32_e32 v78, 16, v82
	v_and_b32_e32 v79, 0xffff0000, v82
	v_lshlrev_b32_e32 v80, 16, v83
	v_and_b32_e32 v81, 0xffff0000, v83
	v_lshlrev_b32_e32 v82, 16, v84
	v_and_b32_e32 v83, 0xffff0000, v84
	v_lshlrev_b32_e32 v84, 16, v85
	v_and_b32_e32 v85, 0xffff0000, v85
	v_lshl_add_u64 v[50:51], s[6:7], 0, v[50:51]
	v_lshl_add_u64 v[48:49], v[48:49], 0, v[144:145]
	v_lshl_add_u64 v[50:51], v[50:51], 0, v[144:145]
	global_load_dwordx4 v[60:63], v[48:49], off
	global_load_dwordx4 v[66:69], v[48:49], off offset:256
	s_waitcnt vmcnt(0)
	v_lshlrev_b32_e32 v86, 16, v52
	v_and_b32_e32 v87, 0xffff0000, v52
	v_lshlrev_b32_e32 v52, 16, v53
	v_and_b32_e32 v53, 0xffff0000, v53
	v_lshlrev_b32_e32 v88, 16, v54
	v_and_b32_e32 v89, 0xffff0000, v54
	v_lshlrev_b32_e32 v54, 16, v55
	v_and_b32_e32 v55, 0xffff0000, v55
	v_lshlrev_b32_e32 v90, 16, v56
	v_and_b32_e32 v91, 0xffff0000, v56
	v_lshlrev_b32_e32 v56, 16, v57
	v_and_b32_e32 v57, 0xffff0000, v57
	v_lshlrev_b32_e32 v92, 16, v58
	v_and_b32_e32 v93, 0xffff0000, v58
	v_lshlrev_b32_e32 v58, 16, v59
	v_and_b32_e32 v59, 0xffff0000, v59
	v_pk_fma_f32 v[46:47], v[46:47], v[52:53], v[72:73]
	v_pk_fma_f32 v[44:45], v[44:45], v[86:87], v[70:71]
	v_pk_fma_f32 v[42:43], v[42:43], v[54:55], v[76:77]
	v_pk_fma_f32 v[40:41], v[40:41], v[88:89], v[74:75]
	v_pk_fma_f32 v[52:53], v[38:39], v[56:57], v[80:81]
	v_pk_fma_f32 v[54:55], v[36:37], v[90:91], v[78:79]
	v_cvt_pk_bf16_f32 v36, v44, v45
	v_cvt_pk_bf16_f32 v37, v46, v47
	v_cvt_pk_bf16_f32 v38, v40, v41
	v_cvt_pk_bf16_f32 v39, v42, v43
	v_pk_fma_f32 v[40:41], v[34:35], v[58:59], v[84:85]
	v_pk_fma_f32 v[34:35], v[32:33], v[92:93], v[82:83]
	global_store_dwordx4 v[64:65], v[36:39], off
	v_cvt_pk_bf16_f32 v32, v54, v55
	v_cvt_pk_bf16_f32 v33, v52, v53
	v_cvt_pk_bf16_f32 v34, v34, v35
	v_cvt_pk_bf16_f32 v35, v40, v41
	global_load_dwordx4 v[36:39], v[50:51], off offset:2048
	v_add_u32_e32 v40, 0xb0, v146
	global_store_dwordx4 v[64:65], v[32:35], off offset:256
	global_load_dwordx4 v[32:35], v[50:51], off offset:2304
	v_ashrrev_i32_e32 v41, 31, v40
	v_lshlrev_b64 v[42:43], 12, v[40:41]
	v_lshlrev_b64 v[40:41], 11, v[40:41]
	v_lshlrev_b32_e32 v54, 16, v60
	v_and_b32_e32 v55, 0xffff0000, v60
	v_lshlrev_b32_e32 v56, 16, v61
	v_and_b32_e32 v57, 0xffff0000, v61
	v_lshlrev_b32_e32 v58, 16, v62
	v_and_b32_e32 v59, 0xffff0000, v62
	v_lshlrev_b32_e32 v60, 16, v63
	v_and_b32_e32 v61, 0xffff0000, v63
	v_lshl_add_u64 v[40:41], s[14:15], 0, v[40:41]
	v_lshlrev_b32_e32 v62, 16, v66
	v_and_b32_e32 v63, 0xffff0000, v66
	v_lshlrev_b32_e32 v64, 16, v67
	v_and_b32_e32 v65, 0xffff0000, v67
	v_lshlrev_b32_e32 v66, 16, v68
	v_and_b32_e32 v67, 0xffff0000, v68
	v_lshlrev_b32_e32 v68, 16, v69
	v_and_b32_e32 v69, 0xffff0000, v69
	v_lshl_add_u64 v[42:43], s[6:7], 0, v[42:43]
	v_lshl_add_u64 v[52:53], v[40:41], 0, v[144:145]
	v_lshl_add_u64 v[50:51], v[42:43], 0, v[144:145]
	global_load_dwordx4 v[40:43], v[52:53], off
	global_load_dwordx4 v[44:47], v[52:53], off offset:256
	s_waitcnt vmcnt(0)
	v_lshlrev_b32_e32 v70, 16, v36
	v_and_b32_e32 v71, 0xffff0000, v36
	v_lshlrev_b32_e32 v36, 16, v37
	v_and_b32_e32 v37, 0xffff0000, v37
	v_lshlrev_b32_e32 v72, 16, v38
	v_and_b32_e32 v73, 0xffff0000, v38
	v_lshlrev_b32_e32 v38, 16, v39
	v_and_b32_e32 v39, 0xffff0000, v39
	v_lshlrev_b32_e32 v74, 16, v32
	v_and_b32_e32 v75, 0xffff0000, v32
	v_lshlrev_b32_e32 v32, 16, v33
	v_and_b32_e32 v33, 0xffff0000, v33
	v_lshlrev_b32_e32 v76, 16, v34
	v_and_b32_e32 v77, 0xffff0000, v34
	v_lshlrev_b32_e32 v34, 16, v35
	v_and_b32_e32 v35, 0xffff0000, v35
	v_pk_fma_f32 v[30:31], v[30:31], v[36:37], v[56:57]
	v_pk_fma_f32 v[28:29], v[28:29], v[70:71], v[54:55]
	v_pk_fma_f32 v[26:27], v[26:27], v[38:39], v[60:61]
	v_pk_fma_f32 v[24:25], v[24:25], v[72:73], v[58:59]
	v_pk_fma_f32 v[32:33], v[22:23], v[32:33], v[64:65]
	v_pk_fma_f32 v[36:37], v[20:21], v[74:75], v[62:63]
	v_cvt_pk_bf16_f32 v20, v28, v29
	v_cvt_pk_bf16_f32 v21, v30, v31
	v_cvt_pk_bf16_f32 v22, v24, v25
	v_cvt_pk_bf16_f32 v23, v26, v27
	v_pk_fma_f32 v[24:25], v[18:19], v[34:35], v[68:69]
	v_pk_fma_f32 v[18:19], v[16:17], v[76:77], v[66:67]
	global_store_dwordx4 v[48:49], v[20:23], off
	v_cvt_pk_bf16_f32 v16, v36, v37
	v_cvt_pk_bf16_f32 v17, v32, v33
	v_cvt_pk_bf16_f32 v18, v18, v19
	v_cvt_pk_bf16_f32 v19, v24, v25
	global_load_dwordx4 v[20:23], v[50:51], off offset:2048
	v_lshlrev_b32_e32 v24, 16, v40
	global_store_dwordx4 v[48:49], v[16:19], off offset:256
	global_load_dwordx4 v[16:19], v[50:51], off offset:2304
	v_and_b32_e32 v25, 0xffff0000, v40
	v_lshlrev_b32_e32 v26, 16, v41
	v_and_b32_e32 v27, 0xffff0000, v41
	v_lshlrev_b32_e32 v28, 16, v42
	v_and_b32_e32 v29, 0xffff0000, v42
	v_lshlrev_b32_e32 v30, 16, v43
	v_and_b32_e32 v31, 0xffff0000, v43
	v_lshlrev_b32_e32 v32, 16, v44
	v_and_b32_e32 v33, 0xffff0000, v44
	v_lshlrev_b32_e32 v34, 16, v45
	v_and_b32_e32 v35, 0xffff0000, v45
	v_lshlrev_b32_e32 v36, 16, v46
	v_and_b32_e32 v37, 0xffff0000, v46
	v_lshlrev_b32_e32 v38, 16, v47
	v_and_b32_e32 v39, 0xffff0000, v47
	s_waitcnt vmcnt(0)
	v_lshlrev_b32_e32 v40, 16, v20
	v_and_b32_e32 v41, 0xffff0000, v20
	v_lshlrev_b32_e32 v20, 16, v21
	v_and_b32_e32 v21, 0xffff0000, v21
	v_lshlrev_b32_e32 v42, 16, v22
	v_and_b32_e32 v43, 0xffff0000, v22
	v_lshlrev_b32_e32 v22, 16, v23
	v_and_b32_e32 v23, 0xffff0000, v23
	v_lshlrev_b32_e32 v44, 16, v16
	v_and_b32_e32 v45, 0xffff0000, v16
	v_lshlrev_b32_e32 v16, 16, v17
	v_and_b32_e32 v17, 0xffff0000, v17
	v_lshlrev_b32_e32 v46, 16, v18
	v_and_b32_e32 v47, 0xffff0000, v18
	v_lshlrev_b32_e32 v18, 16, v19
	v_and_b32_e32 v19, 0xffff0000, v19
	v_pk_fma_f32 v[14:15], v[14:15], v[20:21], v[26:27]
	v_pk_fma_f32 v[12:13], v[12:13], v[40:41], v[24:25]
	v_pk_fma_f32 v[10:11], v[10:11], v[22:23], v[30:31]
	v_pk_fma_f32 v[8:9], v[8:9], v[42:43], v[28:29]
	v_pk_fma_f32 v[6:7], v[6:7], v[16:17], v[34:35]
	v_pk_fma_f32 v[4:5], v[4:5], v[44:45], v[32:33]
	v_pk_fma_f32 v[16:17], v[2:3], v[18:19], v[38:39]
	v_pk_fma_f32 v[18:19], v[0:1], v[46:47], v[36:37]
	v_cvt_pk_bf16_f32 v0, v12, v13
	v_cvt_pk_bf16_f32 v1, v14, v15
	v_cvt_pk_bf16_f32 v2, v8, v9
	v_cvt_pk_bf16_f32 v3, v10, v11
	v_cvt_pk_bf16_f32 v4, v4, v5
	v_cvt_pk_bf16_f32 v5, v6, v7
	v_cvt_pk_bf16_f32 v6, v18, v19
	v_cvt_pk_bf16_f32 v7, v16, v17
	global_store_dwordx4 v[52:53], v[0:3], off
	global_store_dwordx4 v[52:53], v[4:7], off offset:256
	s_cbranch_vccz .LBB0_600
	s_waitcnt vmcnt(0)
	s_cmpk_gt_u32 s0, 0xff
	s_cbranch_scc1 .LBB0_607
	s_barrier

.LBB0_628:
	ds_read_b128 v[146:149], v159
	ds_read_b128 v[150:153], v159 offset:1024
	ds_read_b128 v[164:167], v159 offset:2048
	ds_read_b128 v[168:171], v159 offset:3072
	s_add_u32 s52, s50, 0xfffc0080
	s_addc_u32 s53, s51, -1
	s_cmp_eq_u32 s71, 12
	s_cselect_b32 s55, s25, s53
	s_cselect_b32 s54, s47, s52
	s_cselect_b32 s53, s23, s70
	s_cselect_b32 s52, s49, s69
	v_lshl_add_u64 v[204:205], s[50:51], 0, v[138:139]
	s_add_i32 m0, s33, 0xc000
	ds_read_b128 v[172:175], v160
	ds_read_b128 v[176:179], v160 offset:1024
	ds_read_b128 v[180:183], v160 offset:2048
	ds_read_b128 v[184:187], v160 offset:3072
	ds_read_b128 v[188:191], v160 offset:4096
	ds_read_b128 v[192:195], v160 offset:5120
	ds_read_b128 v[196:199], v160 offset:6144
	ds_read_b128 v[200:203], v160 offset:7168
	global_load_lds_dwordx4 v[204:205], off
	s_add_i32 m0, s33, 0xe000
	v_lshl_add_u64 v[204:205], s[50:51], 0, v[140:141]
	global_load_lds_dwordx4 v[204:205], off
	s_waitcnt lgkmcnt(8)
	s_barrier
	s_waitcnt lgkmcnt(0)
	s_waitcnt lgkmcnt(0)
	v_mfma_f32_16x16x32_bf16 v[124:127], v[146:149], v[172:175], v[124:127]
	v_mfma_f32_16x16x32_bf16 v[120:123], v[164:167], v[172:175], v[120:123]
	v_mfma_f32_16x16x32_bf16 v[108:111], v[146:149], v[180:183], v[108:111]
	v_mfma_f32_16x16x32_bf16 v[104:107], v[164:167], v[180:183], v[104:107]
	v_mfma_f32_16x16x32_bf16 v[92:95], v[146:149], v[188:191], v[92:95]
	v_mfma_f32_16x16x32_bf16 v[88:91], v[164:167], v[188:191], v[88:91]
	v_mfma_f32_16x16x32_bf16 v[76:79], v[146:149], v[196:199], v[76:79]
	v_mfma_f32_16x16x32_bf16 v[72:75], v[164:167], v[196:199], v[72:75]
	v_mfma_f32_16x16x32_bf16 v[124:127], v[150:153], v[176:179], v[124:127]
	v_mfma_f32_16x16x32_bf16 v[120:123], v[168:171], v[176:179], v[120:123]
	v_mfma_f32_16x16x32_bf16 v[108:111], v[150:153], v[184:187], v[108:111]
	v_mfma_f32_16x16x32_bf16 v[104:107], v[168:171], v[184:187], v[104:107]
	v_mfma_f32_16x16x32_bf16 v[92:95], v[150:153], v[192:195], v[92:95]
	v_mfma_f32_16x16x32_bf16 v[88:91], v[168:171], v[192:195], v[88:91]
	v_mfma_f32_16x16x32_bf16 v[76:79], v[150:153], v[200:203], v[76:79]
	v_mfma_f32_16x16x32_bf16 v[72:75], v[168:171], v[200:203], v[72:75]
	s_barrier
	s_add_i32 s73, s63, s1
	v_lshl_add_u64 v[220:221], s[52:53], 0, v[130:131]
	s_mov_b32 m0, s73
	ds_read_b128 v[204:207], v161
	ds_read_b128 v[208:211], v161 offset:1024
	ds_read_b128 v[212:215], v161 offset:2048
	ds_read_b128 v[216:219], v161 offset:3072
	global_load_lds_dwordx4 v[220:221], off
	s_add_i32 m0, s73, 0x2000
	v_lshl_add_u64 v[222:223], s[52:53], 0, v[134:135]
	global_load_lds_dwordx4 v[222:223], off
	s_barrier
	s_waitcnt lgkmcnt(0)
	s_waitcnt lgkmcnt(0)
	v_mfma_f32_16x16x32_bf16 v[116:119], v[204:207], v[172:175], v[116:119]
	v_mfma_f32_16x16x32_bf16 v[112:115], v[212:215], v[172:175], v[112:115]
	v_mfma_f32_16x16x32_bf16 v[100:103], v[204:207], v[180:183], v[100:103]
	v_mfma_f32_16x16x32_bf16 v[96:99], v[212:215], v[180:183], v[96:99]
	v_mfma_f32_16x16x32_bf16 v[84:87], v[204:207], v[188:191], v[84:87]
	v_mfma_f32_16x16x32_bf16 v[80:83], v[212:215], v[188:191], v[80:83]
	v_mfma_f32_16x16x32_bf16 v[68:71], v[204:207], v[196:199], v[68:71]
	v_mfma_f32_16x16x32_bf16 v[64:67], v[212:215], v[196:199], v[64:67]
	v_mfma_f32_16x16x32_bf16 v[116:119], v[208:211], v[176:179], v[116:119]
	v_mfma_f32_16x16x32_bf16 v[112:115], v[216:219], v[176:179], v[112:115]
	v_mfma_f32_16x16x32_bf16 v[100:103], v[208:211], v[184:187], v[100:103]
	v_mfma_f32_16x16x32_bf16 v[96:99], v[216:219], v[184:187], v[96:99]
	v_mfma_f32_16x16x32_bf16 v[84:87], v[208:211], v[192:195], v[84:87]
	v_mfma_f32_16x16x32_bf16 v[80:83], v[216:219], v[192:195], v[80:83]
	v_mfma_f32_16x16x32_bf16 v[68:71], v[208:211], v[200:203], v[68:71]
	v_mfma_f32_16x16x32_bf16 v[64:67], v[216:219], v[200:203], v[64:67]
	s_mov_b32 m0, s33
	v_lshl_add_u64 v[224:225], s[54:55], 0, v[128:129]
	s_barrier
	ds_read_b128 v[172:175], v160 offset:16384
	ds_read_b128 v[176:179], v160 offset:17408
	ds_read_b128 v[180:183], v160 offset:18432
	ds_read_b128 v[184:187], v160 offset:19456
	ds_read_b128 v[188:191], v160 offset:20480
	ds_read_b128 v[192:195], v160 offset:21504
	ds_read_b128 v[196:199], v160 offset:22528
	ds_read_b128 v[200:203], v160 offset:23552
	global_load_lds_dwordx4 v[224:225], off
	s_mov_b32 m0, s34
	v_lshl_add_u64 v[226:227], s[54:55], 0, v[132:133]
	global_load_lds_dwordx4 v[226:227], off
	s_barrier
	s_waitcnt lgkmcnt(0)
	s_waitcnt lgkmcnt(0)
	v_mfma_f32_16x16x32_bf16 v[60:63], v[146:149], v[172:175], v[60:63]
	v_mfma_f32_16x16x32_bf16 v[56:59], v[164:167], v[172:175], v[56:59]
	v_mfma_f32_16x16x32_bf16 v[44:47], v[146:149], v[180:183], v[44:47]
	v_mfma_f32_16x16x32_bf16 v[40:43], v[164:167], v[180:183], v[40:43]
	v_mfma_f32_16x16x32_bf16 v[28:31], v[146:149], v[188:191], v[28:31]
	v_mfma_f32_16x16x32_bf16 v[24:27], v[164:167], v[188:191], v[24:27]
	v_mfma_f32_16x16x32_bf16 v[12:15], v[146:149], v[196:199], v[12:15]
	v_mfma_f32_16x16x32_bf16 v[8:11], v[164:167], v[196:199], v[8:11]
	v_mfma_f32_16x16x32_bf16 v[60:63], v[150:153], v[176:179], v[60:63]
	v_mfma_f32_16x16x32_bf16 v[56:59], v[168:171], v[176:179], v[56:59]
	v_mfma_f32_16x16x32_bf16 v[44:47], v[150:153], v[184:187], v[44:47]
	v_mfma_f32_16x16x32_bf16 v[40:43], v[168:171], v[184:187], v[40:43]
	v_mfma_f32_16x16x32_bf16 v[28:31], v[150:153], v[192:195], v[28:31]
	v_mfma_f32_16x16x32_bf16 v[24:27], v[168:171], v[192:195], v[24:27]
	v_mfma_f32_16x16x32_bf16 v[12:15], v[150:153], v[200:203], v[12:15]
	v_mfma_f32_16x16x32_bf16 v[8:11], v[168:171], v[200:203], v[8:11]
	s_barrier
	s_add_u32 s74, s52, 0x40000
	s_addc_u32 s75, s53, 0
	s_add_i32 s73, s72, s1
	s_mov_b32 m0, s73
	v_lshl_add_u64 v[146:147], s[74:75], 0, v[130:131]
	global_load_lds_dwordx4 v[146:147], off
	s_add_i32 m0, s73, 0x2000
	v_lshl_add_u64 v[146:147], s[74:75], 0, v[134:135]
	global_load_lds_dwordx4 v[146:147], off
	s_waitcnt vmcnt(6)
	s_barrier
	v_mfma_f32_16x16x32_bf16 v[52:55], v[204:207], v[172:175], v[52:55]
	v_mfma_f32_16x16x32_bf16 v[48:51], v[212:215], v[172:175], v[48:51]
	v_mfma_f32_16x16x32_bf16 v[36:39], v[204:207], v[180:183], v[36:39]
	v_mfma_f32_16x16x32_bf16 v[32:35], v[212:215], v[180:183], v[32:35]
	v_mfma_f32_16x16x32_bf16 v[20:23], v[204:207], v[188:191], v[20:23]
	v_mfma_f32_16x16x32_bf16 v[16:19], v[212:215], v[188:191], v[16:19]
	v_mfma_f32_16x16x32_bf16 v[4:7], v[204:207], v[196:199], v[4:7]
	v_mfma_f32_16x16x32_bf16 v[0:3], v[212:215], v[196:199], v[0:3]
	v_mfma_f32_16x16x32_bf16 v[52:55], v[208:211], v[176:179], v[52:55]
	v_mfma_f32_16x16x32_bf16 v[48:51], v[216:219], v[176:179], v[48:51]
	v_mfma_f32_16x16x32_bf16 v[36:39], v[208:211], v[184:187], v[36:39]
	v_mfma_f32_16x16x32_bf16 v[32:35], v[216:219], v[184:187], v[32:35]
	v_mfma_f32_16x16x32_bf16 v[20:23], v[208:211], v[192:195], v[20:23]
	v_mfma_f32_16x16x32_bf16 v[16:19], v[216:219], v[192:195], v[16:19]
	v_mfma_f32_16x16x32_bf16 v[4:7], v[208:211], v[200:203], v[4:7]
	v_mfma_f32_16x16x32_bf16 v[0:3], v[216:219], v[200:203], v[0:3]
	s_add_i32 s73, 0, 0x18000
	v_add_u32_e32 v136, s73, v157
	s_barrier
	ds_read_b128 v[146:149], v136
	ds_read_b128 v[150:153], v136 offset:1024
	ds_read_b128 v[164:167], v136 offset:2048
	ds_read_b128 v[168:171], v136 offset:3072
	s_add_u32 s54, s54, 0x40000
	s_addc_u32 s55, s55, 0
	s_mov_b32 m0, s35
	v_lshl_add_u64 v[204:205], s[54:55], 0, v[128:129]
	ds_read_b128 v[172:175], v160 offset:32768
	ds_read_b128 v[176:179], v160 offset:33792
	ds_read_b128 v[180:183], v160 offset:34816
	ds_read_b128 v[184:187], v160 offset:35840
	ds_read_b128 v[188:191], v160 offset:36864
	ds_read_b128 v[192:195], v160 offset:37888
	ds_read_b128 v[196:199], v160 offset:38912
	ds_read_b128 v[200:203], v160 offset:39936
	global_load_lds_dwordx4 v[204:205], off
	s_mov_b32 m0, s56
	v_lshl_add_u64 v[204:205], s[54:55], 0, v[132:133]
	global_load_lds_dwordx4 v[204:205], off
	s_waitcnt lgkmcnt(8)
	s_barrier
	s_waitcnt lgkmcnt(0)
	s_waitcnt lgkmcnt(0)
	v_mfma_f32_16x16x32_bf16 v[124:127], v[146:149], v[172:175], v[124:127]
	v_mfma_f32_16x16x32_bf16 v[120:123], v[164:167], v[172:175], v[120:123]
	v_mfma_f32_16x16x32_bf16 v[108:111], v[146:149], v[180:183], v[108:111]
	v_mfma_f32_16x16x32_bf16 v[104:107], v[164:167], v[180:183], v[104:107]
	v_mfma_f32_16x16x32_bf16 v[92:95], v[146:149], v[188:191], v[92:95]
	v_mfma_f32_16x16x32_bf16 v[88:91], v[164:167], v[188:191], v[88:91]
	v_mfma_f32_16x16x32_bf16 v[76:79], v[146:149], v[196:199], v[76:79]
	v_mfma_f32_16x16x32_bf16 v[72:75], v[164:167], v[196:199], v[72:75]
	v_mfma_f32_16x16x32_bf16 v[124:127], v[150:153], v[176:179], v[124:127]
	v_mfma_f32_16x16x32_bf16 v[120:123], v[168:171], v[176:179], v[120:123]
	v_mfma_f32_16x16x32_bf16 v[108:111], v[150:153], v[184:187], v[108:111]
	v_mfma_f32_16x16x32_bf16 v[104:107], v[168:171], v[184:187], v[104:107]
	v_mfma_f32_16x16x32_bf16 v[92:95], v[150:153], v[192:195], v[92:95]
	v_mfma_f32_16x16x32_bf16 v[88:91], v[168:171], v[192:195], v[88:91]
	v_mfma_f32_16x16x32_bf16 v[76:79], v[150:153], v[200:203], v[76:79]
	v_mfma_f32_16x16x32_bf16 v[72:75], v[168:171], v[200:203], v[72:75]
	s_barrier
	s_add_i32 s54, s73, s1
	v_add_u32_e32 v136, s97, v157
	v_lshl_add_u64 v[220:221], v[220:221], 0, s[20:21]
	s_mov_b32 m0, s54
	ds_read_b128 v[204:207], v136
	ds_read_b128 v[208:211], v136 offset:1024
	ds_read_b128 v[212:215], v136 offset:2048
	ds_read_b128 v[216:219], v136 offset:3072
	global_load_lds_dwordx4 v[220:221], off
	s_add_i32 m0, s54, 0x2000
	v_lshl_add_u64 v[220:221], v[222:223], 0, s[20:21]
	global_load_lds_dwordx4 v[220:221], off
	s_barrier
	s_waitcnt lgkmcnt(0)
	s_waitcnt lgkmcnt(0)
	v_mfma_f32_16x16x32_bf16 v[116:119], v[204:207], v[172:175], v[116:119]
	v_mfma_f32_16x16x32_bf16 v[112:115], v[212:215], v[172:175], v[112:115]
	v_mfma_f32_16x16x32_bf16 v[100:103], v[204:207], v[180:183], v[100:103]
	v_mfma_f32_16x16x32_bf16 v[96:99], v[212:215], v[180:183], v[96:99]
	v_mfma_f32_16x16x32_bf16 v[84:87], v[204:207], v[188:191], v[84:87]
	v_mfma_f32_16x16x32_bf16 v[80:83], v[212:215], v[188:191], v[80:83]
	v_mfma_f32_16x16x32_bf16 v[68:71], v[204:207], v[196:199], v[68:71]
	v_mfma_f32_16x16x32_bf16 v[64:67], v[212:215], v[196:199], v[64:67]
	v_mfma_f32_16x16x32_bf16 v[116:119], v[208:211], v[176:179], v[116:119]
	v_mfma_f32_16x16x32_bf16 v[112:115], v[216:219], v[176:179], v[112:115]
	v_mfma_f32_16x16x32_bf16 v[100:103], v[208:211], v[184:187], v[100:103]
	v_mfma_f32_16x16x32_bf16 v[96:99], v[216:219], v[184:187], v[96:99]
	v_mfma_f32_16x16x32_bf16 v[84:87], v[208:211], v[192:195], v[84:87]
	v_mfma_f32_16x16x32_bf16 v[80:83], v[216:219], v[192:195], v[80:83]
	v_mfma_f32_16x16x32_bf16 v[68:71], v[208:211], v[200:203], v[68:71]
	v_mfma_f32_16x16x32_bf16 v[64:67], v[216:219], v[200:203], v[64:67]
	s_mov_b32 m0, s58
	v_lshl_add_u64 v[220:221], v[224:225], 0, s[20:21]
	s_barrier
	ds_read_b128 v[172:175], v160 offset:49152
	ds_read_b128 v[176:179], v160 offset:50176
	ds_read_b128 v[180:183], v160 offset:51200
	ds_read_b128 v[184:187], v160 offset:52224
	ds_read_b128 v[188:191], v160 offset:53248
	ds_read_b128 v[192:195], v160 offset:54272
	ds_read_b128 v[196:199], v160 offset:55296
	ds_read_b128 v[200:203], v160 offset:56320
	global_load_lds_dwordx4 v[220:221], off
	s_mov_b32 m0, s59
	v_lshl_add_u64 v[220:221], v[226:227], 0, s[20:21]
	global_load_lds_dwordx4 v[220:221], off
	s_barrier
	s_waitcnt lgkmcnt(0)
	s_waitcnt lgkmcnt(0)
	v_mfma_f32_16x16x32_bf16 v[60:63], v[146:149], v[172:175], v[60:63]
	v_mfma_f32_16x16x32_bf16 v[56:59], v[164:167], v[172:175], v[56:59]
	v_mfma_f32_16x16x32_bf16 v[44:47], v[146:149], v[180:183], v[44:47]
	v_mfma_f32_16x16x32_bf16 v[40:43], v[164:167], v[180:183], v[40:43]
	v_mfma_f32_16x16x32_bf16 v[28:31], v[146:149], v[188:191], v[28:31]
	v_mfma_f32_16x16x32_bf16 v[24:27], v[164:167], v[188:191], v[24:27]
	v_mfma_f32_16x16x32_bf16 v[12:15], v[146:149], v[196:199], v[12:15]
	v_mfma_f32_16x16x32_bf16 v[8:11], v[164:167], v[196:199], v[8:11]
	v_mfma_f32_16x16x32_bf16 v[60:63], v[150:153], v[176:179], v[60:63]
	v_mfma_f32_16x16x32_bf16 v[56:59], v[168:171], v[176:179], v[56:59]
	v_mfma_f32_16x16x32_bf16 v[44:47], v[150:153], v[184:187], v[44:47]
	v_mfma_f32_16x16x32_bf16 v[40:43], v[168:171], v[184:187], v[40:43]
	v_mfma_f32_16x16x32_bf16 v[28:31], v[150:153], v[192:195], v[28:31]
	v_mfma_f32_16x16x32_bf16 v[24:27], v[168:171], v[192:195], v[24:27]
	v_mfma_f32_16x16x32_bf16 v[12:15], v[150:153], v[200:203], v[12:15]
	v_mfma_f32_16x16x32_bf16 v[8:11], v[168:171], v[200:203], v[8:11]
	s_barrier
	s_add_u32 s52, s52, 0x40080
	s_addc_u32 s53, s53, 0
	s_add_i32 s54, s97, s1
	s_mov_b32 m0, s54
	v_lshl_add_u64 v[146:147], s[52:53], 0, v[130:131]
	global_load_lds_dwordx4 v[146:147], off
	s_add_i32 m0, s54, 0x2000
	v_lshl_add_u64 v[146:147], s[52:53], 0, v[134:135]
	global_load_lds_dwordx4 v[146:147], off
	s_waitcnt vmcnt(6)
	s_barrier
	v_mfma_f32_16x16x32_bf16 v[52:55], v[204:207], v[172:175], v[52:55]
	v_mfma_f32_16x16x32_bf16 v[48:51], v[212:215], v[172:175], v[48:51]
	v_mfma_f32_16x16x32_bf16 v[36:39], v[204:207], v[180:183], v[36:39]
	v_mfma_f32_16x16x32_bf16 v[32:35], v[212:215], v[180:183], v[32:35]
	v_mfma_f32_16x16x32_bf16 v[20:23], v[204:207], v[188:191], v[20:23]
	v_mfma_f32_16x16x32_bf16 v[16:19], v[212:215], v[188:191], v[16:19]
	v_mfma_f32_16x16x32_bf16 v[4:7], v[204:207], v[196:199], v[4:7]
	v_mfma_f32_16x16x32_bf16 v[0:3], v[212:215], v[196:199], v[0:3]
	v_mfma_f32_16x16x32_bf16 v[52:55], v[208:211], v[176:179], v[52:55]
	v_mfma_f32_16x16x32_bf16 v[48:51], v[216:219], v[176:179], v[48:51]
	v_mfma_f32_16x16x32_bf16 v[36:39], v[208:211], v[184:187], v[36:39]
	v_mfma_f32_16x16x32_bf16 v[32:35], v[216:219], v[184:187], v[32:35]
	v_mfma_f32_16x16x32_bf16 v[20:23], v[208:211], v[192:195], v[20:23]
	v_mfma_f32_16x16x32_bf16 v[16:19], v[216:219], v[192:195], v[16:19]
	v_mfma_f32_16x16x32_bf16 v[4:7], v[208:211], v[200:203], v[4:7]
	v_mfma_f32_16x16x32_bf16 v[0:3], v[216:219], v[200:203], v[0:3]
	s_add_i32 s71, s71, 2
	s_add_u32 s50, s50, 0x100
	s_addc_u32 s51, s51, 0
	s_add_u32 s69, s69, 0x100
	s_addc_u32 s70, s70, 0
	s_cmp_gt_u32 s71, 13
	s_barrier
	s_cbranch_scc0 .LBB0_628
	v_lshl_add_u32 v150, s48, 8, v156
	v_cmp_lt_i32_e32 vcc, s64, v150
	s_and_saveexec_b64 s[48:49], vcc
	s_xor_b64 s[48:49], exec, s[48:49]
	v_add_u32_e32 v136, 0xffff0000, v150
	v_lshlrev_b64 v[146:147], 12, v[136:137]
	v_lshl_add_u64 v[152:153], s[38:39], 0, v[146:147]
	v_mov_b32_e32 v151, v137
	s_andn2_saveexec_b64 s[48:49], s[48:49]
	v_ashrrev_i32_e32 v151, 31, v150
	v_lshlrev_b64 v[146:147], 12, v[150:151]
	v_lshl_add_u64 v[152:153], s[36:37], 0, v[146:147]
	s_or_b64 exec, exec, s[48:49]
	v_lshl_or_b32 v146, s46, 8, v158
	v_ashrrev_i32_e32 v147, 31, v146
	v_lshlrev_b64 v[148:149], 2, v[146:147]
	v_lshl_add_u64 v[152:153], v[152:153], 0, v[148:149]
	global_load_dwordx4 v[164:167], v[152:153], off
	global_load_dwordx4 v[168:171], v[152:153], off offset:16
	v_lshlrev_b64 v[172:173], 12, v[150:151]
	v_lshlrev_b64 v[174:175], 11, v[150:151]
	v_lshl_add_u64 v[172:173], s[42:43], 0, v[172:173]
	v_lshl_add_u64 v[174:175], s[84:85], 0, v[174:175]
	v_lshl_add_u64 v[176:177], v[146:147], 1, v[174:175]
	v_lshl_add_u64 v[178:179], v[172:173], 0, v[148:149]
	s_waitcnt vmcnt(0)
	v_pk_add_f32 v[126:127], v[126:127], v[166:167]
	v_pk_add_f32 v[124:125], v[124:125], v[164:165]
	v_pk_add_f32 v[166:167], v[122:123], v[170:171]
	v_pk_add_f32 v[164:165], v[120:121], v[168:169]
	v_cvt_pk_bf16_f32 v120, v124, v125
	v_cvt_pk_bf16_f32 v121, v126, v127
	v_cvt_pk_bf16_f32 v122, v164, v165
	v_cvt_pk_bf16_f32 v123, v166, v167
	global_store_dwordx4 v[178:179], v[124:127], off
	global_store_dwordx4 v[178:179], v[164:167], off offset:16
	global_store_dwordx4 v[176:177], v[120:123], off
	global_load_dwordx4 v[168:171], v[152:153], off offset:512
	global_load_dwordx4 v[172:175], v[152:153], off offset:528
	v_and_b32_e32 v121, 64, v162
	v_xor_b32_e32 v120, 16, v162
	v_add_u32_e32 v121, 64, v121
	v_xor_b32_e32 v122, 32, v162
	v_cmp_lt_i32_e32 vcc, v120, v121
	v_mul_f32_e32 v123, v165, v165
	v_mul_f32_e32 v136, v166, v166
	v_cndmask_b32_e32 v120, v162, v120, vcc
	v_cmp_lt_i32_e32 vcc, v122, v121
	v_fmac_f32_e32 v123, v125, v125
	v_mul_f32_e32 v152, v167, v167
	v_cndmask_b32_e32 v121, v162, v122, vcc
	v_mul_f32_e32 v122, v164, v164
	v_fmac_f32_e32 v122, v124, v124
	v_fmac_f32_e32 v136, v126, v126
	v_add_f32_e32 v122, v122, v123
	v_fmac_f32_e32 v152, v127, v127
	v_add_f32_e32 v122, v136, v122
	v_add_f32_e32 v126, v152, v122
	v_lshlrev_b32_e32 v120, 2, v120
	s_waitcnt vmcnt(0)
	v_pk_add_f32 v[122:123], v[116:117], v[168:169]
	v_pk_add_f32 v[164:165], v[112:113], v[172:173]
	v_pk_add_f32 v[166:167], v[114:115], v[174:175]
	v_mul_f32_e32 v112, v164, v164
	v_mul_f32_e32 v113, v165, v165
	v_fmac_f32_e32 v112, v122, v122
	v_pk_add_f32 v[124:125], v[118:119], v[170:171]
	v_mul_f32_e32 v114, v166, v166
	v_fmac_f32_e32 v113, v123, v123
	v_add_f32_e32 v112, v126, v112
	v_mul_f32_e32 v115, v167, v167
	v_fmac_f32_e32 v114, v124, v124
	v_add_f32_e32 v112, v113, v112
	v_add_f32_e32 v112, v114, v112
	v_fmac_f32_e32 v115, v125, v125
	v_add_f32_e32 v112, v115, v112
	ds_bpermute_b32 v113, v120, v112
	v_lshlrev_b32_e32 v116, 2, v121
	global_store_dwordx4 v[178:179], v[122:125], off offset:512
	global_store_dwordx4 v[178:179], v[164:167], off offset:528
	s_waitcnt lgkmcnt(0)
	v_add_f32_e32 v112, v112, v113
	ds_bpermute_b32 v113, v116, v112
	v_cvt_pk_bf16_f32 v122, v122, v123
	v_cvt_pk_bf16_f32 v123, v124, v125
	v_cvt_pk_bf16_f32 v124, v164, v165
	v_cvt_pk_bf16_f32 v125, v166, v167
	global_store_dwordx4 v[176:177], v[122:125], off offset:256
	s_and_saveexec_b64 s[46:47], s[4:5]
	s_cbranch_execz .LBB0_635
	v_lshl_add_u64 v[114:115], v[150:151], 2, s[18:19]
	s_waitcnt lgkmcnt(0)
	v_add_f32_e32 v112, v112, v113
	global_atomic_add_f32 v[114:115], v112, off

.LBB0_697:
	ds_read_b128 v[144:147], v157
	ds_read_b128 v[148:151], v157 offset:1024
	ds_read_b128 v[162:165], v157 offset:2048
	ds_read_b128 v[166:169], v157 offset:3072
	s_add_u32 s48, s6, 0xfffc0080
	s_addc_u32 s49, s7, -1
	s_cmp_eq_u32 s71, 12
	s_cselect_b32 s51, s39, s49
	s_cselect_b32 s50, s67, s48
	s_cselect_b32 s49, s37, s70
	s_cselect_b32 s48, s68, s69
	v_lshl_add_u64 v[202:203], s[6:7], 0, v[136:137]
	s_add_i32 m0, s47, 0xc000
	ds_read_b128 v[170:173], v158
	ds_read_b128 v[174:177], v158 offset:1024
	ds_read_b128 v[178:181], v158 offset:2048
	ds_read_b128 v[182:185], v158 offset:3072
	ds_read_b128 v[186:189], v158 offset:4096
	ds_read_b128 v[190:193], v158 offset:5120
	ds_read_b128 v[194:197], v158 offset:6144
	ds_read_b128 v[198:201], v158 offset:7168
	global_load_lds_dwordx4 v[202:203], off
	s_add_i32 m0, s47, 0xe000
	v_lshl_add_u64 v[202:203], s[6:7], 0, v[138:139]
	global_load_lds_dwordx4 v[202:203], off
	s_waitcnt lgkmcnt(8)
	s_barrier
	s_waitcnt lgkmcnt(0)
	s_waitcnt lgkmcnt(0)
	v_mfma_f32_16x16x32_bf16 v[124:127], v[144:147], v[170:173], v[124:127]
	v_mfma_f32_16x16x32_bf16 v[120:123], v[162:165], v[170:173], v[120:123]
	v_mfma_f32_16x16x32_bf16 v[108:111], v[144:147], v[178:181], v[108:111]
	v_mfma_f32_16x16x32_bf16 v[104:107], v[162:165], v[178:181], v[104:107]
	v_mfma_f32_16x16x32_bf16 v[92:95], v[144:147], v[186:189], v[92:95]
	v_mfma_f32_16x16x32_bf16 v[88:91], v[162:165], v[186:189], v[88:91]
	v_mfma_f32_16x16x32_bf16 v[76:79], v[144:147], v[194:197], v[76:79]
	v_mfma_f32_16x16x32_bf16 v[72:75], v[162:165], v[194:197], v[72:75]
	v_mfma_f32_16x16x32_bf16 v[124:127], v[148:151], v[174:177], v[124:127]
	v_mfma_f32_16x16x32_bf16 v[120:123], v[166:169], v[174:177], v[120:123]
	v_mfma_f32_16x16x32_bf16 v[108:111], v[148:151], v[182:185], v[108:111]
	v_mfma_f32_16x16x32_bf16 v[104:107], v[166:169], v[182:185], v[104:107]
	v_mfma_f32_16x16x32_bf16 v[92:95], v[148:151], v[190:193], v[92:95]
	v_mfma_f32_16x16x32_bf16 v[88:91], v[166:169], v[190:193], v[88:91]
	v_mfma_f32_16x16x32_bf16 v[76:79], v[148:151], v[198:201], v[76:79]
	v_mfma_f32_16x16x32_bf16 v[72:75], v[166:169], v[198:201], v[72:75]
	s_barrier
	s_add_i32 s73, s60, s34
	v_lshl_add_u64 v[218:219], s[48:49], 0, v[132:133]
	s_mov_b32 m0, s73
	ds_read_b128 v[202:205], v159
	ds_read_b128 v[206:209], v159 offset:1024
	ds_read_b128 v[210:213], v159 offset:2048
	ds_read_b128 v[214:217], v159 offset:3072
	global_load_lds_dwordx4 v[218:219], off
	s_add_i32 m0, s73, 0x2000
	v_lshl_add_u64 v[220:221], s[48:49], 0, v[128:129]
	global_load_lds_dwordx4 v[220:221], off
	s_barrier
	s_waitcnt lgkmcnt(0)
	s_waitcnt lgkmcnt(0)
	v_mfma_f32_16x16x32_bf16 v[116:119], v[202:205], v[170:173], v[116:119]
	v_mfma_f32_16x16x32_bf16 v[112:115], v[210:213], v[170:173], v[112:115]
	v_mfma_f32_16x16x32_bf16 v[100:103], v[202:205], v[178:181], v[100:103]
	v_mfma_f32_16x16x32_bf16 v[96:99], v[210:213], v[178:181], v[96:99]
	v_mfma_f32_16x16x32_bf16 v[84:87], v[202:205], v[186:189], v[84:87]
	v_mfma_f32_16x16x32_bf16 v[80:83], v[210:213], v[186:189], v[80:83]
	v_mfma_f32_16x16x32_bf16 v[68:71], v[202:205], v[194:197], v[68:71]
	v_mfma_f32_16x16x32_bf16 v[64:67], v[210:213], v[194:197], v[64:67]
	v_mfma_f32_16x16x32_bf16 v[116:119], v[206:209], v[174:177], v[116:119]
	v_mfma_f32_16x16x32_bf16 v[112:115], v[214:217], v[174:177], v[112:115]
	v_mfma_f32_16x16x32_bf16 v[100:103], v[206:209], v[182:185], v[100:103]
	v_mfma_f32_16x16x32_bf16 v[96:99], v[214:217], v[182:185], v[96:99]
	v_mfma_f32_16x16x32_bf16 v[84:87], v[206:209], v[190:193], v[84:87]
	v_mfma_f32_16x16x32_bf16 v[80:83], v[214:217], v[190:193], v[80:83]
	v_mfma_f32_16x16x32_bf16 v[68:71], v[206:209], v[198:201], v[68:71]
	v_mfma_f32_16x16x32_bf16 v[64:67], v[214:217], v[198:201], v[64:67]
	s_mov_b32 m0, s47
	v_lshl_add_u64 v[222:223], s[50:51], 0, v[134:135]
	s_barrier
	ds_read_b128 v[170:173], v158 offset:16384
	ds_read_b128 v[174:177], v158 offset:17408
	ds_read_b128 v[178:181], v158 offset:18432
	ds_read_b128 v[182:185], v158 offset:19456
	ds_read_b128 v[186:189], v158 offset:20480
	ds_read_b128 v[190:193], v158 offset:21504
	ds_read_b128 v[194:197], v158 offset:22528
	ds_read_b128 v[198:201], v158 offset:23552
	global_load_lds_dwordx4 v[222:223], off
	s_mov_b32 m0, s53
	v_lshl_add_u64 v[224:225], s[50:51], 0, v[130:131]
	global_load_lds_dwordx4 v[224:225], off
	s_barrier
	s_waitcnt lgkmcnt(0)
	s_waitcnt lgkmcnt(0)
	v_mfma_f32_16x16x32_bf16 v[60:63], v[144:147], v[170:173], v[60:63]
	v_mfma_f32_16x16x32_bf16 v[56:59], v[162:165], v[170:173], v[56:59]
	v_mfma_f32_16x16x32_bf16 v[44:47], v[144:147], v[178:181], v[44:47]
	v_mfma_f32_16x16x32_bf16 v[40:43], v[162:165], v[178:181], v[40:43]
	v_mfma_f32_16x16x32_bf16 v[28:31], v[144:147], v[186:189], v[28:31]
	v_mfma_f32_16x16x32_bf16 v[24:27], v[162:165], v[186:189], v[24:27]
	v_mfma_f32_16x16x32_bf16 v[12:15], v[144:147], v[194:197], v[12:15]
	v_mfma_f32_16x16x32_bf16 v[8:11], v[162:165], v[194:197], v[8:11]
	v_mfma_f32_16x16x32_bf16 v[60:63], v[148:151], v[174:177], v[60:63]
	v_mfma_f32_16x16x32_bf16 v[56:59], v[166:169], v[174:177], v[56:59]
	v_mfma_f32_16x16x32_bf16 v[44:47], v[148:151], v[182:185], v[44:47]
	v_mfma_f32_16x16x32_bf16 v[40:43], v[166:169], v[182:185], v[40:43]
	v_mfma_f32_16x16x32_bf16 v[28:31], v[148:151], v[190:193], v[28:31]
	v_mfma_f32_16x16x32_bf16 v[24:27], v[166:169], v[190:193], v[24:27]
	v_mfma_f32_16x16x32_bf16 v[12:15], v[148:151], v[198:201], v[12:15]
	v_mfma_f32_16x16x32_bf16 v[8:11], v[166:169], v[198:201], v[8:11]
	s_barrier
	s_add_u32 s74, s48, 0x40000
	s_addc_u32 s75, s49, 0
	s_add_i32 s73, s72, s34
	s_mov_b32 m0, s73
	v_lshl_add_u64 v[144:145], s[74:75], 0, v[132:133]
	global_load_lds_dwordx4 v[144:145], off
	s_add_i32 m0, s73, 0x2000
	v_lshl_add_u64 v[144:145], s[74:75], 0, v[128:129]
	global_load_lds_dwordx4 v[144:145], off
	s_waitcnt vmcnt(6)
	s_barrier
	v_mfma_f32_16x16x32_bf16 v[52:55], v[202:205], v[170:173], v[52:55]
	v_mfma_f32_16x16x32_bf16 v[48:51], v[210:213], v[170:173], v[48:51]
	v_mfma_f32_16x16x32_bf16 v[36:39], v[202:205], v[178:181], v[36:39]
	v_mfma_f32_16x16x32_bf16 v[32:35], v[210:213], v[178:181], v[32:35]
	v_mfma_f32_16x16x32_bf16 v[20:23], v[202:205], v[186:189], v[20:23]
	v_mfma_f32_16x16x32_bf16 v[16:19], v[210:213], v[186:189], v[16:19]
	v_mfma_f32_16x16x32_bf16 v[4:7], v[202:205], v[194:197], v[4:7]
	v_mfma_f32_16x16x32_bf16 v[0:3], v[210:213], v[194:197], v[0:3]
	v_mfma_f32_16x16x32_bf16 v[52:55], v[206:209], v[174:177], v[52:55]
	v_mfma_f32_16x16x32_bf16 v[48:51], v[214:217], v[174:177], v[48:51]
	v_mfma_f32_16x16x32_bf16 v[36:39], v[206:209], v[182:185], v[36:39]
	v_mfma_f32_16x16x32_bf16 v[32:35], v[214:217], v[182:185], v[32:35]
	v_mfma_f32_16x16x32_bf16 v[20:23], v[206:209], v[190:193], v[20:23]
	v_mfma_f32_16x16x32_bf16 v[16:19], v[214:217], v[190:193], v[16:19]
	v_mfma_f32_16x16x32_bf16 v[4:7], v[206:209], v[198:201], v[4:7]
	v_mfma_f32_16x16x32_bf16 v[0:3], v[214:217], v[198:201], v[0:3]
	s_add_i32 s73, 0, 0x18000
	v_add_u32_e32 v161, s73, v153
	s_barrier
	ds_read_b128 v[144:147], v161
	ds_read_b128 v[148:151], v161 offset:1024
	ds_read_b128 v[162:165], v161 offset:2048
	ds_read_b128 v[166:169], v161 offset:3072
	s_add_u32 s50, s50, 0x40000
	s_addc_u32 s51, s51, 0
	s_mov_b32 m0, s54
	v_lshl_add_u64 v[202:203], s[50:51], 0, v[134:135]
	ds_read_b128 v[170:173], v158 offset:32768
	ds_read_b128 v[174:177], v158 offset:33792
	ds_read_b128 v[178:181], v158 offset:34816
	ds_read_b128 v[182:185], v158 offset:35840
	ds_read_b128 v[186:189], v158 offset:36864
	ds_read_b128 v[190:193], v158 offset:37888
	ds_read_b128 v[194:197], v158 offset:38912
	ds_read_b128 v[198:201], v158 offset:39936
	global_load_lds_dwordx4 v[202:203], off
	s_mov_b32 m0, s55
	v_lshl_add_u64 v[202:203], s[50:51], 0, v[130:131]
	global_load_lds_dwordx4 v[202:203], off
	s_waitcnt lgkmcnt(8)
	s_barrier
	s_waitcnt lgkmcnt(0)
	s_waitcnt lgkmcnt(0)
	v_mfma_f32_16x16x32_bf16 v[124:127], v[144:147], v[170:173], v[124:127]
	v_mfma_f32_16x16x32_bf16 v[120:123], v[162:165], v[170:173], v[120:123]
	v_mfma_f32_16x16x32_bf16 v[108:111], v[144:147], v[178:181], v[108:111]
	v_mfma_f32_16x16x32_bf16 v[104:107], v[162:165], v[178:181], v[104:107]
	v_mfma_f32_16x16x32_bf16 v[92:95], v[144:147], v[186:189], v[92:95]
	v_mfma_f32_16x16x32_bf16 v[88:91], v[162:165], v[186:189], v[88:91]
	v_mfma_f32_16x16x32_bf16 v[76:79], v[144:147], v[194:197], v[76:79]
	v_mfma_f32_16x16x32_bf16 v[72:75], v[162:165], v[194:197], v[72:75]
	v_mfma_f32_16x16x32_bf16 v[124:127], v[148:151], v[174:177], v[124:127]
	v_mfma_f32_16x16x32_bf16 v[120:123], v[166:169], v[174:177], v[120:123]
	v_mfma_f32_16x16x32_bf16 v[108:111], v[148:151], v[182:185], v[108:111]
	v_mfma_f32_16x16x32_bf16 v[104:107], v[166:169], v[182:185], v[104:107]
	v_mfma_f32_16x16x32_bf16 v[92:95], v[148:151], v[190:193], v[92:95]
	v_mfma_f32_16x16x32_bf16 v[88:91], v[166:169], v[190:193], v[88:91]
	v_mfma_f32_16x16x32_bf16 v[76:79], v[148:151], v[198:201], v[76:79]
	v_mfma_f32_16x16x32_bf16 v[72:75], v[166:169], v[198:201], v[72:75]
	s_barrier
	s_add_i32 s50, s73, s34
	v_add_u32_e32 v161, s97, v153
	v_lshl_add_u64 v[218:219], v[218:219], 0, s[14:15]
	s_mov_b32 m0, s50
	ds_read_b128 v[202:205], v161
	ds_read_b128 v[206:209], v161 offset:1024
	ds_read_b128 v[210:213], v161 offset:2048
	ds_read_b128 v[214:217], v161 offset:3072
	global_load_lds_dwordx4 v[218:219], off
	s_add_i32 m0, s50, 0x2000
	v_lshl_add_u64 v[218:219], v[220:221], 0, s[14:15]
	global_load_lds_dwordx4 v[218:219], off
	s_barrier
	s_waitcnt lgkmcnt(0)
	s_waitcnt lgkmcnt(0)
	v_mfma_f32_16x16x32_bf16 v[116:119], v[202:205], v[170:173], v[116:119]
	v_mfma_f32_16x16x32_bf16 v[112:115], v[210:213], v[170:173], v[112:115]
	v_mfma_f32_16x16x32_bf16 v[100:103], v[202:205], v[178:181], v[100:103]
	v_mfma_f32_16x16x32_bf16 v[96:99], v[210:213], v[178:181], v[96:99]
	v_mfma_f32_16x16x32_bf16 v[84:87], v[202:205], v[186:189], v[84:87]
	v_mfma_f32_16x16x32_bf16 v[80:83], v[210:213], v[186:189], v[80:83]
	v_mfma_f32_16x16x32_bf16 v[68:71], v[202:205], v[194:197], v[68:71]
	v_mfma_f32_16x16x32_bf16 v[64:67], v[210:213], v[194:197], v[64:67]
	v_mfma_f32_16x16x32_bf16 v[116:119], v[206:209], v[174:177], v[116:119]
	v_mfma_f32_16x16x32_bf16 v[112:115], v[214:217], v[174:177], v[112:115]
	v_mfma_f32_16x16x32_bf16 v[100:103], v[206:209], v[182:185], v[100:103]
	v_mfma_f32_16x16x32_bf16 v[96:99], v[214:217], v[182:185], v[96:99]
	v_mfma_f32_16x16x32_bf16 v[84:87], v[206:209], v[190:193], v[84:87]
	v_mfma_f32_16x16x32_bf16 v[80:83], v[214:217], v[190:193], v[80:83]
	v_mfma_f32_16x16x32_bf16 v[68:71], v[206:209], v[198:201], v[68:71]
	v_mfma_f32_16x16x32_bf16 v[64:67], v[214:217], v[198:201], v[64:67]
	s_mov_b32 m0, s57
	v_lshl_add_u64 v[218:219], v[222:223], 0, s[14:15]
	s_barrier
	ds_read_b128 v[170:173], v158 offset:49152
	ds_read_b128 v[174:177], v158 offset:50176
	ds_read_b128 v[178:181], v158 offset:51200
	ds_read_b128 v[182:185], v158 offset:52224
	ds_read_b128 v[186:189], v158 offset:53248
	ds_read_b128 v[190:193], v158 offset:54272
	ds_read_b128 v[194:197], v158 offset:55296
	ds_read_b128 v[198:201], v158 offset:56320
	global_load_lds_dwordx4 v[218:219], off
	s_mov_b32 m0, s58
	v_lshl_add_u64 v[218:219], v[224:225], 0, s[14:15]
	global_load_lds_dwordx4 v[218:219], off
	s_barrier
	s_waitcnt lgkmcnt(0)
	s_waitcnt lgkmcnt(0)
	v_mfma_f32_16x16x32_bf16 v[60:63], v[144:147], v[170:173], v[60:63]
	v_mfma_f32_16x16x32_bf16 v[56:59], v[162:165], v[170:173], v[56:59]
	v_mfma_f32_16x16x32_bf16 v[44:47], v[144:147], v[178:181], v[44:47]
	v_mfma_f32_16x16x32_bf16 v[40:43], v[162:165], v[178:181], v[40:43]
	v_mfma_f32_16x16x32_bf16 v[28:31], v[144:147], v[186:189], v[28:31]
	v_mfma_f32_16x16x32_bf16 v[24:27], v[162:165], v[186:189], v[24:27]
	v_mfma_f32_16x16x32_bf16 v[12:15], v[144:147], v[194:197], v[12:15]
	v_mfma_f32_16x16x32_bf16 v[8:11], v[162:165], v[194:197], v[8:11]
	v_mfma_f32_16x16x32_bf16 v[60:63], v[148:151], v[174:177], v[60:63]
	v_mfma_f32_16x16x32_bf16 v[56:59], v[166:169], v[174:177], v[56:59]
	v_mfma_f32_16x16x32_bf16 v[44:47], v[148:151], v[182:185], v[44:47]
	v_mfma_f32_16x16x32_bf16 v[40:43], v[166:169], v[182:185], v[40:43]
	v_mfma_f32_16x16x32_bf16 v[28:31], v[148:151], v[190:193], v[28:31]
	v_mfma_f32_16x16x32_bf16 v[24:27], v[166:169], v[190:193], v[24:27]
	v_mfma_f32_16x16x32_bf16 v[12:15], v[148:151], v[198:201], v[12:15]
	v_mfma_f32_16x16x32_bf16 v[8:11], v[166:169], v[198:201], v[8:11]
	s_barrier
	s_add_u32 s48, s48, 0x40080
	s_addc_u32 s49, s49, 0
	s_add_i32 s50, s97, s34
	s_mov_b32 m0, s50
	v_lshl_add_u64 v[144:145], s[48:49], 0, v[132:133]
	global_load_lds_dwordx4 v[144:145], off
	s_add_i32 m0, s50, 0x2000
	v_lshl_add_u64 v[144:145], s[48:49], 0, v[128:129]
	global_load_lds_dwordx4 v[144:145], off
	s_waitcnt vmcnt(6)
	s_barrier
	v_mfma_f32_16x16x32_bf16 v[52:55], v[202:205], v[170:173], v[52:55]
	v_mfma_f32_16x16x32_bf16 v[48:51], v[210:213], v[170:173], v[48:51]
	v_mfma_f32_16x16x32_bf16 v[36:39], v[202:205], v[178:181], v[36:39]
	v_mfma_f32_16x16x32_bf16 v[32:35], v[210:213], v[178:181], v[32:35]
	v_mfma_f32_16x16x32_bf16 v[20:23], v[202:205], v[186:189], v[20:23]
	v_mfma_f32_16x16x32_bf16 v[16:19], v[210:213], v[186:189], v[16:19]
	v_mfma_f32_16x16x32_bf16 v[4:7], v[202:205], v[194:197], v[4:7]
	v_mfma_f32_16x16x32_bf16 v[0:3], v[210:213], v[194:197], v[0:3]
	v_mfma_f32_16x16x32_bf16 v[52:55], v[206:209], v[174:177], v[52:55]
	v_mfma_f32_16x16x32_bf16 v[48:51], v[214:217], v[174:177], v[48:51]
	v_mfma_f32_16x16x32_bf16 v[36:39], v[206:209], v[182:185], v[36:39]
	v_mfma_f32_16x16x32_bf16 v[32:35], v[214:217], v[182:185], v[32:35]
	v_mfma_f32_16x16x32_bf16 v[20:23], v[206:209], v[190:193], v[20:23]
	v_mfma_f32_16x16x32_bf16 v[16:19], v[214:217], v[190:193], v[16:19]
	v_mfma_f32_16x16x32_bf16 v[4:7], v[206:209], v[198:201], v[4:7]
	v_mfma_f32_16x16x32_bf16 v[0:3], v[214:217], v[198:201], v[0:3]
	s_add_i32 s71, s71, 2
	s_add_u32 s6, s6, 0x100
	s_addc_u32 s7, s7, 0
	s_add_u32 s69, s69, 0x100
	s_addc_u32 s70, s70, 0
	s_cmp_gt_u32 s71, 13
	s_barrier
	s_cbranch_scc0 .LBB0_697
	v_lshl_add_u32 v148, s46, 8, v152
	v_ashrrev_i32_e32 v149, 31, v148
	v_lshl_add_u64 v[144:145], v[148:149], 2, s[18:19]
	global_load_dword v151, v[144:145], off
	v_lshlrev_b64 v[146:147], 12, v[148:149]
	s_cmp_lt_i32 s66, 8
	s_cselect_b32 s7, s1, s29
	s_cselect_b32 s6, s0, s28
	s_cselect_b32 s37, 0, 0xfffff800
	s_lshl_b32 s39, s66, 8
	s_add_i32 s37, s37, s39
	v_or_b32_e32 v150, s37, v156
	v_or_b32_e32 v162, 16, v148
	v_lshl_add_u64 v[146:147], s[6:7], 0, v[146:147]
	v_ashrrev_i32_e32 v163, 31, v162
	v_lshl_add_u64 v[164:165], v[162:163], 2, s[18:19]
	s_mov_b32 s46, s38
	s_mov_b64 s[48:49], s[44:45]
	s_mov_b64 s[50:51], s[40:41]
	s_mov_b32 s66, s36
	s_waitcnt vmcnt(0)
	v_fmamk_f32 v149, v151, 0x3a800000, v160
	v_mul_f32_e32 v151, 0x4b800000, v149
	v_cmp_gt_f32_e32 vcc, s61, v149
	s_nop 1
	v_cndmask_b32_e32 v149, v149, v151, vcc
	v_rsq_f32_e32 v149, v149
	v_ashrrev_i32_e32 v151, 31, v150
	v_lshlrev_b64 v[150:151], 1, v[150:151]
	v_lshl_add_u64 v[146:147], v[146:147], 0, v[150:151]
	v_mul_f32_e32 v161, 0x45800000, v149
	v_cndmask_b32_e32 v149, v149, v161, vcc
	v_mul_f32_e32 v124, v124, v149
	v_mul_f32_e32 v120, v120, v149
	v_mul_f32_e32 v125, v125, v149
	v_mul_f32_e32 v121, v121, v149
	v_mul_f32_e32 v126, v126, v149
	v_mul_f32_e32 v122, v122, v149
	v_mul_f32_e32 v127, v127, v149
	v_mul_f32_e32 v123, v123, v149
	v_mul_f32_e32 v161, v116, v149
	v_mul_f32_e32 v166, v112, v149
	v_mul_f32_e32 v167, v117, v149
	v_mul_f32_e32 v168, v113, v149
	v_mul_f32_e32 v169, v118, v149
	v_mul_f32_e32 v170, v114, v149
	v_mul_f32_e32 v171, v119, v149
	v_mul_f32_e32 v149, v115, v149
	v_max_f32_e32 v112, 0, v124
	v_max_f32_e32 v114, 0, v120
	v_max_f32_e32 v113, 0, v125
	v_max_f32_e32 v115, 0, v121
	v_max_f32_e32 v116, 0, v126
	v_max_f32_e32 v118, 0, v122
	v_max_f32_e32 v117, 0, v127
	v_max_f32_e32 v119, 0, v123
	v_max_f32_e32 v120, 0, v161
	v_max_f32_e32 v122, 0, v166
	v_max_f32_e32 v121, 0, v167
	v_max_f32_e32 v123, 0, v168
	v_max_f32_e32 v124, 0, v169
	v_max_f32_e32 v126, 0, v170
	v_max_f32_e32 v125, 0, v171
	v_max_f32_e32 v127, 0, v149
	v_pk_mul_f32 v[112:113], v[112:113], v[112:113]
	v_pk_mul_f32 v[114:115], v[114:115], v[114:115]
	v_pk_mul_f32 v[116:117], v[116:117], v[116:117]
	v_pk_mul_f32 v[118:119], v[118:119], v[118:119]
	v_pk_mul_f32 v[120:121], v[120:121], v[120:121]
	v_pk_mul_f32 v[122:123], v[122:123], v[122:123]
	v_pk_mul_f32 v[124:125], v[124:125], v[124:125]
	v_pk_mul_f32 v[126:127], v[126:127], v[126:127]
	v_cvt_pk_bf16_f32 v112, v112, v113
	v_cvt_pk_bf16_f32 v113, v116, v117
	v_cvt_pk_bf16_f32 v114, v114, v115
	v_cvt_pk_bf16_f32 v115, v118, v119
	v_cvt_pk_bf16_f32 v116, v120, v121
	v_cvt_pk_bf16_f32 v117, v124, v125
	v_cvt_pk_bf16_f32 v118, v122, v123
	v_cvt_pk_bf16_f32 v119, v126, v127
	global_store_dwordx4 v[146:147], v[112:115], off
	global_store_dwordx4 v[146:147], v[116:119], off offset:256
	global_load_dword v116, v[164:165], off
	v_lshlrev_b64 v[114:115], 12, v[162:163]
	v_or_b32_e32 v112, 32, v148
	v_lshl_add_u64 v[114:115], s[6:7], 0, v[114:115]
	v_ashrrev_i32_e32 v113, 31, v112
	v_lshl_add_u64 v[114:115], v[114:115], 0, v[150:151]
	s_waitcnt vmcnt(0)
	v_fmamk_f32 v116, v116, 0x3a800000, v160
	v_mul_f32_e32 v117, 0x4b800000, v116
	v_cmp_gt_f32_e32 vcc, s61, v116
	s_nop 1
	v_cndmask_b32_e32 v116, v116, v117, vcc
	v_rsq_f32_e32 v118, v116
	v_lshl_add_u64 v[116:117], v[112:113], 2, s[18:19]
	v_mul_f32_e32 v119, 0x45800000, v118
	v_cndmask_b32_e32 v118, v118, v119, vcc
	v_mul_f32_e32 v108, v108, v118
	v_mul_f32_e32 v104, v104, v118
	v_mul_f32_e32 v109, v109, v118
	v_mul_f32_e32 v105, v105, v118
	v_mul_f32_e32 v110, v110, v118
	v_mul_f32_e32 v106, v106, v118
	v_mul_f32_e32 v111, v111, v118
	v_mul_f32_e32 v107, v107, v118
	v_mul_f32_e32 v119, v100, v118
	v_mul_f32_e32 v120, v96, v118
	v_mul_f32_e32 v121, v101, v118
	v_mul_f32_e32 v122, v97, v118
	v_mul_f32_e32 v123, v102, v118
	v_mul_f32_e32 v124, v98, v118
	v_mul_f32_e32 v125, v103, v118
	v_mul_f32_e32 v118, v99, v118
	v_max_f32_e32 v96, 0, v108
	v_max_f32_e32 v98, 0, v104
	v_max_f32_e32 v97, 0, v109
	v_max_f32_e32 v99, 0, v105
	v_max_f32_e32 v100, 0, v110
	v_max_f32_e32 v102, 0, v106
	v_max_f32_e32 v101, 0, v111
	v_max_f32_e32 v103, 0, v107
	v_max_f32_e32 v104, 0, v119
	v_max_f32_e32 v106, 0, v120
	v_max_f32_e32 v105, 0, v121
	v_max_f32_e32 v107, 0, v122
	v_max_f32_e32 v108, 0, v123
	v_max_f32_e32 v110, 0, v124
	v_max_f32_e32 v109, 0, v125
	v_max_f32_e32 v111, 0, v118
	v_pk_mul_f32 v[96:97], v[96:97], v[96:97]
	v_pk_mul_f32 v[98:99], v[98:99], v[98:99]
	v_pk_mul_f32 v[100:101], v[100:101], v[100:101]
	v_pk_mul_f32 v[102:103], v[102:103], v[102:103]
	v_pk_mul_f32 v[104:105], v[104:105], v[104:105]
	v_pk_mul_f32 v[106:107], v[106:107], v[106:107]
	v_pk_mul_f32 v[108:109], v[108:109], v[108:109]
	v_pk_mul_f32 v[110:111], v[110:111], v[110:111]
	v_cvt_pk_bf16_f32 v96, v96, v97
	v_cvt_pk_bf16_f32 v97, v100, v101
	v_cvt_pk_bf16_f32 v98, v98, v99
	v_cvt_pk_bf16_f32 v99, v102, v103
	v_cvt_pk_bf16_f32 v100, v104, v105
	v_cvt_pk_bf16_f32 v101, v108, v109
	v_cvt_pk_bf16_f32 v102, v106, v107
	v_cvt_pk_bf16_f32 v103, v110, v111
	global_store_dwordx4 v[114:115], v[96:99], off
	global_store_dwordx4 v[114:115], v[100:103], off offset:256
	global_load_dword v100, v[116:117], off
	v_lshlrev_b64 v[98:99], 12, v[112:113]
	v_or_b32_e32 v96, 48, v148
	v_lshl_add_u64 v[98:99], s[6:7], 0, v[98:99]
	v_ashrrev_i32_e32 v97, 31, v96
	v_lshl_add_u64 v[98:99], v[98:99], 0, v[150:151]
	s_waitcnt vmcnt(0)
	v_fmamk_f32 v100, v100, 0x3a800000, v160
	v_mul_f32_e32 v101, 0x4b800000, v100
	v_cmp_gt_f32_e32 vcc, s61, v100
	s_nop 1
	v_cndmask_b32_e32 v100, v100, v101, vcc
	v_rsq_f32_e32 v102, v100
	v_lshl_add_u64 v[100:101], v[96:97], 2, s[18:19]
	v_mul_f32_e32 v103, 0x45800000, v102
	v_cndmask_b32_e32 v102, v102, v103, vcc
	v_mul_f32_e32 v92, v92, v102
	v_mul_f32_e32 v88, v88, v102
	v_mul_f32_e32 v93, v93, v102
	v_mul_f32_e32 v89, v89, v102
	v_mul_f32_e32 v94, v94, v102
	v_mul_f32_e32 v90, v90, v102
	v_mul_f32_e32 v95, v95, v102
	v_mul_f32_e32 v91, v91, v102
	v_mul_f32_e32 v103, v84, v102
	v_mul_f32_e32 v104, v80, v102
	v_mul_f32_e32 v105, v85, v102
	v_mul_f32_e32 v106, v81, v102
	v_mul_f32_e32 v107, v86, v102
	v_mul_f32_e32 v108, v82, v102
	v_mul_f32_e32 v109, v87, v102
	v_mul_f32_e32 v102, v83, v102
	v_max_f32_e32 v80, 0, v92
	v_max_f32_e32 v82, 0, v88
	v_max_f32_e32 v81, 0, v93
	v_max_f32_e32 v83, 0, v89
	v_max_f32_e32 v84, 0, v94
	v_max_f32_e32 v86, 0, v90
	v_max_f32_e32 v85, 0, v95
	v_max_f32_e32 v87, 0, v91
	v_max_f32_e32 v88, 0, v103
	v_max_f32_e32 v90, 0, v104
	v_max_f32_e32 v89, 0, v105
	v_max_f32_e32 v91, 0, v106
	v_max_f32_e32 v92, 0, v107
	v_max_f32_e32 v94, 0, v108
	v_max_f32_e32 v93, 0, v109
	v_max_f32_e32 v95, 0, v102
	v_pk_mul_f32 v[80:81], v[80:81], v[80:81]
	v_pk_mul_f32 v[82:83], v[82:83], v[82:83]
	v_pk_mul_f32 v[84:85], v[84:85], v[84:85]
	v_pk_mul_f32 v[86:87], v[86:87], v[86:87]
	v_pk_mul_f32 v[88:89], v[88:89], v[88:89]
	v_pk_mul_f32 v[90:91], v[90:91], v[90:91]
	v_pk_mul_f32 v[92:93], v[92:93], v[92:93]
	v_pk_mul_f32 v[94:95], v[94:95], v[94:95]
	v_cvt_pk_bf16_f32 v80, v80, v81
	v_cvt_pk_bf16_f32 v81, v84, v85
	v_cvt_pk_bf16_f32 v82, v82, v83
	v_cvt_pk_bf16_f32 v83, v86, v87
	v_cvt_pk_bf16_f32 v84, v88, v89
	v_cvt_pk_bf16_f32 v85, v92, v93
	v_cvt_pk_bf16_f32 v86, v90, v91
	v_cvt_pk_bf16_f32 v87, v94, v95
	global_store_dwordx4 v[98:99], v[80:83], off
	global_store_dwordx4 v[98:99], v[84:87], off offset:256
	global_load_dword v80, v[100:101], off
	s_waitcnt vmcnt(0)
	v_fmamk_f32 v80, v80, 0x3a800000, v160
	v_mul_f32_e32 v81, 0x4b800000, v80
	v_cmp_gt_f32_e32 vcc, s61, v80
	s_nop 1
	v_cndmask_b32_e32 v80, v80, v81, vcc
	v_rsq_f32_e32 v82, v80
	v_lshlrev_b64 v[80:81], 12, v[96:97]
	v_lshl_add_u64 v[80:81], s[6:7], 0, v[80:81]
	v_lshl_add_u64 v[80:81], v[80:81], 0, v[150:151]
	v_mul_f32_e32 v83, 0x45800000, v82
	v_cndmask_b32_e32 v82, v82, v83, vcc
	v_mul_f32_e32 v76, v76, v82
	v_mul_f32_e32 v72, v72, v82
	v_mul_f32_e32 v77, v77, v82
	v_mul_f32_e32 v73, v73, v82
	v_mul_f32_e32 v78, v78, v82
	v_mul_f32_e32 v74, v74, v82
	v_mul_f32_e32 v79, v79, v82
	v_mul_f32_e32 v75, v75, v82
	v_mul_f32_e32 v83, v68, v82
	v_mul_f32_e32 v84, v64, v82
	v_mul_f32_e32 v85, v69, v82
	v_mul_f32_e32 v86, v65, v82
	v_mul_f32_e32 v87, v70, v82
	v_mul_f32_e32 v88, v66, v82
	v_mul_f32_e32 v89, v71, v82
	v_mul_f32_e32 v82, v67, v82
	v_max_f32_e32 v64, 0, v76
	v_max_f32_e32 v66, 0, v72
	v_max_f32_e32 v65, 0, v77
	v_max_f32_e32 v67, 0, v73
	v_max_f32_e32 v68, 0, v78
	v_max_f32_e32 v70, 0, v74
	v_max_f32_e32 v69, 0, v79
	v_max_f32_e32 v71, 0, v75
	v_max_f32_e32 v72, 0, v83
	v_max_f32_e32 v74, 0, v84
	v_max_f32_e32 v73, 0, v85
	v_max_f32_e32 v75, 0, v86
	v_max_f32_e32 v76, 0, v87
	v_max_f32_e32 v78, 0, v88
	v_max_f32_e32 v77, 0, v89
	v_max_f32_e32 v79, 0, v82
	v_pk_mul_f32 v[64:65], v[64:65], v[64:65]
	v_pk_mul_f32 v[66:67], v[66:67], v[66:67]
	v_pk_mul_f32 v[68:69], v[68:69], v[68:69]
	v_pk_mul_f32 v[70:71], v[70:71], v[70:71]
	v_pk_mul_f32 v[72:73], v[72:73], v[72:73]
	v_pk_mul_f32 v[74:75], v[74:75], v[74:75]
	v_pk_mul_f32 v[76:77], v[76:77], v[76:77]
	v_pk_mul_f32 v[78:79], v[78:79], v[78:79]
	v_cvt_pk_bf16_f32 v64, v64, v65
	v_cvt_pk_bf16_f32 v65, v68, v69
	v_cvt_pk_bf16_f32 v66, v66, v67
	v_cvt_pk_bf16_f32 v67, v70, v71
	v_cvt_pk_bf16_f32 v68, v72, v73
	v_cvt_pk_bf16_f32 v69, v76, v77
	v_cvt_pk_bf16_f32 v70, v74, v75
	v_cvt_pk_bf16_f32 v71, v78, v79
	global_store_dwordx4 v[80:81], v[64:67], off
	global_store_dwordx4 v[80:81], v[68:71], off offset:256
	global_load_dword v66, v[144:145], off offset:512
	v_lshl_add_u64 v[64:65], v[146:147], 0, s[16:17]
	s_waitcnt vmcnt(0)
	v_fmamk_f32 v66, v66, 0x3a800000, v160
	v_mul_f32_e32 v67, 0x4b800000, v66
	v_cmp_gt_f32_e32 vcc, s61, v66
	s_nop 1
	v_cndmask_b32_e32 v66, v66, v67, vcc
	v_rsq_f32_e32 v68, v66
	v_add_co_u32_e64 v66, s[6:7], s62, v146
	v_mul_f32_e32 v69, 0x45800000, v68
	v_cndmask_b32_e32 v68, v68, v69, vcc
	v_mul_f32_e32 v60, v60, v68
	v_mul_f32_e32 v56, v56, v68
	v_mul_f32_e32 v61, v61, v68
	v_mul_f32_e32 v57, v57, v68
	v_mul_f32_e32 v62, v62, v68
	v_mul_f32_e32 v58, v58, v68
	v_mul_f32_e32 v63, v63, v68
	v_mul_f32_e32 v59, v59, v68
	v_mul_f32_e32 v69, v52, v68
	v_mul_f32_e32 v70, v48, v68
	v_mul_f32_e32 v71, v53, v68
	v_mul_f32_e32 v72, v49, v68
	v_mul_f32_e32 v73, v54, v68
	v_mul_f32_e32 v74, v50, v68
	v_mul_f32_e32 v75, v55, v68
	v_mul_f32_e32 v68, v51, v68
	v_max_f32_e32 v48, 0, v60
	v_max_f32_e32 v50, 0, v56
	v_max_f32_e32 v49, 0, v61
	v_max_f32_e32 v51, 0, v57
	v_max_f32_e32 v52, 0, v62
	v_max_f32_e32 v54, 0, v58
	v_max_f32_e32 v53, 0, v63
	v_max_f32_e32 v55, 0, v59
	v_max_f32_e32 v56, 0, v69
	v_max_f32_e32 v58, 0, v70
	v_max_f32_e32 v57, 0, v71
	v_max_f32_e32 v59, 0, v72
	v_max_f32_e32 v60, 0, v73
	v_max_f32_e32 v62, 0, v74
	v_max_f32_e32 v61, 0, v75
	v_max_f32_e32 v63, 0, v68
	v_pk_mul_f32 v[48:49], v[48:49], v[48:49]
	v_pk_mul_f32 v[50:51], v[50:51], v[50:51]
	v_pk_mul_f32 v[52:53], v[52:53], v[52:53]
	v_pk_mul_f32 v[54:55], v[54:55], v[54:55]
	v_addc_co_u32_e64 v67, s[6:7], 0, v147, s[6:7]
	v_pk_mul_f32 v[56:57], v[56:57], v[56:57]
	v_pk_mul_f32 v[58:59], v[58:59], v[58:59]
	v_pk_mul_f32 v[60:61], v[60:61], v[60:61]
	v_pk_mul_f32 v[62:63], v[62:63], v[62:63]
	v_cvt_pk_bf16_f32 v48, v48, v49
	v_cvt_pk_bf16_f32 v49, v52, v53
	v_cvt_pk_bf16_f32 v50, v50, v51
	v_cvt_pk_bf16_f32 v51, v54, v55
	v_cvt_pk_bf16_f32 v52, v56, v57
	v_cvt_pk_bf16_f32 v53, v60, v61
	v_cvt_pk_bf16_f32 v54, v58, v59
	v_cvt_pk_bf16_f32 v55, v62, v63
	global_store_dwordx4 v[66:67], v[48:51], off
	global_store_dwordx4 v[64:65], v[52:55], off offset:256
	global_load_dword v50, v[144:145], off offset:576
	v_lshl_add_u64 v[48:49], v[146:147], 0, s[20:21]
	s_waitcnt vmcnt(0)
	v_fmamk_f32 v50, v50, 0x3a800000, v160
	v_mul_f32_e32 v51, 0x4b800000, v50
	v_cmp_gt_f32_e32 vcc, s61, v50
	s_nop 1
	v_cndmask_b32_e32 v50, v50, v51, vcc
	v_rsq_f32_e32 v52, v50
	v_add_co_u32_e64 v50, s[6:7], s63, v146
	v_mul_f32_e32 v53, 0x45800000, v52
	v_cndmask_b32_e32 v52, v52, v53, vcc
	v_mul_f32_e32 v44, v44, v52
	v_mul_f32_e32 v40, v40, v52
	v_mul_f32_e32 v45, v45, v52
	v_mul_f32_e32 v41, v41, v52
	v_mul_f32_e32 v46, v46, v52
	v_mul_f32_e32 v42, v42, v52
	v_mul_f32_e32 v47, v47, v52
	v_mul_f32_e32 v43, v43, v52
	v_mul_f32_e32 v53, v36, v52
	v_mul_f32_e32 v54, v32, v52
	v_mul_f32_e32 v55, v37, v52
	v_mul_f32_e32 v56, v33, v52
	v_mul_f32_e32 v57, v38, v52
	v_mul_f32_e32 v58, v34, v52
	v_mul_f32_e32 v59, v39, v52
	v_mul_f32_e32 v52, v35, v52
	v_max_f32_e32 v32, 0, v44
	v_max_f32_e32 v34, 0, v40
	v_max_f32_e32 v33, 0, v45
	v_max_f32_e32 v35, 0, v41
	v_max_f32_e32 v36, 0, v46
	v_max_f32_e32 v38, 0, v42
	v_max_f32_e32 v37, 0, v47
	v_max_f32_e32 v39, 0, v43
	v_max_f32_e32 v40, 0, v53
	v_max_f32_e32 v42, 0, v54
	v_max_f32_e32 v41, 0, v55
	v_max_f32_e32 v43, 0, v56
	v_max_f32_e32 v44, 0, v57
	v_max_f32_e32 v46, 0, v58
	v_max_f32_e32 v45, 0, v59
	v_max_f32_e32 v47, 0, v52
	v_pk_mul_f32 v[32:33], v[32:33], v[32:33]
	v_pk_mul_f32 v[34:35], v[34:35], v[34:35]
	v_pk_mul_f32 v[36:37], v[36:37], v[36:37]
	v_pk_mul_f32 v[38:39], v[38:39], v[38:39]
	v_addc_co_u32_e64 v51, s[6:7], 0, v147, s[6:7]
	v_pk_mul_f32 v[40:41], v[40:41], v[40:41]
	v_pk_mul_f32 v[42:43], v[42:43], v[42:43]
	v_pk_mul_f32 v[44:45], v[44:45], v[44:45]
	v_pk_mul_f32 v[46:47], v[46:47], v[46:47]
	v_cvt_pk_bf16_f32 v32, v32, v33
	v_cvt_pk_bf16_f32 v33, v36, v37
	v_cvt_pk_bf16_f32 v34, v34, v35
	v_cvt_pk_bf16_f32 v35, v38, v39
	v_cvt_pk_bf16_f32 v36, v40, v41
	v_cvt_pk_bf16_f32 v37, v44, v45
	v_cvt_pk_bf16_f32 v38, v42, v43
	v_cvt_pk_bf16_f32 v39, v46, v47
	global_store_dwordx4 v[50:51], v[32:35], off
	global_store_dwordx4 v[48:49], v[36:39], off offset:256
	global_load_dword v34, v[144:145], off offset:640
	v_lshl_add_u64 v[32:33], v[146:147], 0, s[22:23]
	s_waitcnt vmcnt(0)
	v_fmamk_f32 v34, v34, 0x3a800000, v160
	v_mul_f32_e32 v35, 0x4b800000, v34
	v_cmp_gt_f32_e32 vcc, s61, v34
	s_nop 1
	v_cndmask_b32_e32 v34, v34, v35, vcc
	v_rsq_f32_e32 v36, v34
	v_add_co_u32_e64 v34, s[6:7], s64, v146
	v_mul_f32_e32 v37, 0x45800000, v36
	v_cndmask_b32_e32 v36, v36, v37, vcc
	v_mul_f32_e32 v28, v28, v36
	v_mul_f32_e32 v24, v24, v36
	v_mul_f32_e32 v29, v29, v36
	v_mul_f32_e32 v25, v25, v36
	v_mul_f32_e32 v30, v30, v36
	v_mul_f32_e32 v26, v26, v36
	v_mul_f32_e32 v31, v31, v36
	v_mul_f32_e32 v27, v27, v36
	v_mul_f32_e32 v37, v20, v36
	v_mul_f32_e32 v38, v16, v36
	v_mul_f32_e32 v39, v21, v36
	v_mul_f32_e32 v40, v17, v36
	v_mul_f32_e32 v41, v22, v36
	v_mul_f32_e32 v42, v18, v36
	v_mul_f32_e32 v43, v23, v36
	v_mul_f32_e32 v36, v19, v36
	v_max_f32_e32 v16, 0, v28
	v_max_f32_e32 v18, 0, v24
	v_max_f32_e32 v17, 0, v29
	v_max_f32_e32 v19, 0, v25
	v_max_f32_e32 v20, 0, v30
	v_max_f32_e32 v22, 0, v26
	v_max_f32_e32 v21, 0, v31
	v_max_f32_e32 v23, 0, v27
	v_max_f32_e32 v24, 0, v37
	v_max_f32_e32 v26, 0, v38
	v_max_f32_e32 v25, 0, v39
	v_max_f32_e32 v27, 0, v40
	v_max_f32_e32 v28, 0, v41
	v_max_f32_e32 v30, 0, v42
	v_max_f32_e32 v29, 0, v43
	v_max_f32_e32 v31, 0, v36
	v_pk_mul_f32 v[16:17], v[16:17], v[16:17]
	v_pk_mul_f32 v[18:19], v[18:19], v[18:19]
	v_pk_mul_f32 v[20:21], v[20:21], v[20:21]
	v_pk_mul_f32 v[22:23], v[22:23], v[22:23]
	v_addc_co_u32_e64 v35, s[6:7], 0, v147, s[6:7]
	v_pk_mul_f32 v[24:25], v[24:25], v[24:25]
	v_pk_mul_f32 v[26:27], v[26:27], v[26:27]
	v_pk_mul_f32 v[28:29], v[28:29], v[28:29]
	v_pk_mul_f32 v[30:31], v[30:31], v[30:31]
	v_cvt_pk_bf16_f32 v16, v16, v17
	v_cvt_pk_bf16_f32 v17, v20, v21
	v_cvt_pk_bf16_f32 v18, v18, v19
	v_cvt_pk_bf16_f32 v19, v22, v23
	v_cvt_pk_bf16_f32 v20, v24, v25
	v_cvt_pk_bf16_f32 v21, v28, v29
	v_cvt_pk_bf16_f32 v22, v26, v27
	v_cvt_pk_bf16_f32 v23, v30, v31
	global_store_dwordx4 v[34:35], v[16:19], off
	global_store_dwordx4 v[32:33], v[20:23], off offset:256
	global_load_dword v18, v[144:145], off offset:704
	s_and_b64 vcc, exec, s[4:5]
	v_lshl_add_u64 v[16:17], v[146:147], 0, s[24:25]
	s_waitcnt vmcnt(0)
	v_fmamk_f32 v18, v18, 0x3a800000, v160
	v_mul_f32_e32 v19, 0x4b800000, v18
	v_cmp_gt_f32_e64 s[4:5], s61, v18
	s_nop 1
	v_cndmask_b32_e64 v18, v18, v19, s[4:5]
	v_rsq_f32_e32 v20, v18
	v_add_co_u32_e64 v18, s[6:7], s65, v146
	v_mul_f32_e32 v21, 0x45800000, v20
	v_cndmask_b32_e64 v20, v20, v21, s[4:5]
	v_mul_f32_e32 v12, v12, v20
	v_mul_f32_e32 v8, v8, v20
	v_mul_f32_e32 v13, v13, v20
	v_mul_f32_e32 v9, v9, v20
	v_mul_f32_e32 v14, v14, v20
	v_mul_f32_e32 v10, v10, v20
	v_mul_f32_e32 v15, v15, v20
	v_mul_f32_e32 v11, v11, v20
	v_mul_f32_e32 v21, v4, v20
	v_mul_f32_e32 v22, v0, v20
	v_mul_f32_e32 v23, v5, v20
	v_mul_f32_e32 v24, v1, v20
	v_mul_f32_e32 v25, v6, v20
	v_mul_f32_e32 v26, v2, v20
	v_mul_f32_e32 v27, v7, v20
	v_mul_f32_e32 v20, v3, v20
	v_max_f32_e32 v0, 0, v12
	v_max_f32_e32 v2, 0, v8
	v_max_f32_e32 v1, 0, v13
	v_max_f32_e32 v3, 0, v9
	v_max_f32_e32 v4, 0, v14
	v_max_f32_e32 v6, 0, v10
	v_max_f32_e32 v5, 0, v15
	v_max_f32_e32 v7, 0, v11
	v_max_f32_e32 v8, 0, v21
	v_max_f32_e32 v10, 0, v22
	v_max_f32_e32 v9, 0, v23
	v_max_f32_e32 v11, 0, v24
	v_max_f32_e32 v12, 0, v25
	v_max_f32_e32 v14, 0, v26
	v_max_f32_e32 v13, 0, v27
	v_max_f32_e32 v15, 0, v20
	v_pk_mul_f32 v[0:1], v[0:1], v[0:1]
	v_pk_mul_f32 v[2:3], v[2:3], v[2:3]
	v_pk_mul_f32 v[4:5], v[4:5], v[4:5]
	v_pk_mul_f32 v[6:7], v[6:7], v[6:7]
	v_addc_co_u32_e64 v19, s[6:7], 0, v147, s[6:7]
	v_pk_mul_f32 v[8:9], v[8:9], v[8:9]
	v_pk_mul_f32 v[10:11], v[10:11], v[10:11]
	v_pk_mul_f32 v[12:13], v[12:13], v[12:13]
	v_pk_mul_f32 v[14:15], v[14:15], v[14:15]
	v_cvt_pk_bf16_f32 v0, v0, v1
	v_cvt_pk_bf16_f32 v1, v4, v5
	v_cvt_pk_bf16_f32 v2, v2, v3
	v_cvt_pk_bf16_f32 v3, v6, v7
	v_cvt_pk_bf16_f32 v4, v8, v9
	v_cvt_pk_bf16_f32 v5, v12, v13
	v_cvt_pk_bf16_f32 v6, v10, v11
	v_cvt_pk_bf16_f32 v7, v14, v15
	global_store_dwordx4 v[18:19], v[0:3], off
	global_store_dwordx4 v[16:17], v[4:7], off offset:256
	s_cbranch_vccz .LBB0_694
	s_waitcnt vmcnt(0)
	s_cmpk_gt_u32 s33, 0xff
	s_cbranch_scc1 .LBB0_701
	s_barrier

.LBB0_722:
	s_or_b32 s52, s37, 1
	s_sub_i32 s53, s52, s57
	s_min_u32 s53, s52, s53
	s_cmp_lt_u32 s52, s57
	s_cselect_b32 s52, s45, s58
	s_cselect_b32 s67, s44, s59
	s_lshl_b32 s53, s53, 7
	v_add_u32_e32 v149, s65, v145
	s_add_u32 s53, s67, s53
	ds_read_b128 v[140:143], v149
	ds_read_b128 v[150:153], v149 offset:1024
	ds_read_b128 v[156:159], v149 offset:2048
	ds_read_b128 v[160:163], v149 offset:3072
	s_addc_u32 s67, s52, 0
	s_lshl_b32 s52, s37, 7
	s_add_u32 s52, s40, s52
	s_addc_u32 s68, s41, 0
	s_add_u32 s52, s52, 0x100
	s_addc_u32 s68, s68, 0
	s_and_b64 s[50:51], exec, s[50:51]
	s_cselect_b32 s51, s19, s68
	s_cselect_b32 s50, s21, s52
	s_add_u32 s52, s53, 0x80000
	s_addc_u32 s53, s67, 0
	v_lshl_add_u64 v[196:197], s[52:53], 0, v[128:129]
	s_add_i32 m0, s35, 0xc000
	ds_read_b128 v[164:167], v147
	ds_read_b128 v[168:171], v147 offset:1024
	ds_read_b128 v[172:175], v147 offset:2048
	ds_read_b128 v[176:179], v147 offset:3072
	ds_read_b128 v[180:183], v147 offset:4096
	ds_read_b128 v[184:187], v147 offset:5120
	ds_read_b128 v[188:191], v147 offset:6144
	ds_read_b128 v[192:195], v147 offset:7168
	global_load_lds_dwordx4 v[196:197], off
	s_add_i32 m0, s35, 0xe000
	v_lshl_add_u64 v[196:197], s[52:53], 0, v[132:133]
	global_load_lds_dwordx4 v[196:197], off
	s_waitcnt lgkmcnt(8)
	s_barrier
	s_waitcnt lgkmcnt(0)
	s_waitcnt lgkmcnt(0)
	v_mfma_f32_16x16x32_bf16 v[124:127], v[140:143], v[164:167], v[124:127]
	v_mfma_f32_16x16x32_bf16 v[120:123], v[156:159], v[164:167], v[120:123]
	v_mfma_f32_16x16x32_bf16 v[108:111], v[140:143], v[172:175], v[108:111]
	v_mfma_f32_16x16x32_bf16 v[104:107], v[156:159], v[172:175], v[104:107]
	v_mfma_f32_16x16x32_bf16 v[92:95], v[140:143], v[180:183], v[92:95]
	v_mfma_f32_16x16x32_bf16 v[88:91], v[156:159], v[180:183], v[88:91]
	v_mfma_f32_16x16x32_bf16 v[76:79], v[140:143], v[188:191], v[76:79]
	v_mfma_f32_16x16x32_bf16 v[72:75], v[156:159], v[188:191], v[72:75]
	v_mfma_f32_16x16x32_bf16 v[124:127], v[150:153], v[168:171], v[124:127]
	v_mfma_f32_16x16x32_bf16 v[120:123], v[160:163], v[168:171], v[120:123]
	v_mfma_f32_16x16x32_bf16 v[108:111], v[150:153], v[176:179], v[108:111]
	v_mfma_f32_16x16x32_bf16 v[104:107], v[160:163], v[176:179], v[104:107]
	v_mfma_f32_16x16x32_bf16 v[92:95], v[150:153], v[184:187], v[92:95]
	v_mfma_f32_16x16x32_bf16 v[88:91], v[160:163], v[184:187], v[88:91]
	v_mfma_f32_16x16x32_bf16 v[76:79], v[150:153], v[192:195], v[76:79]
	v_mfma_f32_16x16x32_bf16 v[72:75], v[160:163], v[192:195], v[72:75]
	s_barrier
	s_add_i32 s52, s65, s34
	v_add_u32_e32 v149, s72, v145
	v_lshl_add_u64 v[212:213], s[50:51], 0, v[130:131]
	s_mov_b32 m0, s52
	ds_read_b128 v[196:199], v149
	ds_read_b128 v[200:203], v149 offset:1024
	ds_read_b128 v[204:207], v149 offset:2048
	ds_read_b128 v[208:211], v149 offset:3072
	global_load_lds_dwordx4 v[212:213], off
	s_add_i32 m0, s52, 0x2000
	v_lshl_add_u64 v[214:215], s[50:51], 0, v[134:135]
	global_load_lds_dwordx4 v[214:215], off
	s_barrier
	s_waitcnt lgkmcnt(0)
	s_waitcnt lgkmcnt(0)
	v_mfma_f32_16x16x32_bf16 v[116:119], v[196:199], v[164:167], v[116:119]
	v_mfma_f32_16x16x32_bf16 v[112:115], v[204:207], v[164:167], v[112:115]
	v_mfma_f32_16x16x32_bf16 v[100:103], v[196:199], v[172:175], v[100:103]
	v_mfma_f32_16x16x32_bf16 v[96:99], v[204:207], v[172:175], v[96:99]
	v_mfma_f32_16x16x32_bf16 v[84:87], v[196:199], v[180:183], v[84:87]
	v_mfma_f32_16x16x32_bf16 v[80:83], v[204:207], v[180:183], v[80:83]
	v_mfma_f32_16x16x32_bf16 v[68:71], v[196:199], v[188:191], v[68:71]
	v_mfma_f32_16x16x32_bf16 v[64:67], v[204:207], v[188:191], v[64:67]
	v_mfma_f32_16x16x32_bf16 v[116:119], v[200:203], v[168:171], v[116:119]
	v_mfma_f32_16x16x32_bf16 v[112:115], v[208:211], v[168:171], v[112:115]
	v_mfma_f32_16x16x32_bf16 v[100:103], v[200:203], v[176:179], v[100:103]
	v_mfma_f32_16x16x32_bf16 v[96:99], v[208:211], v[176:179], v[96:99]
	v_mfma_f32_16x16x32_bf16 v[84:87], v[200:203], v[184:187], v[84:87]
	v_mfma_f32_16x16x32_bf16 v[80:83], v[208:211], v[184:187], v[80:83]
	v_mfma_f32_16x16x32_bf16 v[68:71], v[200:203], v[192:195], v[68:71]
	v_mfma_f32_16x16x32_bf16 v[64:67], v[208:211], v[192:195], v[64:67]
	s_mov_b32 m0, s35
	v_lshl_add_u64 v[216:217], s[48:49], 0, v[128:129]
	s_barrier
	ds_read_b128 v[164:167], v147 offset:16384
	ds_read_b128 v[168:171], v147 offset:17408
	ds_read_b128 v[172:175], v147 offset:18432
	ds_read_b128 v[176:179], v147 offset:19456
	ds_read_b128 v[180:183], v147 offset:20480
	ds_read_b128 v[184:187], v147 offset:21504
	ds_read_b128 v[188:191], v147 offset:22528
	ds_read_b128 v[192:195], v147 offset:23552
	global_load_lds_dwordx4 v[216:217], off
	s_mov_b32 m0, s39
	v_lshl_add_u64 v[218:219], s[48:49], 0, v[132:133]
	global_load_lds_dwordx4 v[218:219], off
	s_barrier
	s_waitcnt lgkmcnt(0)
	s_waitcnt lgkmcnt(0)
	v_mfma_f32_16x16x32_bf16 v[60:63], v[140:143], v[164:167], v[60:63]
	v_mfma_f32_16x16x32_bf16 v[56:59], v[156:159], v[164:167], v[56:59]
	v_mfma_f32_16x16x32_bf16 v[44:47], v[140:143], v[172:175], v[44:47]
	v_mfma_f32_16x16x32_bf16 v[40:43], v[156:159], v[172:175], v[40:43]
	v_mfma_f32_16x16x32_bf16 v[28:31], v[140:143], v[180:183], v[28:31]
	v_mfma_f32_16x16x32_bf16 v[24:27], v[156:159], v[180:183], v[24:27]
	v_mfma_f32_16x16x32_bf16 v[12:15], v[140:143], v[188:191], v[12:15]
	v_mfma_f32_16x16x32_bf16 v[8:11], v[156:159], v[188:191], v[8:11]
	v_mfma_f32_16x16x32_bf16 v[60:63], v[150:153], v[168:171], v[60:63]
	v_mfma_f32_16x16x32_bf16 v[56:59], v[160:163], v[168:171], v[56:59]
	v_mfma_f32_16x16x32_bf16 v[44:47], v[150:153], v[176:179], v[44:47]
	v_mfma_f32_16x16x32_bf16 v[40:43], v[160:163], v[176:179], v[40:43]
	v_mfma_f32_16x16x32_bf16 v[28:31], v[150:153], v[184:187], v[28:31]
	v_mfma_f32_16x16x32_bf16 v[24:27], v[160:163], v[184:187], v[24:27]
	v_mfma_f32_16x16x32_bf16 v[12:15], v[150:153], v[192:195], v[12:15]
	v_mfma_f32_16x16x32_bf16 v[8:11], v[160:163], v[192:195], v[8:11]
	s_barrier
	s_add_u32 s52, s50, 0x100000
	s_addc_u32 s53, s51, 0
	s_add_i32 s67, s72, s34
	s_mov_b32 m0, s67
	v_lshl_add_u64 v[140:141], s[52:53], 0, v[130:131]
	global_load_lds_dwordx4 v[140:141], off
	s_add_i32 m0, s67, 0x2000
	v_lshl_add_u64 v[140:141], s[52:53], 0, v[134:135]
	global_load_lds_dwordx4 v[140:141], off
	s_waitcnt vmcnt(6)
	s_barrier
	v_mfma_f32_16x16x32_bf16 v[52:55], v[196:199], v[164:167], v[52:55]
	v_mfma_f32_16x16x32_bf16 v[48:51], v[204:207], v[164:167], v[48:51]
	v_mfma_f32_16x16x32_bf16 v[36:39], v[196:199], v[172:175], v[36:39]
	v_mfma_f32_16x16x32_bf16 v[32:35], v[204:207], v[172:175], v[32:35]
	v_mfma_f32_16x16x32_bf16 v[20:23], v[196:199], v[180:183], v[20:23]
	v_mfma_f32_16x16x32_bf16 v[16:19], v[204:207], v[180:183], v[16:19]
	v_mfma_f32_16x16x32_bf16 v[4:7], v[196:199], v[188:191], v[4:7]
	v_mfma_f32_16x16x32_bf16 v[0:3], v[204:207], v[188:191], v[0:3]
	v_mfma_f32_16x16x32_bf16 v[52:55], v[200:203], v[168:171], v[52:55]
	v_mfma_f32_16x16x32_bf16 v[48:51], v[208:211], v[168:171], v[48:51]
	v_mfma_f32_16x16x32_bf16 v[36:39], v[200:203], v[176:179], v[36:39]
	v_mfma_f32_16x16x32_bf16 v[32:35], v[208:211], v[176:179], v[32:35]
	v_mfma_f32_16x16x32_bf16 v[20:23], v[200:203], v[184:187], v[20:23]
	v_mfma_f32_16x16x32_bf16 v[16:19], v[208:211], v[184:187], v[16:19]
	v_mfma_f32_16x16x32_bf16 v[4:7], v[200:203], v[192:195], v[4:7]
	v_mfma_f32_16x16x32_bf16 v[0:3], v[208:211], v[192:195], v[0:3]
	s_add_i32 s52, 0, 0x18000
	v_add_u32_e32 v149, s52, v145
	s_barrier
	ds_read_b128 v[140:143], v149
	ds_read_b128 v[150:153], v149 offset:1024
	ds_read_b128 v[156:159], v149 offset:2048
	ds_read_b128 v[160:163], v149 offset:3072
	s_add_u32 s48, s48, 0x80000
	s_addc_u32 s49, s49, 0
	s_mov_b32 m0, s54
	v_lshl_add_u64 v[196:197], s[48:49], 0, v[128:129]
	ds_read_b128 v[164:167], v147 offset:32768
	ds_read_b128 v[168:171], v147 offset:33792
	ds_read_b128 v[172:175], v147 offset:34816
	ds_read_b128 v[176:179], v147 offset:35840
	ds_read_b128 v[180:183], v147 offset:36864
	ds_read_b128 v[184:187], v147 offset:37888
	ds_read_b128 v[188:191], v147 offset:38912
	ds_read_b128 v[192:195], v147 offset:39936
	global_load_lds_dwordx4 v[196:197], off
	s_mov_b32 m0, s55
	v_lshl_add_u64 v[196:197], s[48:49], 0, v[132:133]
	global_load_lds_dwordx4 v[196:197], off
	s_waitcnt lgkmcnt(8)
	s_barrier
	s_waitcnt lgkmcnt(0)
	s_waitcnt lgkmcnt(0)
	v_mfma_f32_16x16x32_bf16 v[124:127], v[140:143], v[164:167], v[124:127]
	v_mfma_f32_16x16x32_bf16 v[120:123], v[156:159], v[164:167], v[120:123]
	v_mfma_f32_16x16x32_bf16 v[108:111], v[140:143], v[172:175], v[108:111]
	v_mfma_f32_16x16x32_bf16 v[104:107], v[156:159], v[172:175], v[104:107]
	v_mfma_f32_16x16x32_bf16 v[92:95], v[140:143], v[180:183], v[92:95]
	v_mfma_f32_16x16x32_bf16 v[88:91], v[156:159], v[180:183], v[88:91]
	v_mfma_f32_16x16x32_bf16 v[76:79], v[140:143], v[188:191], v[76:79]
	v_mfma_f32_16x16x32_bf16 v[72:75], v[156:159], v[188:191], v[72:75]
	v_mfma_f32_16x16x32_bf16 v[124:127], v[150:153], v[168:171], v[124:127]
	v_mfma_f32_16x16x32_bf16 v[120:123], v[160:163], v[168:171], v[120:123]
	v_mfma_f32_16x16x32_bf16 v[108:111], v[150:153], v[176:179], v[108:111]
	v_mfma_f32_16x16x32_bf16 v[104:107], v[160:163], v[176:179], v[104:107]
	v_mfma_f32_16x16x32_bf16 v[92:95], v[150:153], v[184:187], v[92:95]
	v_mfma_f32_16x16x32_bf16 v[88:91], v[160:163], v[184:187], v[88:91]
	v_mfma_f32_16x16x32_bf16 v[76:79], v[150:153], v[192:195], v[76:79]
	v_mfma_f32_16x16x32_bf16 v[72:75], v[160:163], v[192:195], v[72:75]
	s_barrier
	s_add_i32 s48, s52, s34
	v_add_u32_e32 v149, s97, v145
	v_lshl_add_u64 v[212:213], v[212:213], 0, s[16:17]
	s_mov_b32 m0, s48
	ds_read_b128 v[196:199], v149
	ds_read_b128 v[200:203], v149 offset:1024
	ds_read_b128 v[204:207], v149 offset:2048
	ds_read_b128 v[208:211], v149 offset:3072
	global_load_lds_dwordx4 v[212:213], off
	s_add_i32 m0, s48, 0x2000
	v_lshl_add_u64 v[212:213], v[214:215], 0, s[16:17]
	global_load_lds_dwordx4 v[212:213], off
	s_barrier
	s_waitcnt lgkmcnt(0)
	s_waitcnt lgkmcnt(0)
	v_mfma_f32_16x16x32_bf16 v[116:119], v[196:199], v[164:167], v[116:119]
	v_mfma_f32_16x16x32_bf16 v[112:115], v[204:207], v[164:167], v[112:115]
	v_mfma_f32_16x16x32_bf16 v[100:103], v[196:199], v[172:175], v[100:103]
	v_mfma_f32_16x16x32_bf16 v[96:99], v[204:207], v[172:175], v[96:99]
	v_mfma_f32_16x16x32_bf16 v[84:87], v[196:199], v[180:183], v[84:87]
	v_mfma_f32_16x16x32_bf16 v[80:83], v[204:207], v[180:183], v[80:83]
	v_mfma_f32_16x16x32_bf16 v[68:71], v[196:199], v[188:191], v[68:71]
	v_mfma_f32_16x16x32_bf16 v[64:67], v[204:207], v[188:191], v[64:67]
	v_mfma_f32_16x16x32_bf16 v[116:119], v[200:203], v[168:171], v[116:119]
	v_mfma_f32_16x16x32_bf16 v[112:115], v[208:211], v[168:171], v[112:115]
	v_mfma_f32_16x16x32_bf16 v[100:103], v[200:203], v[176:179], v[100:103]
	v_mfma_f32_16x16x32_bf16 v[96:99], v[208:211], v[176:179], v[96:99]
	v_mfma_f32_16x16x32_bf16 v[84:87], v[200:203], v[184:187], v[84:87]
	v_mfma_f32_16x16x32_bf16 v[80:83], v[208:211], v[184:187], v[80:83]
	v_mfma_f32_16x16x32_bf16 v[68:71], v[200:203], v[192:195], v[68:71]
	v_mfma_f32_16x16x32_bf16 v[64:67], v[208:211], v[192:195], v[64:67]
	s_mov_b32 m0, s60
	v_lshl_add_u64 v[212:213], v[216:217], 0, s[16:17]
	s_barrier
	ds_read_b128 v[164:167], v147 offset:49152
	ds_read_b128 v[168:171], v147 offset:50176
	ds_read_b128 v[172:175], v147 offset:51200
	ds_read_b128 v[176:179], v147 offset:52224
	ds_read_b128 v[180:183], v147 offset:53248
	ds_read_b128 v[184:187], v147 offset:54272
	ds_read_b128 v[188:191], v147 offset:55296
	ds_read_b128 v[192:195], v147 offset:56320
	global_load_lds_dwordx4 v[212:213], off
	s_mov_b32 m0, s61
	v_lshl_add_u64 v[212:213], v[218:219], 0, s[16:17]
	global_load_lds_dwordx4 v[212:213], off
	s_barrier
	s_waitcnt lgkmcnt(0)
	s_waitcnt lgkmcnt(0)
	v_mfma_f32_16x16x32_bf16 v[60:63], v[140:143], v[164:167], v[60:63]
	v_mfma_f32_16x16x32_bf16 v[56:59], v[156:159], v[164:167], v[56:59]
	v_mfma_f32_16x16x32_bf16 v[44:47], v[140:143], v[172:175], v[44:47]
	v_mfma_f32_16x16x32_bf16 v[40:43], v[156:159], v[172:175], v[40:43]
	v_mfma_f32_16x16x32_bf16 v[28:31], v[140:143], v[180:183], v[28:31]
	v_mfma_f32_16x16x32_bf16 v[24:27], v[156:159], v[180:183], v[24:27]
	v_mfma_f32_16x16x32_bf16 v[12:15], v[140:143], v[188:191], v[12:15]
	v_mfma_f32_16x16x32_bf16 v[8:11], v[156:159], v[188:191], v[8:11]
	v_mfma_f32_16x16x32_bf16 v[60:63], v[150:153], v[168:171], v[60:63]
	v_mfma_f32_16x16x32_bf16 v[56:59], v[160:163], v[168:171], v[56:59]
	v_mfma_f32_16x16x32_bf16 v[44:47], v[150:153], v[176:179], v[44:47]
	v_mfma_f32_16x16x32_bf16 v[40:43], v[160:163], v[176:179], v[40:43]
	v_mfma_f32_16x16x32_bf16 v[28:31], v[150:153], v[184:187], v[28:31]
	v_mfma_f32_16x16x32_bf16 v[24:27], v[160:163], v[184:187], v[24:27]
	v_mfma_f32_16x16x32_bf16 v[12:15], v[150:153], v[192:195], v[12:15]
	v_mfma_f32_16x16x32_bf16 v[8:11], v[160:163], v[192:195], v[8:11]
	s_barrier
	s_add_u32 s48, s50, 0x100080
	s_addc_u32 s49, s51, 0
	s_add_i32 s50, s97, s34
	s_mov_b32 m0, s50
	v_lshl_add_u64 v[140:141], s[48:49], 0, v[130:131]
	global_load_lds_dwordx4 v[140:141], off
	s_add_i32 m0, s50, 0x2000
	v_lshl_add_u64 v[140:141], s[48:49], 0, v[134:135]
	global_load_lds_dwordx4 v[140:141], off
	s_waitcnt vmcnt(6)
	s_barrier
	v_mfma_f32_16x16x32_bf16 v[52:55], v[196:199], v[164:167], v[52:55]
	v_mfma_f32_16x16x32_bf16 v[48:51], v[204:207], v[164:167], v[48:51]
	v_mfma_f32_16x16x32_bf16 v[36:39], v[196:199], v[172:175], v[36:39]
	v_mfma_f32_16x16x32_bf16 v[32:35], v[204:207], v[172:175], v[32:35]
	v_mfma_f32_16x16x32_bf16 v[20:23], v[196:199], v[180:183], v[20:23]
	v_mfma_f32_16x16x32_bf16 v[16:19], v[204:207], v[180:183], v[16:19]
	v_mfma_f32_16x16x32_bf16 v[4:7], v[196:199], v[188:191], v[4:7]
	v_mfma_f32_16x16x32_bf16 v[0:3], v[204:207], v[188:191], v[0:3]
	v_mfma_f32_16x16x32_bf16 v[52:55], v[200:203], v[168:171], v[52:55]
	v_mfma_f32_16x16x32_bf16 v[48:51], v[208:211], v[168:171], v[48:51]
	v_mfma_f32_16x16x32_bf16 v[36:39], v[200:203], v[176:179], v[36:39]
	v_mfma_f32_16x16x32_bf16 v[32:35], v[208:211], v[176:179], v[32:35]
	v_mfma_f32_16x16x32_bf16 v[20:23], v[200:203], v[184:187], v[20:23]
	v_mfma_f32_16x16x32_bf16 v[16:19], v[208:211], v[184:187], v[16:19]
	v_mfma_f32_16x16x32_bf16 v[4:7], v[200:203], v[192:195], v[4:7]
	v_mfma_f32_16x16x32_bf16 v[0:3], v[208:211], v[192:195], v[0:3]
	s_cmp_gt_u32 s37, 61
	s_mov_b32 s37, s66
	s_barrier
	s_cbranch_scc1 .LBB0_728
